# removed 964 dead SGPR-reload v_readlane in GEMM-phase unit loops/epilogues (global liveness), s_nop 1 kept per removed run
# speedup vs baseline: 1.0102x; 1.0102x over previous
.LBB0_59:
	s_mov_b32 s100, 0
	s_mov_b32 s101, 0
	s_sub_i32 s20, s84, 32
	s_cmp_lt_u32 s20, 10
	s_cselect_b32 s20, 64, 0x48
	s_waitcnt vmcnt(0)
	v_mov_b32_e32 v5, v193
	s_mul_i32 s47, s20, 22
	s_cmp_ge_i32 s96, s47
	v_readfirstlane_b32 s46, v5
	s_cbranch_scc1 .LBB0_71
	v_lshlrev_b32_e32 v3, 4, v5
	v_add_u32_e32 v1, 0x2000, v3
	v_ashrrev_i32_e32 v0, 31, v1
	v_lshrrev_b32_e32 v0, 22, v0
	v_add_u32_e32 v0, v1, v0
	v_ashrrev_i32_e32 v0, 10, v0
	v_mul_i32_i24_e32 v2, 0x400, v0
	v_sub_u32_e32 v1, v1, v2
	v_lshrrev_b32_e32 v2, 4, v1
	v_bitop3_b32 v2, v2, v1, 32 bitop3:0x6c
	v_ashrrev_i32_e32 v1, 31, v2
	v_lshrrev_b32_e32 v1, 26, v1
	v_add_u32_e32 v4, v2, v1
	v_lshlrev_b32_e32 v6, 3, v0
	v_ashrrev_i32_e32 v1, 6, v4
	v_and_b32_e32 v6, -16, v6
	s_nop 1
	v_add_u32_e32 v6, v1, v6
	v_and_b32_e32 v7, 3, v1
	s_mov_b32 s4, 0x1fffe0
	v_lshrrev_b32_e32 v8, 2, v6
	v_lshlrev_b32_e32 v9, 1, v6
	v_and_b32_e32 v4, 0xc0, v4
	v_and_or_b32 v7, v6, s4, v7
	v_and_b32_e32 v8, 4, v8
	v_and_b32_e32 v9, 24, v9
	v_sub_u32_e32 v2, v2, v4
	v_or3_b32 v7, v7, v8, v9
	v_lshlrev_b32_e32 v8, 5, v0
	v_ashrrev_i16_sdwa v2, v250, sext(v2) dst_sel:DWORD dst_unused:UNUSED_PAD src0_sel:DWORD src1_sel:BYTE_0
	v_and_b32_e32 v8, 32, v8
	v_bfe_i32 v2, v2, 0, 16
	v_add_lshl_u32 v4, v8, v2, 1
	v_lshl_add_u32 v128, v7, 11, v4
	v_lshl_add_u32 v130, v6, 11, v4
	v_bfe_i32 v4, v5, 27, 1
	v_lshrrev_b32_e32 v4, 22, v4
	v_add_u32_e32 v4, v3, v4
	v_and_b32_e32 v4, 0xfffffc00, v4
	v_sub_u32_e32 v3, v3, v4
	v_lshrrev_b32_e32 v4, 4, v3
	v_bitop3_b32 v6, v4, v3, 32 bitop3:0x6c
	v_ashrrev_i32_e32 v4, 31, v5
	v_lshrrev_b32_e32 v4, 26, v4
	v_ashrrev_i32_e32 v3, 31, v3
	v_add_u32_e32 v4, v5, v4
	v_lshrrev_b32_e32 v3, 26, v3
	v_ashrrev_i32_e32 v4, 6, v4
	s_bitcmp1_b32 s92, 0
	v_add_u32_e32 v3, v6, v3
	v_lshlrev_b32_e32 v7, 3, v4
	s_cselect_b32 s22, 0x2180000, 0
	v_readlane_b32 s12, v253, 8
	s_mov_b64 s[66:67], s[62:63]
	v_ashrrev_i32_e32 v3, 6, v3
	v_and_b32_e32 v7, -16, v7
	s_nop 1
	v_readlane_b32 s13, v253, 9
	s_mov_b64 s[64:65], s[60:61]
	s_mov_b64 s[62:63], s[58:59]
	s_mov_b64 s[60:61], s[56:57]
	s_mov_b64 s[58:59], s[54:55]
	s_mov_b64 s[56:57], s[52:53]
	s_mov_b64 s[54:55], s[50:51]
	s_mov_b64 s[52:53], s[48:49]
	s_add_u32 s48, s12, s22
	v_add_u32_e32 v7, v3, v7
	v_and_b32_e32 v8, 3, v3
	s_addc_u32 s49, s13, 0
	s_ashr_i32 s23, s46, 6
	v_and_or_b32 v8, v7, s4, v8
	s_lshr_b32 s51, s47, 3
	v_readlane_b32 s4, v254, 5
	s_ashr_i32 s26, s46, 8
	s_lshl_b32 s50, s23, 10
	s_or_b32 s52, s51, 1
	v_readlane_b32 s5, v254, 6
	s_and_b64 s[28:29], s[4:5], exec
	s_cselect_b32 s22, s52, s51
	v_readlane_b32 s4, v254, 7
	s_mul_i32 s22, s22, s4
	v_readlane_b32 s4, v254, 4
	s_add_i32 s22, s22, s4
	v_lshrrev_b32_e32 v9, 2, v7
	v_lshlrev_b32_e32 v10, 1, v7
	s_mul_hi_i32 s27, s22, 0x2e8ba2e9
	v_and_b32_e32 v9, 4, v9
	v_and_b32_e32 v10, 24, v10
	s_lshr_b32 s28, s27, 31
	s_ashr_i32 s27, s27, 5
	v_or3_b32 v8, v8, v9, v10
	v_mul_i32_i24_e32 v10, 64, v3
	s_add_i32 s27, s27, s28
	v_sub_u32_e32 v6, v6, v10
	s_lshl_b32 s30, s27, 3
	v_lshlrev_b32_e32 v9, 5, v4
	v_ashrrev_i16_sdwa v6, v250, sext(v6) dst_sel:DWORD dst_unused:UNUSED_PAD src0_sel:DWORD src1_sel:BYTE_0
	s_sub_i32 s28, s20, s30
	v_and_b32_e32 v9, 32, v9
	v_bfe_i32 v6, v6, 0, 16
	s_min_i32 s31, s28, 8
	v_add_lshl_u32 v9, v9, v6, 1
	s_sext_i32_i16 s28, s31
	v_lshl_add_u32 v132, v7, 11, v9
	v_cvt_f32_i32_e32 v7, s28
	s_mulk_i32 s27, 0xb0
	s_sub_i32 s27, s22, s27
	v_lshl_add_u32 v184, v8, 11, v9
	v_cvt_f32_i32_e32 v8, s27
	v_rcp_iflag_f32_e32 v9, v7
	s_xor_b32 s22, s27, s28
	s_ashr_i32 s22, s22, 30
	s_or_b32 s22, s22, 1
	v_mul_f32_e32 v9, v8, v9
	v_trunc_f32_e32 v9, v9
	v_fma_f32 v8, -v9, v7, v8
	v_cvt_i32_f32_e32 v9, v9
	v_cmp_ge_f32_e64 s[28:29], |v8|, |v7|
	s_and_b64 s[28:29], s[28:29], exec
	s_cselect_b32 s22, s22, 0
	v_readfirstlane_b32 s28, v9
	s_add_i32 s22, s28, s22
	s_mul_i32 s28, s22, s31
	s_sub_i32 s27, s27, s28
	s_sext_i32_i16 s27, s27
	s_add_i32 s38, s30, s27
	s_ashr_i32 s39, s38, 31
	s_bfe_i64 s[30:31], s[22:23], 0x100000
	s_lshl_b64 s[28:29], s[38:39], 19
	s_lshl_b64 s[30:31], s[30:31], 19
	s_add_u32 s42, s48, s30
	s_addc_u32 s43, s49, s31
	s_add_i32 s39, s50, 0x10000
	s_add_i32 s53, s50, 0x12000
	s_waitcnt vmcnt(0)
	s_mov_b32 m0, s39
	s_add_u32 s40, s54, s28
	global_load_lds_dwordx4 v184, s[42:43]
	s_mov_b32 m0, s53
	s_addc_u32 s41, s55, s29
	s_add_i32 s54, s50, 0x2000
	global_load_lds_dwordx4 v128, s[42:43]
	s_mov_b32 m0, s50
	s_add_u32 s28, s42, 0x40000
	global_load_lds_dwordx4 v132, s[40:41]
	s_mov_b32 m0, s54
	s_addc_u32 s29, s43, 0
	s_add_i32 s55, s50, 0x14000
	global_load_lds_dwordx4 v130, s[40:41]
	s_mov_b32 m0, s55
	s_add_i32 s58, s50, 0x16000
	global_load_lds_dwordx4 v184, s[28:29]
	s_mov_b32 m0, s58
	v_writelane_b32 v255, s84, 43
	global_load_lds_dwordx4 v128, s[28:29]
	s_add_u32 s28, s40, 0x40000
	s_addc_u32 s29, s41, 0
	s_add_i32 s59, s50, 0x4000
	s_mov_b32 m0, s59
	s_add_i32 s60, s50, 0x6000
	global_load_lds_dwordx4 v132, s[28:29]
	s_mov_b32 m0, s60
	v_writelane_b32 v255, s85, 44
	global_load_lds_dwordx4 v130, s[28:29]
	v_writelane_b32 v255, s86, 45
	s_mov_b32 s88, s80
	v_writelane_b32 v255, s87, 46
	s_cmp_lg_u32 s26, 1
	s_nop 1
	s_cbranch_scc1 .LBB0_62
	s_barrier

.LBB0_65:
	s_ashr_i32 s31, s30, 31
	s_nop 1
	s_lshl_b64 s[26:27], s[30:31], 19
	v_readlane_b32 s6, v253, 18
	v_readlane_b32 s7, v253, 19
	s_add_u32 s34, s6, s26
	s_addc_u32 s35, s7, s27
	s_cmp_eq_u32 s101, 2
	s_cselect_b32 s26, 0x40000, 0
	s_add_u32 s34, s34, s26
	s_addc_u32 s35, s35, 0
	s_and_b64 s[26:27], s[44:45], exec
	s_cselect_b32 s31, s35, s41
	s_cselect_b32 s80, s34, s40
	s_ashr_i32 s29, s28, 31
	s_lshl_b64 s[26:27], s[28:29], 19
	s_add_u32 s36, s48, s26
	s_addc_u32 s37, s49, s27
	s_and_b64 s[26:27], s[44:45], exec
	s_cselect_b32 s29, s37, s43
	s_cselect_b32 vcc_lo, s36, s42
	s_add_u32 s40, s40, 0x40080
	s_addc_u32 s41, s41, 0
	s_add_u32 s26, s42, 0x100
	v_mov_b32_e32 v0, 0
	s_addc_u32 s27, s43, 0
	s_mov_b32 s96, -2
	v_mov_b32_e32 v1, v0
	v_mov_b32_e32 v2, v0
	v_mov_b32_e32 v3, v0
	v_mov_b32_e32 v8, v0
	v_mov_b32_e32 v9, v0
	v_mov_b32_e32 v10, v0
	v_mov_b32_e32 v11, v0
	v_mov_b32_e32 v16, v0
	v_mov_b32_e32 v17, v0
	v_mov_b32_e32 v18, v0
	v_mov_b32_e32 v19, v0
	v_mov_b32_e32 v24, v0
	v_mov_b32_e32 v25, v0
	v_mov_b32_e32 v26, v0
	v_mov_b32_e32 v27, v0
	v_mov_b32_e32 v32, v0
	v_mov_b32_e32 v33, v0
	v_mov_b32_e32 v34, v0
	v_mov_b32_e32 v35, v0
	v_mov_b32_e32 v40, v0
	v_mov_b32_e32 v41, v0
	v_mov_b32_e32 v42, v0
	v_mov_b32_e32 v43, v0
	v_mov_b32_e32 v48, v0
	v_mov_b32_e32 v49, v0
	v_mov_b32_e32 v50, v0
	v_mov_b32_e32 v51, v0
	v_mov_b32_e32 v56, v0
	v_mov_b32_e32 v57, v0
	v_mov_b32_e32 v58, v0
	v_mov_b32_e32 v59, v0
	v_mov_b32_e32 v4, v0
	v_mov_b32_e32 v5, v0
	v_mov_b32_e32 v6, v0
	v_mov_b32_e32 v7, v0
	v_mov_b32_e32 v12, v0
	v_mov_b32_e32 v13, v0
	v_mov_b32_e32 v14, v0
	v_mov_b32_e32 v15, v0
	v_mov_b32_e32 v20, v0
	v_mov_b32_e32 v21, v0
	v_mov_b32_e32 v22, v0
	v_mov_b32_e32 v23, v0
	v_mov_b32_e32 v28, v0
	v_mov_b32_e32 v29, v0
	v_mov_b32_e32 v30, v0
	v_mov_b32_e32 v31, v0
	v_mov_b32_e32 v36, v0
	v_mov_b32_e32 v37, v0
	v_mov_b32_e32 v38, v0
	v_mov_b32_e32 v39, v0
	v_mov_b32_e32 v44, v0
	v_mov_b32_e32 v45, v0
	v_mov_b32_e32 v46, v0
	v_mov_b32_e32 v47, v0
	v_mov_b32_e32 v52, v0
	v_mov_b32_e32 v53, v0
	v_mov_b32_e32 v54, v0
	v_mov_b32_e32 v55, v0
	v_mov_b32_e32 v60, v0
	v_mov_b32_e32 v61, v0
	v_mov_b32_e32 v62, v0
	v_mov_b32_e32 v63, v0
	v_mov_b32_e32 v64, v0
	v_mov_b32_e32 v65, v0
	v_mov_b32_e32 v66, v0
	v_mov_b32_e32 v67, v0
	v_mov_b32_e32 v72, v0
	v_mov_b32_e32 v73, v0
	v_mov_b32_e32 v74, v0
	v_mov_b32_e32 v75, v0
	v_mov_b32_e32 v80, v0
	v_mov_b32_e32 v81, v0
	v_mov_b32_e32 v82, v0
	v_mov_b32_e32 v83, v0
	v_mov_b32_e32 v88, v0
	v_mov_b32_e32 v89, v0
	v_mov_b32_e32 v90, v0
	v_mov_b32_e32 v91, v0
	v_mov_b32_e32 v96, v0
	v_mov_b32_e32 v97, v0
	v_mov_b32_e32 v98, v0
	v_mov_b32_e32 v99, v0
	v_mov_b32_e32 v104, v0
	v_mov_b32_e32 v105, v0
	v_mov_b32_e32 v106, v0
	v_mov_b32_e32 v107, v0
	v_mov_b32_e32 v112, v0
	v_mov_b32_e32 v113, v0
	v_mov_b32_e32 v114, v0
	v_mov_b32_e32 v115, v0
	v_mov_b32_e32 v120, v0
	v_mov_b32_e32 v121, v0
	v_mov_b32_e32 v122, v0
	v_mov_b32_e32 v123, v0
	v_mov_b32_e32 v68, v0
	v_mov_b32_e32 v69, v0
	v_mov_b32_e32 v70, v0
	v_mov_b32_e32 v71, v0
	v_mov_b32_e32 v76, v0
	v_mov_b32_e32 v77, v0
	v_mov_b32_e32 v78, v0
	v_mov_b32_e32 v79, v0
	v_mov_b32_e32 v84, v0
	v_mov_b32_e32 v85, v0
	v_mov_b32_e32 v86, v0
	v_mov_b32_e32 v87, v0
	v_mov_b32_e32 v92, v0
	v_mov_b32_e32 v93, v0
	v_mov_b32_e32 v94, v0
	v_mov_b32_e32 v95, v0
	v_mov_b32_e32 v100, v0
	v_mov_b32_e32 v101, v0
	v_mov_b32_e32 v102, v0
	v_mov_b32_e32 v103, v0
	v_mov_b32_e32 v108, v0
	v_mov_b32_e32 v109, v0
	v_mov_b32_e32 v110, v0
	v_mov_b32_e32 v111, v0
	v_mov_b32_e32 v116, v0
	v_mov_b32_e32 v117, v0
	v_mov_b32_e32 v118, v0
	v_mov_b32_e32 v119, v0
	v_mov_b32_e32 v124, v0
	v_mov_b32_e32 v125, v0
	v_mov_b32_e32 v126, v0
	v_mov_b32_e32 v127, v0
	s_nop 1

.Luph_nost:
	s_mov_b32 s100, s101
	s_cbranch_vccz .LBB0_63
	s_waitcnt vmcnt(0)
	v_readlane_b32 s64, v255, 43
	v_readlane_b32 s65, v255, 44
	s_cmpk_gt_u32 s46, 0xff
	s_mov_b64 s[84:85], s[64:65]
	s_movk_i32 s33, 0x3fff
	s_mov_b32 s70, 0xbfb8aa3b
	s_mov_b32 s71, 0x42ce8ed0
	s_nop 1
	s_cbranch_scc1 .LBB0_70
	s_barrier
.LBB0_70:
	s_nop 1
	s_barrier
	s_nop 1
	v_readlane_b32 s52, v253, 20
	s_nop 1
	v_readlane_b32 s55, v253, 23
	s_nop 1
	s_mov_b32 s80, s88

.LBB0_81:
	s_and_b64 vcc, exec, s[0:1]
	s_cbranch_vccz .LBB0_187
	s_cmp_eq_u32 s91, 4
	s_cselect_b64 s[56:57], -1, 0
	s_cmp_lg_u32 s91, 4
	s_mov_b64 s[0:1], -1
	s_cbranch_scc0 .LBB0_100
	s_mov_b32 s100, 0
	s_mov_b32 s101, 0
	s_sub_i32 s0, s84, 32
	s_cmp_lt_u32 s0, 10
	s_cselect_b32 s20, 64, 0x48
	s_waitcnt vmcnt(0)
	v_mov_b32_e32 v6, v193
	s_lshl_b32 s38, s20, 2
	s_cmp_ge_i32 s96, s38
	v_readfirstlane_b32 s33, v6
	s_cbranch_scc1 .LBB0_99
	v_lshlrev_b32_e32 v3, 4, v6
	v_add_u32_e32 v0, 0x2000, v3
	v_ashrrev_i32_e32 v1, 31, v0
	v_lshrrev_b32_e32 v1, 22, v1
	v_add_u32_e32 v1, v0, v1
	v_ashrrev_i32_e32 v1, 10, v1
	v_mul_i32_i24_e32 v2, 0x400, v1
	v_sub_u32_e32 v0, v0, v2
	s_nop 1
	v_lshrrev_b32_e32 v2, 4, v0
	s_nop 1
	v_bitop3_b32 v2, v2, v0, 32 bitop3:0x6c
	s_bitcmp1_b32 s92, 0
	v_readlane_b32 s4, v254, 2
	v_ashrrev_i32_e32 v0, 31, v2
	s_cselect_b32 s0, 0x2180000, 0
	s_cmp_eq_u32 s91, 5
	v_readlane_b32 s6, v253, 18
	v_readlane_b32 s7, v253, 19
	s_nop 1
	v_readlane_b32 s5, v254, 3
	v_lshrrev_b32_e32 v0, 26, v0
	s_cselect_b32 s39, s7, s5
	s_cselect_b32 s40, s6, s4
	s_nop 1
	v_add_u32_e32 v4, v2, v0
	v_lshlrev_b32_e32 v5, 3, v1
	v_readlane_b32 s10, v253, 6
	v_readlane_b32 s14, v253, 10
	v_ashrrev_i32_e32 v0, 6, v4
	v_and_b32_e32 v5, -16, v5
	s_movk_i32 s1, 0xb00
	v_readlane_b32 s11, v253, 7
	v_readlane_b32 s15, v253, 11
	s_cselect_b32 s22, s10, s14
	v_add_u32_e32 v5, v0, v5
	s_cselect_b32 s26, 0x400, s1
	s_cselect_b32 s1, s11, s15
	s_add_u32 s41, s22, s0
	v_and_b32_e32 v0, 3, v0
	s_mov_b32 s0, 0xffffe0
	v_lshrrev_b32_e32 v7, 2, v5
	v_lshlrev_b32_e32 v8, 1, v5
	v_and_or_b32 v0, v5, s0, v0
	v_and_b32_e32 v7, 4, v7
	v_and_b32_e32 v8, 24, v8
	v_or3_b32 v0, v0, v7, v8
	v_mul_u32_u24_e32 v7, s26, v0
	v_lshlrev_b32_e32 v0, 5, v1
	v_and_b32_e32 v1, 0xc0, v4
	v_sub_u32_e32 v1, v2, v1
	v_ashrrev_i16_sdwa v1, v250, sext(v1) dst_sel:DWORD dst_unused:UNUSED_PAD src0_sel:DWORD src1_sel:BYTE_0
	v_and_b32_e32 v0, 32, v0
	v_bfe_i32 v1, v1, 0, 16
	v_add_u32_e32 v4, v0, v1
	v_mul_lo_u32 v2, v5, s26
	v_add_lshl_u32 v128, v7, v4, 1
	v_add_lshl_u32 v130, v4, v2, 1
	v_bfe_i32 v4, v6, 27, 1
	v_lshrrev_b32_e32 v4, 22, v4
	v_add_u32_e32 v4, v3, v4
	v_and_b32_e32 v4, 0xfffffc00, v4
	v_sub_u32_e32 v3, v3, v4
	v_lshrrev_b32_e32 v4, 4, v3
	v_bitop3_b32 v4, v4, v3, 32 bitop3:0x6c
	v_ashrrev_i32_e32 v3, 31, v3
	v_lshrrev_b32_e32 v3, 26, v3
	v_add_u32_e32 v3, v4, v3
	v_ashrrev_i32_e32 v5, 6, v3
	v_ashrrev_i32_e32 v3, 31, v6
	v_lshrrev_b32_e32 v3, 26, v3
	v_add_u32_e32 v3, v6, v3
	s_nop 1
	v_ashrrev_i32_e32 v3, 6, v3
	s_addc_u32 s42, s1, 0
	s_ashr_i32 s1, s33, 6
	v_lshlrev_b32_e32 v7, 3, v3
	s_lshr_b32 s45, s20, 1
	v_readlane_b32 s4, v254, 5
	s_lshl_b32 s43, s26, 9
	s_ashr_i32 s27, s33, 8
	s_lshl_b32 s88, s26, 8
	s_lshl_b32 s44, s1, 10
	v_and_b32_e32 v7, -16, v7
	s_or_b32 s46, s45, 1
	v_readlane_b32 s5, v254, 6
	v_add_u32_e32 v7, v5, v7
	v_and_b32_e32 v8, 3, v5
	s_and_b64 s[22:23], s[4:5], exec
	v_and_or_b32 v8, v7, s0, v8
	s_cselect_b32 s0, s46, s45
	v_readlane_b32 s4, v254, 7
	s_mul_i32 s0, s0, s4
	v_readlane_b32 s4, v254, 4
	s_add_i32 s0, s0, s4
	s_ashr_i32 s22, s0, 31
	s_lshr_b32 s22, s22, 27
	s_add_i32 s22, s0, s22
	s_ashr_i32 s23, s22, 5
	s_lshl_b32 s28, s23, 3
	s_sub_i32 s23, s20, s28
	s_min_i32 s29, s23, 8
	v_mul_i32_i24_e32 v5, 64, v5
	s_sext_i32_i8 s23, s29
	v_lshrrev_b32_e32 v9, 2, v7
	v_lshlrev_b32_e32 v10, 1, v7
	v_sub_u32_e32 v4, v4, v5
	v_mul_lo_u32 v5, v7, s26
	v_cvt_f32_i32_e32 v7, s23
	v_and_b32_e32 v9, 4, v9
	v_and_b32_e32 v10, 24, v10
	v_lshlrev_b32_e32 v3, 5, v3
	v_ashrrev_i16_sdwa v4, v250, sext(v4) dst_sel:DWORD dst_unused:UNUSED_PAD src0_sel:DWORD src1_sel:BYTE_0
	v_or3_b32 v8, v8, v9, v10
	v_and_b32_e32 v3, 32, v3
	v_bfe_i32 v4, v4, 0, 16
	s_andn2_b32 s22, s22, 31
	v_mul_u32_u24_e32 v8, s26, v8
	v_add_u32_e32 v9, v3, v4
	s_sub_i32 s30, s0, s22
	v_add_lshl_u32 v184, v8, v9, 1
	v_add_lshl_u32 v132, v9, v5, 1
	v_cvt_f32_i32_e32 v8, s30
	v_rcp_iflag_f32_e32 v9, v7
	s_xor_b32 s0, s30, s23
	s_ashr_i32 s0, s0, 30
	s_or_b32 s0, s0, 1
	v_mul_f32_e32 v9, v8, v9
	v_trunc_f32_e32 v9, v9
	v_fma_f32 v8, -v9, v7, v8
	v_cvt_i32_f32_e32 v9, v9
	v_cmp_ge_f32_e64 s[22:23], |v8|, |v7|
	s_and_b64 s[22:23], s[22:23], exec
	s_cselect_b32 s0, s0, 0
	v_readfirstlane_b32 s22, v9
	s_add_i32 s0, s22, s0
	s_mul_i32 s22, s0, s29
	s_sub_i32 s22, s30, s22
	s_sext_i32_i8 s22, s22
	s_add_i32 s69, s28, s22
	s_bfe_i64 s[22:23], s[0:1], 0x80000
	s_mul_hi_i32 s23, s22, s43
	s_mul_i32 s22, s22, s43
	s_add_u32 s34, s41, s22
	s_mul_i32 s29, s69, s43
	s_addc_u32 s35, s42, s23
	s_add_i32 s47, s44, 0x10000
	s_add_i32 s48, s44, 0x12000
	s_mul_hi_i32 s28, s69, s43
	s_waitcnt vmcnt(0)
	s_mov_b32 m0, s47
	s_add_u32 s30, s40, s29
	global_load_lds_dwordx4 v184, s[34:35]
	s_mov_b32 m0, s48
	s_addc_u32 s31, s39, s28
	s_add_i32 s49, s44, 0x2000
	global_load_lds_dwordx4 v128, s[34:35]
	s_mov_b32 m0, s44
	s_add_u32 s22, s34, s88
	global_load_lds_dwordx4 v132, s[30:31]
	s_mov_b32 m0, s49
	s_addc_u32 s23, s35, 0
	s_add_i32 s50, s44, 0x14000
	s_add_i32 s51, s44, 0x16000
	global_load_lds_dwordx4 v130, s[30:31]
	s_mov_b32 m0, s50
	s_add_u32 s28, s30, s88
	global_load_lds_dwordx4 v184, s[22:23]
	s_mov_b32 m0, s51
	s_addc_u32 s29, s31, 0
	s_add_i32 s52, s44, 0x4000
	global_load_lds_dwordx4 v128, s[22:23]
	s_mov_b32 m0, s52
	s_add_i32 s53, s44, 0x6000
	global_load_lds_dwordx4 v132, s[28:29]
	s_mov_b32 m0, s53
	v_writelane_b32 v255, s84, 43
	global_load_lds_dwordx4 v130, s[28:29]
	s_nop 0
	v_writelane_b32 v255, s85, 44
	v_writelane_b32 v255, s86, 45
	v_writelane_b32 v255, s87, 46
	s_cmp_lg_u32 s27, 1
	s_nop 1
	s_cbranch_scc1 .LBB0_86
	s_barrier

.Lpjh_s7:
	s_setprio 0
	s_add_u32 s30, s30, 0x100
	s_addc_u32 s31, s31, 0
	s_add_u32 s26, s26, 0x100
	s_addc_u32 s27, s27, 0
	s_cmp_ge_u32 s71, s54
	s_mov_b32 s34, s71
	s_barrier
	s_cbranch_scc0 .LBB0_94
	v_lshl_add_u32 v138, s69, 8, v140
	s_cmp_eq_u32 s100, 2
	s_cselect_b32 vcc_lo, 0x80, 0
	s_nop 0
	v_add_u32_e32 v138, vcc_lo, v138
	v_lshl_or_b32 v144, s70, 8, v143
	v_ashrrev_i32_e32 v139, 31, v138
	v_readlane_b32 s4, v253, 16
	v_ashrrev_i32_e32 v145, 31, v144
	v_cvt_pk_bf16_f32 v124, v124, v125
	v_cvt_pk_bf16_f32 v125, v126, v127
	v_cvt_pk_bf16_f32 v126, v120, v121
	v_lshlrev_b64 v[120:121], 11, v[138:139]
	v_readlane_b32 s5, v253, 17
	v_cvt_pk_bf16_f32 v127, v122, v123
	v_lshlrev_b64 v[122:123], 1, v[144:145]
	v_cvt_pk_bf16_f32 v116, v116, v117
	v_cvt_pk_bf16_f32 v117, v118, v119
	v_cvt_pk_bf16_f32 v119, v114, v115
	s_nop 0
	v_lshl_add_u64 v[120:121], s[4:5], 0, v[120:121]
	v_lshl_add_u64 v[120:121], v[120:121], 0, v[122:123]
	global_store_dwordx4 v[120:121], v[124:127], off
	v_or_b32_e32 v114, 32, v138
	v_cvt_pk_bf16_f32 v108, v108, v109
	v_cvt_pk_bf16_f32 v109, v110, v111
	v_cvt_pk_bf16_f32 v111, v106, v107
	v_or_b32_e32 v106, 48, v138
	v_or_b32_e32 v124, 16, v138
	v_cvt_pk_bf16_f32 v68, v68, v69
	v_cvt_pk_bf16_f32 v69, v70, v71
	v_cvt_pk_bf16_f32 v70, v64, v65
	v_add_u32_e32 v64, 0x80, v138
	v_cvt_pk_bf16_f32 v60, v60, v61
	v_cvt_pk_bf16_f32 v61, v62, v63
	v_cvt_pk_bf16_f32 v63, v58, v59
	v_add_u32_e32 v58, 0x90, v138
	v_cvt_pk_bf16_f32 v52, v52, v53
	v_cvt_pk_bf16_f32 v53, v54, v55
	v_cvt_pk_bf16_f32 v55, v50, v51
	v_add_u32_e32 v50, 0xa0, v138
	v_cvt_pk_bf16_f32 v44, v44, v45
	v_cvt_pk_bf16_f32 v45, v46, v47
	v_cvt_pk_bf16_f32 v47, v42, v43
	v_add_u32_e32 v42, 0xb0, v138
	v_ashrrev_i32_e32 v125, 31, v124
	v_ashrrev_i32_e32 v115, 31, v114
	v_ashrrev_i32_e32 v107, 31, v106
	v_ashrrev_i32_e32 v65, 31, v64
	v_ashrrev_i32_e32 v59, 31, v58
	v_ashrrev_i32_e32 v51, 31, v50
	v_ashrrev_i32_e32 v43, 31, v42
	v_cvt_pk_bf16_f32 v118, v112, v113
	v_lshlrev_b64 v[112:113], 11, v[124:125]
	v_cvt_pk_bf16_f32 v110, v104, v105
	v_lshlrev_b64 v[104:105], 11, v[114:115]
	v_cvt_pk_bf16_f32 v100, v100, v101
	v_cvt_pk_bf16_f32 v101, v102, v103
	v_cvt_pk_bf16_f32 v102, v96, v97
	v_lshlrev_b64 v[96:97], 11, v[106:107]
	v_cvt_pk_bf16_f32 v62, v56, v57
	v_lshlrev_b64 v[56:57], 11, v[64:65]
	v_cvt_pk_bf16_f32 v54, v48, v49
	v_lshlrev_b64 v[48:49], 11, v[58:59]
	v_cvt_pk_bf16_f32 v46, v40, v41
	v_lshlrev_b64 v[40:41], 11, v[50:51]
	v_cvt_pk_bf16_f32 v36, v36, v37
	v_cvt_pk_bf16_f32 v37, v38, v39
	v_cvt_pk_bf16_f32 v38, v32, v33
	v_lshlrev_b64 v[32:33], 11, v[42:43]
	v_lshl_add_u64 v[112:113], s[4:5], 0, v[112:113]
	v_lshl_add_u64 v[104:105], s[4:5], 0, v[104:105]
	v_lshl_add_u64 v[96:97], s[4:5], 0, v[96:97]
	v_lshl_add_u64 v[56:57], s[4:5], 0, v[56:57]
	v_lshl_add_u64 v[48:49], s[4:5], 0, v[48:49]
	v_lshl_add_u64 v[40:41], s[4:5], 0, v[40:41]
	v_lshl_add_u64 v[32:33], s[4:5], 0, v[32:33]
	v_lshl_add_u64 v[112:113], v[112:113], 0, v[122:123]
	v_lshl_add_u64 v[104:105], v[104:105], 0, v[122:123]
	v_lshl_add_u64 v[96:97], v[96:97], 0, v[122:123]
	v_lshl_add_u64 v[56:57], v[56:57], 0, v[122:123]
	v_lshl_add_u64 v[48:49], v[48:49], 0, v[122:123]
	v_lshl_add_u64 v[40:41], v[40:41], 0, v[122:123]
	v_lshl_add_u64 v[32:33], v[32:33], 0, v[122:123]
	s_and_b64 vcc, exec, s[22:23]
	s_mov_b32 s70, s65
	s_mov_b32 s69, s68
	s_mov_b64 s[34:35], s[0:1]
	s_mov_b64 s[30:31], s[28:29]
	s_mov_b32 s71, 0x42ce8ed0
	s_nop 1
	global_store_dwordx4 v[112:113], v[116:119], off
	global_store_dwordx4 v[104:105], v[108:111], off
	v_cvt_pk_bf16_f32 v103, v98, v99
	global_store_dwordx4 v[96:97], v[100:103], off
	v_cvt_pk_bf16_f32 v92, v92, v93
	v_cvt_pk_bf16_f32 v93, v94, v95
	v_cvt_pk_bf16_f32 v94, v88, v89
	v_cvt_pk_bf16_f32 v95, v90, v91
	global_store_dwordx4 v[120:121], v[92:95], off offset:256
	v_cvt_pk_bf16_f32 v84, v84, v85
	v_cvt_pk_bf16_f32 v85, v86, v87
	v_cvt_pk_bf16_f32 v86, v80, v81
	v_cvt_pk_bf16_f32 v87, v82, v83
	global_store_dwordx4 v[112:113], v[84:87], off offset:256
	v_cvt_pk_bf16_f32 v76, v76, v77
	v_cvt_pk_bf16_f32 v77, v78, v79
	v_cvt_pk_bf16_f32 v78, v72, v73
	v_cvt_pk_bf16_f32 v79, v74, v75
	global_store_dwordx4 v[104:105], v[76:79], off offset:256
	v_cvt_pk_bf16_f32 v71, v66, v67
	global_store_dwordx4 v[96:97], v[68:71], off offset:256
	s_cmp_lg_u32 s100, 0
	s_cbranch_scc1 .Lpjh_nost
	global_store_dwordx4 v[56:57], v[60:63], off
	global_store_dwordx4 v[48:49], v[52:55], off
	global_store_dwordx4 v[40:41], v[44:47], off
	v_cvt_pk_bf16_f32 v39, v34, v35
	global_store_dwordx4 v[32:33], v[36:39], off
	v_cvt_pk_bf16_f32 v28, v28, v29
	v_cvt_pk_bf16_f32 v29, v30, v31
	v_cvt_pk_bf16_f32 v30, v24, v25
	v_cvt_pk_bf16_f32 v31, v26, v27
	global_store_dwordx4 v[56:57], v[28:31], off offset:256
	v_cvt_pk_bf16_f32 v20, v20, v21
	v_cvt_pk_bf16_f32 v21, v22, v23
	v_cvt_pk_bf16_f32 v22, v16, v17
	v_cvt_pk_bf16_f32 v23, v18, v19
	global_store_dwordx4 v[48:49], v[20:23], off offset:256
	v_cvt_pk_bf16_f32 v12, v12, v13
	v_cvt_pk_bf16_f32 v13, v14, v15
	v_cvt_pk_bf16_f32 v14, v8, v9
	v_cvt_pk_bf16_f32 v15, v10, v11
	global_store_dwordx4 v[40:41], v[12:15], off offset:256
	v_cvt_pk_bf16_f32 v4, v4, v5
	v_cvt_pk_bf16_f32 v5, v6, v7
	v_cvt_pk_bf16_f32 v6, v0, v1
	v_cvt_pk_bf16_f32 v7, v2, v3
	global_store_dwordx4 v[32:33], v[4:7], off offset:256

.LBB0_98:
	v_readlane_b32 s64, v255, 43
	v_readlane_b32 s65, v255, 44
	s_mov_b64 s[84:85], s[64:65]
	s_barrier
	s_nop 1

.LBB0_103:
	s_andn2_b64 vcc, exec, s[0:1]
	s_cbranch_vccnz .LBB0_149
	v_bfe_i32 v2, v0, 27, 1
	v_lshlrev_b32_e32 v4, 4, v0
	v_lshrrev_b32_e32 v2, 22, v2
	v_add_u32_e32 v2, v4, v2
	v_and_b32_e32 v2, 0xfffffc00, v2
	v_sub_u32_e32 v2, v4, v2
	v_lshrrev_b32_e32 v3, 4, v2
	v_bitop3_b32 v3, v3, v2, 32 bitop3:0x6c
	v_ashrrev_i32_e32 v2, 31, v2
	v_lshrrev_b32_e32 v2, 26, v2
	v_ashrrev_i32_e32 v1, 31, v0
	v_add_u32_e32 v2, v3, v2
	v_lshrrev_b32_e32 v1, 26, v1
	v_ashrrev_i32_e32 v2, 6, v2
	v_add_u32_e32 v1, v0, v1
	v_mul_i32_i24_e32 v7, 64, v2
	v_ashrrev_i32_e32 v1, 6, v1
	v_sub_u32_e32 v3, v3, v7
	v_lshlrev_b32_e32 v5, 3, v1
	v_lshlrev_b32_e32 v6, 5, v1
	v_ashrrev_i16_sdwa v3, v250, sext(v3) dst_sel:DWORD dst_unused:UNUSED_PAD src0_sel:DWORD src1_sel:BYTE_0
	v_and_b32_e32 v5, -16, v5
	v_and_b32_e32 v6, 32, v6
	v_bfe_i32 v3, v3, 0, 16
	v_add_u32_e32 v5, v2, v5
	v_and_b32_e32 v9, 3, v2
	s_mov_b32 s1, 0x7fffe0
	v_add_lshl_u32 v6, v6, v3, 1
	v_lshlrev_b32_e32 v7, 1, v5
	v_lshrrev_b32_e32 v8, 2, v5
	v_and_or_b32 v9, v5, s1, v9
	v_lshl_add_u32 v186, v5, 11, v6
	v_add_u32_e32 v5, 0x2000, v4
	v_ashrrev_i32_e32 v4, 31, v5
	v_lshrrev_b32_e32 v4, 22, v4
	v_and_b32_e32 v7, 24, v7
	v_and_b32_e32 v8, 4, v8
	v_add_u32_e32 v4, v5, v4
	v_or3_b32 v7, v9, v8, v7
	v_ashrrev_i32_e32 v4, 10, v4
	v_lshl_add_u32 v184, v7, 9, v6
	v_mul_i32_i24_e32 v6, 0x400, v4
	v_sub_u32_e32 v5, v5, v6
	v_lshrrev_b32_e32 v6, 4, v5
	v_bitop3_b32 v6, v6, v5, 32 bitop3:0x6c
	v_lshlrev_b32_e32 v5, 3, v4
	s_bitcmp1_b32 s92, 0
	s_nop 1
	v_and_b32_e32 v7, -16, v5
	v_ashrrev_i32_e32 v5, 31, v6
	s_cselect_b32 s0, 0x2180000, 0
	v_readlane_b32 s8, v253, 4
	v_lshrrev_b32_e32 v5, 26, v5
	v_readlane_b32 s9, v253, 5
	s_add_u32 s66, s8, s0
	v_add_u32_e32 v8, v6, v5
	s_addc_u32 s67, s9, 0
	v_ashrrev_i32_e32 v5, 6, v8
	s_lshl_b32 s26, s55, 8
	s_ashr_i32 s0, s30, 6
	v_add_u32_e32 v7, v5, v7
	v_and_b32_e32 v8, 0xc0, v8
	v_and_b32_e32 v11, 3, v5
	s_ashr_i32 s53, s52, 31
	s_ashr_i32 s27, s26, 31
	s_nop 1
	v_sub_u32_e32 v6, v6, v8
	v_and_or_b32 v11, v7, s1, v11
	s_ashr_i32 s1, s30, 8
	s_lshl_b32 s59, s0, 10
	s_lshl_b64 s[22:23], s[52:53], 19
	s_lshl_b64 s[26:27], s[26:27], 9
	v_lshlrev_b32_e32 v9, 5, v4
	v_ashrrev_i16_sdwa v6, v250, sext(v6) dst_sel:DWORD dst_unused:UNUSED_PAD src0_sel:DWORD src1_sel:BYTE_0
	v_lshlrev_b32_e32 v8, 1, v7
	v_lshrrev_b32_e32 v10, 2, v7
	s_add_u32 s28, s66, s26
	s_nop 1
	v_and_b32_e32 v9, 32, v9
	v_bfe_i32 v6, v6, 0, 16
	v_and_b32_e32 v8, 24, v8
	v_and_b32_e32 v10, 4, v10
	s_addc_u32 s29, s67, s27
	s_add_i32 s53, s59, 0x10000
	s_add_i32 s60, s59, 0x12000
	v_readlane_b32 s8, v253, 20
	v_or3_b32 v8, v11, v10, v8
	v_add_lshl_u32 v9, v9, v6, 1
	s_waitcnt vmcnt(0)
	s_mov_b32 m0, s53
	v_readlane_b32 s9, v253, 21
	s_add_u32 s22, s8, s22
	v_lshl_add_u32 v190, v8, 9, v9
	global_load_lds_dwordx4 v184, s[28:29]
	s_mov_b32 m0, s60
	s_addc_u32 s23, s9, s23
	s_add_i32 s61, s59, 0x2000
	global_load_lds_dwordx4 v190, s[28:29]
	s_mov_b32 m0, s59
	s_add_u32 s26, s28, 0x10000
	v_lshl_add_u32 v188, v7, 11, v9
	global_load_lds_dwordx4 v186, s[22:23]
	s_mov_b32 m0, s61
	s_addc_u32 s27, s29, 0
	s_add_i32 s62, s59, 0x14000
	global_load_lds_dwordx4 v188, s[22:23]
	s_mov_b32 m0, s62
	s_add_i32 s63, s59, 0x16000
	global_load_lds_dwordx4 v184, s[26:27]
	s_mov_b32 m0, s63
	v_writelane_b32 v255, s84, 43
	global_load_lds_dwordx4 v190, s[26:27]
	s_add_u32 s26, s22, 0x40000
	s_addc_u32 s27, s23, 0
	s_add_i32 s64, s59, 0x4000
	s_mov_b32 m0, s64
	s_add_i32 s65, s59, 0x6000
	global_load_lds_dwordx4 v186, s[26:27]
	s_mov_b32 m0, s65
	v_writelane_b32 v255, s85, 44
	global_load_lds_dwordx4 v188, s[26:27]
	v_writelane_b32 v255, s86, 45
	v_writelane_b32 v255, s87, 46
	v_mov_b32_e32 v227, 0x23804
	v_mov_b32_e32 v226, 0x23800
	v_mov_b32_e32 v225, v234
	v_mov_b32_e32 v237, 1
	s_mov_b32 s85, s30
	s_cmp_lg_u32 s1, 1
	s_nop 1
	s_cbranch_scc1 .LBB0_106
	s_barrier

.LBB0_110:
	s_lshl_b32 s36, s43, 8
	s_ashr_i32 s45, s44, 31
	s_ashr_i32 s37, s36, 31
	s_nop 1
	s_lshl_b64 s[38:39], s[44:45], 19
	s_lshl_b64 s[36:37], s[36:37], 1
	v_readlane_b32 s8, v253, 20
	v_readlane_b32 s9, v253, 21
	s_add_u32 s27, s8, s38
	s_addc_u32 s33, s9, s39
	s_add_u32 s48, s27, s36
	s_addc_u32 s49, s33, s37
	s_lshl_b32 s27, s43, 10
	s_lshl_b32 s33, s42, 8
	s_add_i32 s36, s33, s27
	s_nop 1
	s_ashr_i32 s37, s36, 31
	s_lshl_b64 s[36:37], s[36:37], 9
	v_readlane_b32 s4, v255, 47
	s_add_u32 s50, s66, s36
	v_readlane_b32 s5, v255, 48
	s_addc_u32 s51, s67, s37
	s_andn2_b64 vcc, exec, s[4:5]
	s_nop 1
	s_cbranch_vccnz .LBB0_114
	s_and_b64 s[30:31], s[30:31], exec
	s_cselect_b32 s27, s49, s23
	s_cselect_b32 s33, s48, s22
	s_cselect_b32 s36, s51, s29
	s_cselect_b32 s37, s50, s28
	s_add_u32 s22, s22, 0x40080
	s_addc_u32 s23, s23, 0
	s_add_u32 s38, s28, 0x100
	s_mov_b32 s5, s67
	s_mov_b32 s4, s66
	s_addc_u32 s39, s29, 0
	s_mov_b32 s28, 0

.LBB0_114:
	s_lshl_b32 s22, s52, 4
	s_lshl_b32 s28, s26, 5
	s_add_i32 s22, s22, s20
	s_ashr_i32 s29, s28, 31
	s_lshl_b32 s27, s55, 3
	s_ashr_i32 s23, s22, 31
	s_ashr_i32 s30, s27, 31
	s_or_b64 s[28:29], s[28:29], s[0:1]
	s_add_u32 s28, s28, s27
	s_addc_u32 s29, s29, s30
	s_lshl_b64 s[22:23], s[22:23], 17
	s_lshl_b64 s[28:29], s[28:29], 10
	s_add_u32 s22, s78, s22
	s_addc_u32 s23, s79, s23
	s_add_u32 s22, s22, s28
	s_addc_u32 s23, s23, s29
	v_mov_b32_e32 v100, v245
	s_cmp_eq_u32 s26, 3
	s_cselect_b64 s[36:37], -1, 0
	v_ashrrev_i32_e32 v101, 31, v100
	v_lshl_add_u64 v[208:209], v[100:101], 4, s[22:23]
	s_and_b64 s[28:29], s[36:37], exec
	global_load_dwordx4 v[198:201], v[208:209], off
	s_cselect_b32 s27, 0, 0x800
	s_lshl_b32 s88, s27, 4
	v_lshl_add_u64 v[100:101], v[208:209], 0, s[88:89]
	global_load_dwordx4 v[202:205], v[100:101], off
	s_mov_b64 s[22:23], 0x20000
	v_lshl_add_u64 v[100:101], v[208:209], 0, s[22:23]
	s_mov_b32 s22, 0x21000
	v_add_co_u32_e32 v102, vcc, s22, v208
	v_lshl_add_u64 v[100:101], v[100:101], 0, s[88:89]
	s_nop 0
	v_addc_co_u32_e32 v103, vcc, 0, v209, vcc
	s_mov_b64 s[22:23], 0x40000
	global_load_dwordx4 v[180:183], v[102:103], off offset:-4096
	global_load_dwordx4 v[176:179], v[100:101], off
	v_lshl_add_u64 v[100:101], v[208:209], 0, s[22:23]
	s_mov_b32 s22, 0x41000
	v_lshl_add_u64 v[100:101], v[100:101], 0, s[88:89]
	v_add_co_u32_e32 v104, vcc, s22, v208
	global_load_dwordx4 v[172:175], v[100:101], off
	global_load_dwordx4 v[140:143], v[102:103], off
	v_lshl_add_u64 v[100:101], v[208:209], 0, s[82:83]
	v_addc_co_u32_e32 v105, vcc, 0, v209, vcc
	v_lshl_add_u64 v[100:101], v[100:101], 0, s[88:89]
	global_load_dwordx4 v[168:171], v[104:105], off offset:-4096
	global_load_dwordx4 v[160:163], v[100:101], off
	s_mov_b32 s22, 0x61000
	v_lshl_add_u64 v[100:101], v[208:209], 0, s[94:95]
	v_add_co_u32_e32 v106, vcc, s22, v208
	v_lshl_add_u64 v[100:101], v[100:101], 0, s[88:89]
	s_mov_b64 s[22:23], 0x21000
	global_load_dwordx4 v[152:155], v[100:101], off
	global_load_dwordx4 v[120:123], v[104:105], off
	v_lshl_add_u64 v[100:101], v[208:209], 0, s[22:23]
	v_addc_co_u32_e32 v107, vcc, 0, v209, vcc
	s_movk_i32 s4, 0x1000
	v_lshl_add_u64 v[100:101], v[100:101], 0, s[88:89]
	s_mov_b64 s[22:23], 0x41000
	global_load_dwordx4 v[164:167], v[106:107], off offset:-4096
	global_load_dwordx4 v[132:135], v[100:101], off
	v_add_co_u32_e32 v116, vcc, s4, v208
	v_lshl_add_u64 v[100:101], v[208:209], 0, s[22:23]
	s_nop 0
	v_addc_co_u32_e32 v117, vcc, 0, v209, vcc
	v_lshl_add_u64 v[100:101], v[100:101], 0, s[88:89]
	s_mov_b64 s[22:23], 0x61000
	global_load_dwordx4 v[156:159], v[116:117], off
	s_movk_i32 s33, 0x3fff
	global_load_dwordx4 v[116:119], v[100:101], off
	s_cmp_lg_u32 s26, 3
	global_load_dwordx4 v[104:107], v[106:107], off
	v_lshl_add_u64 v[100:101], v[208:209], 0, s[22:23]
	v_lshl_add_u64 v[100:101], v[100:101], 0, s[88:89]
	global_load_dwordx4 v[100:103], v[100:101], off
	v_lshl_add_u32 v216, s52, 8, v242
	s_waitcnt vmcnt(14)
	v_lshlrev_b32_e32 v206, 16, v198
	v_and_b32_e32 v207, 0xffff0000, v198
	v_rcp_f32_e32 v206, v206
	v_rcp_f32_e32 v207, v207
	v_lshlrev_b32_e32 v210, 16, v199
	v_and_b32_e32 v211, 0xffff0000, v199
	v_lshlrev_b32_e32 v198, 16, v202
	v_and_b32_e32 v199, 0xffff0000, v202
	v_pk_mul_f32 v[198:199], v[206:207], v[198:199]
	v_lshlrev_b32_e32 v212, 16, v200
	v_cndmask_b32_e64 v199, v199, v207, s[36:37]
	v_cndmask_b32_e64 v198, v198, v206, s[36:37]
	v_pk_mul_f32 v[198:199], v[148:149], v[198:199]
	v_rcp_f32_e32 v148, v210
	v_rcp_f32_e32 v149, v211
	v_and_b32_e32 v213, 0xffff0000, v200
	v_lshlrev_b32_e32 v214, 16, v201
	v_and_b32_e32 v215, 0xffff0000, v201
	v_lshlrev_b32_e32 v200, 16, v203
	v_and_b32_e32 v201, 0xffff0000, v203
	v_pk_mul_f32 v[200:201], v[148:149], v[200:201]
	v_lshlrev_b32_e32 v202, 16, v204
	v_cndmask_b32_e64 v149, v201, v149, s[36:37]
	v_cndmask_b32_e64 v148, v200, v148, s[36:37]
	v_pk_mul_f32 v[200:201], v[150:151], v[148:149]
	v_rcp_f32_e32 v148, v212
	v_rcp_f32_e32 v149, v213
	v_and_b32_e32 v203, 0xffff0000, v204
	v_lshlrev_b32_e32 v204, 16, v205
	v_and_b32_e32 v205, 0xffff0000, v205
	v_pk_mul_f32 v[150:151], v[148:149], v[202:203]
	v_lshl_or_b32 v206, s55, 8, v192
	v_cndmask_b32_e64 v149, v151, v149, s[36:37]
	v_cndmask_b32_e64 v148, v150, v148, s[36:37]
	v_pk_mul_f32 v[202:203], v[144:145], v[148:149]
	v_rcp_f32_e32 v144, v214
	v_rcp_f32_e32 v145, v215
	s_nop 0
	v_pk_mul_f32 v[148:149], v[144:145], v[204:205]
	s_nop 0
	v_cndmask_b32_e64 v145, v149, v145, s[36:37]
	v_cndmask_b32_e64 v144, v148, v144, s[36:37]
	v_pk_mul_f32 v[204:205], v[146:147], v[144:145]
	s_cbranch_scc1 .LBB0_116
	v_ashrrev_i32_e32 v217, 31, v216
	s_nop 1
	v_lshlrev_b64 v[148:149], 11, v[216:217]
	v_readlane_b32 s6, v253, 18
	v_readlane_b32 s7, v253, 19
	v_ashrrev_i32_e32 v207, 31, v206
	v_cvt_pk_bf16_f32 v144, v198, v199
	v_cvt_pk_bf16_f32 v145, v200, v201
	v_cvt_pk_bf16_f32 v146, v202, v203
	v_cvt_pk_bf16_f32 v147, v204, v205
	s_nop 0
	v_lshl_add_u64 v[148:149], s[6:7], 0, v[148:149]
	v_lshl_add_u64 v[148:149], v[206:207], 1, v[148:149]
	s_nop 1
	global_store_dwordx4 v[148:149], v[144:147], off
.LBB0_116:
	s_waitcnt vmcnt(12)
	v_lshlrev_b32_e32 v207, 16, v180
	v_and_b32_e32 v180, 0xffff0000, v180
	v_lshlrev_b32_e32 v144, 16, v176
	v_and_b32_e32 v145, 0xffff0000, v176
	v_lshlrev_b32_e32 v146, 16, v177
	v_and_b32_e32 v147, 0xffff0000, v177
	v_rcp_f32_e32 v176, v207
	v_rcp_f32_e32 v177, v180
	v_lshlrev_b32_e32 v210, 16, v181
	v_and_b32_e32 v181, 0xffff0000, v181
	v_lshlrev_b32_e32 v211, 16, v182
	v_pk_mul_f32 v[144:145], v[176:177], v[144:145]
	v_and_b32_e32 v182, 0xffff0000, v182
	v_cndmask_b32_e64 v145, v145, v177, s[36:37]
	v_cndmask_b32_e64 v144, v144, v176, s[36:37]
	v_pk_mul_f32 v[176:177], v[136:137], v[144:145]
	v_rcp_f32_e32 v136, v210
	v_rcp_f32_e32 v137, v181
	v_lshlrev_b32_e32 v148, 16, v178
	v_and_b32_e32 v149, 0xffff0000, v178
	v_lshlrev_b32_e32 v150, 16, v179
	v_pk_mul_f32 v[144:145], v[136:137], v[146:147]
	v_and_b32_e32 v151, 0xffff0000, v179
	v_cndmask_b32_e64 v137, v145, v137, s[36:37]
	v_cndmask_b32_e64 v136, v144, v136, s[36:37]
	v_pk_mul_f32 v[178:179], v[138:139], v[136:137]
	v_rcp_f32_e32 v136, v211
	v_rcp_f32_e32 v137, v182
	v_lshlrev_b32_e32 v212, 16, v183
	v_and_b32_e32 v183, 0xffff0000, v183
	s_andn2_b64 vcc, exec, s[36:37]
	v_pk_mul_f32 v[138:139], v[136:137], v[148:149]
	s_nop 0
	v_cndmask_b32_e64 v137, v139, v137, s[36:37]
	v_cndmask_b32_e64 v136, v138, v136, s[36:37]
	v_pk_mul_f32 v[180:181], v[128:129], v[136:137]
	v_rcp_f32_e32 v128, v212
	v_rcp_f32_e32 v129, v183
	s_nop 0
	v_pk_mul_f32 v[136:137], v[128:129], v[150:151]
	s_nop 0
	v_cndmask_b32_e64 v129, v137, v129, s[36:37]
	v_cndmask_b32_e64 v128, v136, v128, s[36:37]
	v_pk_mul_f32 v[182:183], v[130:131], v[128:129]
	v_cndmask_b32_e64 v128, 0, 1, s[36:37]
	v_cmp_ne_u32_e64 s[38:39], 1, v128
	v_or_b32_e32 v128, 16, v242
	v_lshl_add_u32 v214, s52, 8, v128
	s_cbranch_vccnz .LBB0_118
	v_ashrrev_i32_e32 v215, 31, v214
	s_nop 1
	v_lshlrev_b64 v[136:137], 11, v[214:215]
	v_readlane_b32 s6, v253, 18
	v_readlane_b32 s7, v253, 19
	v_ashrrev_i32_e32 v207, 31, v206
	v_cvt_pk_bf16_f32 v128, v176, v177
	v_cvt_pk_bf16_f32 v129, v178, v179
	v_cvt_pk_bf16_f32 v130, v180, v181
	v_cvt_pk_bf16_f32 v131, v182, v183
	s_nop 0
	v_lshl_add_u64 v[136:137], s[6:7], 0, v[136:137]
	v_lshl_add_u64 v[136:137], v[206:207], 1, v[136:137]
	s_nop 1
	global_store_dwordx4 v[136:137], v[128:131], off
.LBB0_118:
	s_waitcnt vmcnt(9)
	v_lshlrev_b32_e32 v144, 16, v168
	v_and_b32_e32 v145, 0xffff0000, v168
	v_rcp_f32_e32 v144, v144
	v_rcp_f32_e32 v145, v145
	v_lshlrev_b32_e32 v128, 16, v172
	v_and_b32_e32 v129, 0xffff0000, v172
	v_lshlrev_b32_e32 v146, 16, v169
	v_pk_mul_f32 v[128:129], v[144:145], v[128:129]
	v_and_b32_e32 v147, 0xffff0000, v169
	v_cndmask_b32_e64 v129, v129, v145, s[36:37]
	v_cndmask_b32_e64 v128, v128, v144, s[36:37]
	v_pk_mul_f32 v[168:169], v[124:125], v[128:129]
	v_rcp_f32_e32 v124, v146
	v_rcp_f32_e32 v125, v147
	v_lshlrev_b32_e32 v130, 16, v173
	v_and_b32_e32 v131, 0xffff0000, v173
	v_lshlrev_b32_e32 v148, 16, v170
	v_pk_mul_f32 v[128:129], v[124:125], v[130:131]
	v_and_b32_e32 v149, 0xffff0000, v170
	v_cndmask_b32_e64 v125, v129, v125, s[36:37]
	v_cndmask_b32_e64 v124, v128, v124, s[36:37]
	v_lshlrev_b32_e32 v150, 16, v171
	v_and_b32_e32 v151, 0xffff0000, v171
	v_pk_mul_f32 v[170:171], v[126:127], v[124:125]
	v_rcp_f32_e32 v124, v148
	v_rcp_f32_e32 v125, v149
	v_lshlrev_b32_e32 v136, 16, v174
	v_and_b32_e32 v137, 0xffff0000, v174
	v_lshlrev_b32_e32 v138, 16, v175
	v_pk_mul_f32 v[126:127], v[124:125], v[136:137]
	v_and_b32_e32 v139, 0xffff0000, v175
	v_cndmask_b32_e64 v125, v127, v125, s[36:37]
	v_cndmask_b32_e64 v124, v126, v124, s[36:37]
	v_pk_mul_f32 v[172:173], v[112:113], v[124:125]
	v_rcp_f32_e32 v112, v150
	v_rcp_f32_e32 v113, v151
	s_and_b64 vcc, exec, s[38:39]
	v_pk_mul_f32 v[124:125], v[112:113], v[138:139]
	s_nop 0
	v_cndmask_b32_e64 v113, v125, v113, s[36:37]
	v_cndmask_b32_e64 v112, v124, v112, s[36:37]
	v_pk_mul_f32 v[174:175], v[114:115], v[112:113]
	v_or_b32_e32 v112, 32, v242
	v_lshl_add_u32 v212, s52, 8, v112
	s_cbranch_vccnz .LBB0_120
	v_ashrrev_i32_e32 v213, 31, v212
	s_nop 1
	v_lshlrev_b64 v[124:125], 11, v[212:213]
	v_readlane_b32 s6, v253, 18
	v_readlane_b32 s7, v253, 19
	v_ashrrev_i32_e32 v207, 31, v206
	v_cvt_pk_bf16_f32 v112, v168, v169
	v_cvt_pk_bf16_f32 v113, v170, v171
	v_cvt_pk_bf16_f32 v114, v172, v173
	v_cvt_pk_bf16_f32 v115, v174, v175
	s_nop 0
	v_lshl_add_u64 v[124:125], s[6:7], 0, v[124:125]
	v_lshl_add_u64 v[124:125], v[206:207], 1, v[124:125]
	s_nop 1
	global_store_dwordx4 v[124:125], v[112:115], off
.LBB0_120:
	s_waitcnt vmcnt(5)
	v_lshlrev_b32_e32 v128, 16, v164
	v_and_b32_e32 v129, 0xffff0000, v164
	v_rcp_f32_e32 v128, v128
	v_rcp_f32_e32 v129, v129
	v_lshlrev_b32_e32 v112, 16, v160
	v_and_b32_e32 v113, 0xffff0000, v160
	v_lshlrev_b32_e32 v130, 16, v165
	v_pk_mul_f32 v[112:113], v[128:129], v[112:113]
	v_and_b32_e32 v131, 0xffff0000, v165
	v_cndmask_b32_e64 v113, v113, v129, s[36:37]
	v_cndmask_b32_e64 v112, v112, v128, s[36:37]
	v_lshlrev_b32_e32 v114, 16, v161
	v_and_b32_e32 v115, 0xffff0000, v161
	v_pk_mul_f32 v[160:161], v[108:109], v[112:113]
	v_rcp_f32_e32 v108, v130
	v_rcp_f32_e32 v109, v131
	v_lshlrev_b32_e32 v136, 16, v166
	v_and_b32_e32 v137, 0xffff0000, v166
	v_lshlrev_b32_e32 v124, 16, v162
	v_pk_mul_f32 v[112:113], v[108:109], v[114:115]
	v_and_b32_e32 v125, 0xffff0000, v162
	v_cndmask_b32_e64 v109, v113, v109, s[36:37]
	v_cndmask_b32_e64 v108, v112, v108, s[36:37]
	v_lshlrev_b32_e32 v126, 16, v163
	v_and_b32_e32 v127, 0xffff0000, v163
	v_pk_mul_f32 v[162:163], v[110:111], v[108:109]
	v_rcp_f32_e32 v108, v136
	v_rcp_f32_e32 v109, v137
	v_lshlrev_b32_e32 v138, 16, v167
	v_and_b32_e32 v139, 0xffff0000, v167
	s_and_b64 vcc, exec, s[38:39]
	v_pk_mul_f32 v[110:111], v[108:109], v[124:125]
	v_lshl_add_u32 v210, s52, 8, v246
	v_cndmask_b32_e64 v109, v111, v109, s[36:37]
	v_cndmask_b32_e64 v108, v110, v108, s[36:37]
	v_pk_mul_f32 v[164:165], v[96:97], v[108:109]
	v_rcp_f32_e32 v96, v138
	v_rcp_f32_e32 v97, v139
	s_nop 0
	v_pk_mul_f32 v[108:109], v[96:97], v[126:127]
	s_nop 0
	v_cndmask_b32_e64 v97, v109, v97, s[36:37]
	v_cndmask_b32_e64 v96, v108, v96, s[36:37]
	v_pk_mul_f32 v[166:167], v[98:99], v[96:97]
	s_cbranch_vccnz .LBB0_122
	v_ashrrev_i32_e32 v211, 31, v210
	s_nop 1
	v_lshlrev_b64 v[108:109], 11, v[210:211]
	v_readlane_b32 s6, v253, 18
	v_readlane_b32 s7, v253, 19
	v_ashrrev_i32_e32 v207, 31, v206
	v_cvt_pk_bf16_f32 v96, v160, v161
	v_cvt_pk_bf16_f32 v97, v162, v163
	v_cvt_pk_bf16_f32 v98, v164, v165
	v_cvt_pk_bf16_f32 v99, v166, v167
	s_nop 0
	v_lshl_add_u64 v[108:109], s[6:7], 0, v[108:109]
	v_lshl_add_u64 v[108:109], v[206:207], 1, v[108:109]
	s_nop 1
	global_store_dwordx4 v[108:109], v[96:99], off
.LBB0_122:
	s_mov_b64 s[22:23], 0x100000
	s_nop 0
	v_lshl_add_u64 v[96:97], v[208:209], 0, s[22:23]
	v_add_co_u32_e32 v98, vcc, 0x100000, v208
	v_lshl_add_u64 v[96:97], v[96:97], 0, s[88:89]
	s_nop 0
	v_addc_co_u32_e32 v99, vcc, 0, v209, vcc
	s_mov_b64 s[22:23], 0x120000
	global_load_dwordx4 v[144:147], v[98:99], off
	global_load_dwordx4 v[148:151], v[96:97], off
	v_lshl_add_u64 v[96:97], v[208:209], 0, s[22:23]
	v_add_co_u32_e32 v98, vcc, 0x120000, v208
	v_lshl_add_u64 v[96:97], v[96:97], 0, s[88:89]
	s_nop 0
	v_addc_co_u32_e32 v99, vcc, 0, v209, vcc
	s_mov_b64 s[22:23], 0x140000
	global_load_dwordx4 v[128:131], v[98:99], off
	global_load_dwordx4 v[136:139], v[96:97], off
	v_lshl_add_u64 v[96:97], v[208:209], 0, s[22:23]
	v_add_co_u32_e32 v98, vcc, 0x140000, v208
	v_lshl_add_u64 v[96:97], v[96:97], 0, s[88:89]
	s_nop 0
	v_addc_co_u32_e32 v99, vcc, 0, v209, vcc
	s_mov_b64 s[22:23], 0x160000
	global_load_dwordx4 v[112:115], v[98:99], off
	global_load_dwordx4 v[124:127], v[96:97], off
	v_lshl_add_u64 v[108:109], v[208:209], 0, s[22:23]
	v_add_co_u32_e32 v96, vcc, 0x160000, v208
	v_lshl_add_u64 v[108:109], v[108:109], 0, s[88:89]
	s_nop 0
	v_addc_co_u32_e32 v97, vcc, 0, v209, vcc
	global_load_dwordx4 v[96:99], v[96:97], off
	s_waitcnt vmcnt(10)
	v_lshlrev_b32_e32 v207, 16, v156
	global_load_dwordx4 v[108:111], v[108:109], off
	v_and_b32_e32 v211, 0xffff0000, v156
	v_lshlrev_b32_e32 v213, 16, v157
	v_and_b32_e32 v215, 0xffff0000, v157
	v_lshlrev_b32_e32 v217, 16, v158
	v_and_b32_e32 v251, 0xffff0000, v158
	v_lshlrev_b32_e32 v252, 16, v159
	v_and_b32_e32 v234, 0xffff0000, v159
	v_lshlrev_b32_e32 v156, 16, v152
	v_and_b32_e32 v157, 0xffff0000, v152
	v_lshlrev_b32_e32 v158, 16, v153
	v_and_b32_e32 v159, 0xffff0000, v153
	v_rcp_f32_e32 v152, v207
	v_rcp_f32_e32 v153, v211
	v_lshlrev_b32_e32 v230, 16, v154
	v_and_b32_e32 v231, 0xffff0000, v154
	v_lshlrev_b32_e32 v232, 16, v155
	v_and_b32_e32 v233, 0xffff0000, v155
	v_pk_mul_f32 v[154:155], v[152:153], v[156:157]
	s_and_b64 vcc, exec, s[38:39]
	v_cndmask_b32_e64 v153, v155, v153, s[36:37]
	v_cndmask_b32_e64 v152, v154, v152, s[36:37]
	v_pk_mul_f32 v[152:153], v[92:93], v[152:153]
	v_rcp_f32_e32 v92, v213
	v_rcp_f32_e32 v93, v215
	s_nop 0
	v_pk_mul_f32 v[154:155], v[92:93], v[158:159]
	s_nop 0
	v_cndmask_b32_e64 v93, v155, v93, s[36:37]
	v_cndmask_b32_e64 v92, v154, v92, s[36:37]
	v_pk_mul_f32 v[154:155], v[94:95], v[92:93]
	v_rcp_f32_e32 v92, v217
	v_rcp_f32_e32 v93, v251
	s_nop 0
	v_pk_mul_f32 v[94:95], v[92:93], v[230:231]
	s_nop 0
	v_cndmask_b32_e64 v93, v95, v93, s[36:37]
	v_cndmask_b32_e64 v92, v94, v92, s[36:37]
	v_pk_mul_f32 v[156:157], v[88:89], v[92:93]
	v_rcp_f32_e32 v88, v252
	v_rcp_f32_e32 v89, v234
	s_nop 0
	v_pk_mul_f32 v[92:93], v[88:89], v[232:233]
	s_nop 0
	v_cndmask_b32_e64 v89, v93, v89, s[36:37]
	v_cndmask_b32_e64 v88, v92, v88, s[36:37]
	v_pk_mul_f32 v[158:159], v[90:91], v[88:89]
	s_cbranch_vccnz .LBB0_124
	s_lshl_b32 s22, s55, 8
	v_ashrrev_i32_e32 v217, 31, v216
	s_nop 1
	v_lshlrev_b64 v[92:93], 11, v[216:217]
	v_readlane_b32 s6, v253, 18
	v_readlane_b32 s7, v253, 19
	s_ashr_i32 s23, s22, 31
	v_mov_b32_e32 v95, s23
	v_lshl_add_u64 v[92:93], s[6:7], 0, v[92:93]
	v_or_b32_e32 v94, s22, v192
	v_lshl_add_u64 v[92:93], v[94:95], 1, v[92:93]
	v_cvt_pk_bf16_f32 v88, v152, v153
	v_cvt_pk_bf16_f32 v89, v154, v155
	v_cvt_pk_bf16_f32 v90, v156, v157
	v_cvt_pk_bf16_f32 v91, v158, v159
	s_nop 1
	global_store_dwordx4 v[92:93], v[88:91], off offset:256
.LBB0_124:
	v_lshlrev_b32_e32 v207, 16, v140
	v_and_b32_e32 v140, 0xffff0000, v140
	v_lshlrev_b32_e32 v88, 16, v132
	v_and_b32_e32 v89, 0xffff0000, v132
	v_lshlrev_b32_e32 v90, 16, v133
	v_and_b32_e32 v91, 0xffff0000, v133
	v_rcp_f32_e32 v132, v207
	v_rcp_f32_e32 v133, v140
	v_lshlrev_b32_e32 v211, 16, v141
	v_and_b32_e32 v141, 0xffff0000, v141
	v_lshlrev_b32_e32 v213, 16, v142
	v_pk_mul_f32 v[88:89], v[132:133], v[88:89]
	v_and_b32_e32 v142, 0xffff0000, v142
	v_cndmask_b32_e64 v89, v89, v133, s[36:37]
	v_cndmask_b32_e64 v88, v88, v132, s[36:37]
	v_pk_mul_f32 v[132:133], v[84:85], v[88:89]
	v_rcp_f32_e32 v84, v211
	v_rcp_f32_e32 v85, v141
	v_lshlrev_b32_e32 v92, 16, v134
	v_and_b32_e32 v93, 0xffff0000, v134
	v_lshlrev_b32_e32 v94, 16, v135
	v_pk_mul_f32 v[88:89], v[84:85], v[90:91]
	v_and_b32_e32 v95, 0xffff0000, v135
	v_cndmask_b32_e64 v85, v89, v85, s[36:37]
	v_cndmask_b32_e64 v84, v88, v84, s[36:37]
	v_pk_mul_f32 v[134:135], v[86:87], v[84:85]
	v_rcp_f32_e32 v84, v213
	v_rcp_f32_e32 v85, v142
	v_lshlrev_b32_e32 v215, 16, v143
	v_and_b32_e32 v143, 0xffff0000, v143
	s_and_b64 vcc, exec, s[38:39]
	v_pk_mul_f32 v[86:87], v[84:85], v[92:93]
	s_nop 0
	v_cndmask_b32_e64 v85, v87, v85, s[36:37]
	v_cndmask_b32_e64 v84, v86, v84, s[36:37]
	v_pk_mul_f32 v[140:141], v[80:81], v[84:85]
	v_rcp_f32_e32 v80, v215
	v_rcp_f32_e32 v81, v143
	s_nop 0
	v_pk_mul_f32 v[84:85], v[80:81], v[94:95]
	s_nop 0
	v_cndmask_b32_e64 v81, v85, v81, s[36:37]
	v_cndmask_b32_e64 v80, v84, v80, s[36:37]
	v_pk_mul_f32 v[142:143], v[82:83], v[80:81]
	s_cbranch_vccnz .LBB0_126
	s_lshl_b32 s22, s55, 8
	v_ashrrev_i32_e32 v215, 31, v214
	s_nop 1
	v_lshlrev_b64 v[84:85], 11, v[214:215]
	v_readlane_b32 s6, v253, 18
	v_readlane_b32 s7, v253, 19
	s_ashr_i32 s23, s22, 31
	v_mov_b32_e32 v87, s23
	v_lshl_add_u64 v[84:85], s[6:7], 0, v[84:85]
	v_or_b32_e32 v86, s22, v192
	v_lshl_add_u64 v[84:85], v[86:87], 1, v[84:85]
	v_cvt_pk_bf16_f32 v80, v132, v133
	v_cvt_pk_bf16_f32 v81, v134, v135
	v_cvt_pk_bf16_f32 v82, v140, v141
	v_cvt_pk_bf16_f32 v83, v142, v143
	s_nop 1
	global_store_dwordx4 v[84:85], v[80:83], off offset:256
.LBB0_126:
	s_waitcnt vmcnt(10)
	v_lshlrev_b32_e32 v88, 16, v120
	v_and_b32_e32 v89, 0xffff0000, v120
	v_rcp_f32_e32 v88, v88
	v_rcp_f32_e32 v89, v89
	v_lshlrev_b32_e32 v80, 16, v116
	v_and_b32_e32 v81, 0xffff0000, v116
	v_lshlrev_b32_e32 v90, 16, v121
	v_pk_mul_f32 v[80:81], v[88:89], v[80:81]
	v_and_b32_e32 v91, 0xffff0000, v121
	v_cndmask_b32_e64 v81, v81, v89, s[36:37]
	v_cndmask_b32_e64 v80, v80, v88, s[36:37]
	v_lshlrev_b32_e32 v82, 16, v117
	v_and_b32_e32 v83, 0xffff0000, v117
	v_pk_mul_f32 v[116:117], v[76:77], v[80:81]
	v_rcp_f32_e32 v76, v90
	v_rcp_f32_e32 v77, v91
	v_lshlrev_b32_e32 v92, 16, v122
	v_and_b32_e32 v93, 0xffff0000, v122
	v_lshlrev_b32_e32 v84, 16, v118
	v_pk_mul_f32 v[80:81], v[76:77], v[82:83]
	v_and_b32_e32 v85, 0xffff0000, v118
	v_cndmask_b32_e64 v77, v81, v77, s[36:37]
	v_cndmask_b32_e64 v76, v80, v76, s[36:37]
	v_lshlrev_b32_e32 v86, 16, v119
	v_and_b32_e32 v87, 0xffff0000, v119
	v_pk_mul_f32 v[118:119], v[78:79], v[76:77]
	v_rcp_f32_e32 v76, v92
	v_rcp_f32_e32 v77, v93
	v_lshlrev_b32_e32 v94, 16, v123
	v_and_b32_e32 v95, 0xffff0000, v123
	s_and_b64 vcc, exec, s[38:39]
	v_pk_mul_f32 v[78:79], v[76:77], v[84:85]
	s_nop 0
	v_cndmask_b32_e64 v77, v79, v77, s[36:37]
	v_cndmask_b32_e64 v76, v78, v76, s[36:37]
	v_pk_mul_f32 v[120:121], v[72:73], v[76:77]
	v_rcp_f32_e32 v72, v94
	v_rcp_f32_e32 v73, v95
	s_nop 0
	v_pk_mul_f32 v[76:77], v[72:73], v[86:87]
	s_nop 0
	v_cndmask_b32_e64 v73, v77, v73, s[36:37]
	v_cndmask_b32_e64 v72, v76, v72, s[36:37]
	v_pk_mul_f32 v[122:123], v[74:75], v[72:73]
	s_cbranch_vccnz .LBB0_128
	s_lshl_b32 s22, s55, 8
	v_ashrrev_i32_e32 v213, 31, v212
	s_nop 1
	v_lshlrev_b64 v[76:77], 11, v[212:213]
	v_readlane_b32 s6, v253, 18
	v_readlane_b32 s7, v253, 19
	s_ashr_i32 s23, s22, 31
	v_mov_b32_e32 v79, s23
	v_lshl_add_u64 v[76:77], s[6:7], 0, v[76:77]
	v_or_b32_e32 v78, s22, v192
	v_lshl_add_u64 v[76:77], v[78:79], 1, v[76:77]
	v_cvt_pk_bf16_f32 v72, v116, v117
	v_cvt_pk_bf16_f32 v73, v118, v119
	v_cvt_pk_bf16_f32 v74, v120, v121
	v_cvt_pk_bf16_f32 v75, v122, v123
	s_nop 1
	global_store_dwordx4 v[76:77], v[72:75], off offset:256
.LBB0_128:
	s_waitcnt vmcnt(8)
	v_lshlrev_b32_e32 v80, 16, v104
	v_and_b32_e32 v81, 0xffff0000, v104
	v_rcp_f32_e32 v80, v80
	v_rcp_f32_e32 v81, v81
	v_lshlrev_b32_e32 v72, 16, v100
	v_and_b32_e32 v73, 0xffff0000, v100
	v_lshlrev_b32_e32 v82, 16, v105
	v_pk_mul_f32 v[72:73], v[80:81], v[72:73]
	v_and_b32_e32 v83, 0xffff0000, v105
	v_cndmask_b32_e64 v73, v73, v81, s[36:37]
	v_cndmask_b32_e64 v72, v72, v80, s[36:37]
	v_lshlrev_b32_e32 v74, 16, v101
	v_and_b32_e32 v75, 0xffff0000, v101
	v_pk_mul_f32 v[100:101], v[68:69], v[72:73]
	v_rcp_f32_e32 v68, v82
	v_rcp_f32_e32 v69, v83
	v_lshlrev_b32_e32 v84, 16, v106
	v_and_b32_e32 v85, 0xffff0000, v106
	v_lshlrev_b32_e32 v76, 16, v102
	v_pk_mul_f32 v[72:73], v[68:69], v[74:75]
	v_and_b32_e32 v77, 0xffff0000, v102
	v_cndmask_b32_e64 v69, v73, v69, s[36:37]
	v_cndmask_b32_e64 v68, v72, v68, s[36:37]
	v_lshlrev_b32_e32 v78, 16, v103
	v_and_b32_e32 v79, 0xffff0000, v103
	v_pk_mul_f32 v[102:103], v[70:71], v[68:69]
	v_rcp_f32_e32 v68, v84
	v_rcp_f32_e32 v69, v85
	v_lshlrev_b32_e32 v86, 16, v107
	v_and_b32_e32 v87, 0xffff0000, v107
	s_and_b64 vcc, exec, s[38:39]
	v_pk_mul_f32 v[70:71], v[68:69], v[76:77]
	s_nop 0
	v_cndmask_b32_e64 v69, v71, v69, s[36:37]
	v_cndmask_b32_e64 v68, v70, v68, s[36:37]
	v_pk_mul_f32 v[104:105], v[64:65], v[68:69]
	v_rcp_f32_e32 v64, v86
	v_rcp_f32_e32 v65, v87
	s_nop 0
	v_pk_mul_f32 v[68:69], v[64:65], v[78:79]
	s_nop 0
	v_cndmask_b32_e64 v65, v69, v65, s[36:37]
	v_cndmask_b32_e64 v64, v68, v64, s[36:37]
	v_pk_mul_f32 v[106:107], v[66:67], v[64:65]
	s_cbranch_vccnz .LBB0_130
	s_lshl_b32 s22, s55, 8
	v_ashrrev_i32_e32 v211, 31, v210
	s_nop 1
	v_lshlrev_b64 v[68:69], 11, v[210:211]
	v_readlane_b32 s6, v253, 18
	v_readlane_b32 s7, v253, 19
	s_ashr_i32 s23, s22, 31
	v_mov_b32_e32 v71, s23
	v_lshl_add_u64 v[68:69], s[6:7], 0, v[68:69]
	v_or_b32_e32 v70, s22, v192
	v_lshl_add_u64 v[68:69], v[70:71], 1, v[68:69]
	v_cvt_pk_bf16_f32 v64, v100, v101
	v_cvt_pk_bf16_f32 v65, v102, v103
	v_cvt_pk_bf16_f32 v66, v104, v105
	v_cvt_pk_bf16_f32 v67, v106, v107
	s_nop 1
	global_store_dwordx4 v[68:69], v[64:67], off offset:256
.LBB0_130:
	s_mov_b64 s[22:23], 0x101000
	s_nop 0
	v_lshl_add_u64 v[64:65], v[208:209], 0, s[22:23]
	v_add_co_u32_e32 v66, vcc, 0x101000, v208
	v_lshl_add_u64 v[64:65], v[64:65], 0, s[88:89]
	s_nop 0
	v_addc_co_u32_e32 v67, vcc, 0, v209, vcc
	s_mov_b64 s[22:23], 0x121000
	global_load_dwordx4 v[88:91], v[66:67], off
	global_load_dwordx4 v[92:95], v[64:65], off
	v_lshl_add_u64 v[64:65], v[208:209], 0, s[22:23]
	v_add_co_u32_e32 v66, vcc, 0x121000, v208
	v_lshl_add_u64 v[64:65], v[64:65], 0, s[88:89]
	s_nop 0
	v_addc_co_u32_e32 v67, vcc, 0, v209, vcc
	s_mov_b64 s[22:23], 0x141000
	global_load_dwordx4 v[80:83], v[66:67], off
	global_load_dwordx4 v[84:87], v[64:65], off
	v_lshl_add_u64 v[64:65], v[208:209], 0, s[22:23]
	v_add_co_u32_e32 v66, vcc, 0x141000, v208
	v_lshl_add_u64 v[64:65], v[64:65], 0, s[88:89]
	s_nop 0
	v_addc_co_u32_e32 v67, vcc, 0, v209, vcc
	s_mov_b64 s[22:23], 0x161000
	global_load_dwordx4 v[72:75], v[66:67], off
	global_load_dwordx4 v[76:79], v[64:65], off
	v_lshl_add_u64 v[68:69], v[208:209], 0, s[22:23]
	v_add_co_u32_e32 v64, vcc, 0x161000, v208
	v_lshl_add_u64 v[68:69], v[68:69], 0, s[88:89]
	s_nop 0
	v_addc_co_u32_e32 v65, vcc, 0, v209, vcc
	global_load_dwordx4 v[64:67], v[64:65], off
	s_waitcnt vmcnt(13)
	v_lshlrev_b32_e32 v207, 16, v144
	global_load_dwordx4 v[68:71], v[68:69], off
	v_and_b32_e32 v209, 0xffff0000, v144
	v_rcp_f32_e32 v208, v207
	v_rcp_f32_e32 v209, v209
	v_lshlrev_b32_e32 v210, 16, v145
	v_and_b32_e32 v211, 0xffff0000, v145
	v_lshlrev_b32_e32 v144, 16, v148
	v_and_b32_e32 v145, 0xffff0000, v148
	v_pk_mul_f32 v[144:145], v[208:209], v[144:145]
	v_lshlrev_b32_e32 v212, 16, v146
	v_cndmask_b32_e64 v145, v145, v209, s[36:37]
	v_cndmask_b32_e64 v144, v144, v208, s[36:37]
	v_pk_mul_f32 v[60:61], v[60:61], v[144:145]
	v_rcp_f32_e32 v144, v210
	v_rcp_f32_e32 v145, v211
	v_and_b32_e32 v213, 0xffff0000, v146
	v_lshlrev_b32_e32 v214, 16, v147
	v_and_b32_e32 v215, 0xffff0000, v147
	v_lshlrev_b32_e32 v146, 16, v149
	v_and_b32_e32 v147, 0xffff0000, v149
	v_pk_mul_f32 v[146:147], v[144:145], v[146:147]
	v_lshlrev_b32_e32 v148, 16, v150
	v_cndmask_b32_e64 v145, v147, v145, s[36:37]
	v_cndmask_b32_e64 v144, v146, v144, s[36:37]
	v_pk_mul_f32 v[62:63], v[62:63], v[144:145]
	v_rcp_f32_e32 v144, v212
	v_rcp_f32_e32 v145, v213
	v_and_b32_e32 v149, 0xffff0000, v150
	v_lshlrev_b32_e32 v150, 16, v151
	v_and_b32_e32 v151, 0xffff0000, v151
	v_pk_mul_f32 v[146:147], v[144:145], v[148:149]
	s_and_b64 vcc, exec, s[38:39]
	v_cndmask_b32_e64 v145, v147, v145, s[36:37]
	v_cndmask_b32_e64 v144, v146, v144, s[36:37]
	v_pk_mul_f32 v[56:57], v[56:57], v[144:145]
	v_rcp_f32_e32 v144, v214
	v_rcp_f32_e32 v145, v215
	s_nop 0
	v_pk_mul_f32 v[146:147], v[144:145], v[150:151]
	s_nop 0
	v_cndmask_b32_e64 v145, v147, v145, s[36:37]
	v_cndmask_b32_e64 v144, v146, v144, s[36:37]
	v_pk_mul_f32 v[58:59], v[58:59], v[144:145]
	v_lshl_add_u32 v144, s52, 8, v247
	s_cbranch_vccnz .LBB0_132
	v_ashrrev_i32_e32 v145, 31, v144
	s_nop 1
	v_lshlrev_b64 v[150:151], 11, v[144:145]
	v_readlane_b32 s6, v253, 18
	v_readlane_b32 s7, v253, 19
	v_ashrrev_i32_e32 v207, 31, v206
	v_cvt_pk_bf16_f32 v146, v60, v61
	v_cvt_pk_bf16_f32 v147, v62, v63
	v_cvt_pk_bf16_f32 v148, v56, v57
	v_cvt_pk_bf16_f32 v149, v58, v59
	s_nop 0
	v_lshl_add_u64 v[150:151], s[6:7], 0, v[150:151]
	v_lshl_add_u64 v[150:151], v[206:207], 1, v[150:151]
	s_nop 1
	global_store_dwordx4 v[150:151], v[146:149], off
.LBB0_132:
	s_waitcnt vmcnt(12)
	v_lshlrev_b32_e32 v145, 16, v128
	s_nop 0
	v_and_b32_e32 v147, 0xffff0000, v128
	v_rcp_f32_e32 v146, v145
	v_rcp_f32_e32 v147, v147
	v_lshlrev_b32_e32 v148, 16, v129
	v_and_b32_e32 v149, 0xffff0000, v129
	v_lshlrev_b32_e32 v128, 16, v136
	v_and_b32_e32 v129, 0xffff0000, v136
	v_pk_mul_f32 v[128:129], v[146:147], v[128:129]
	v_lshlrev_b32_e32 v150, 16, v130
	v_cndmask_b32_e64 v129, v129, v147, s[36:37]
	v_cndmask_b32_e64 v128, v128, v146, s[36:37]
	v_pk_mul_f32 v[52:53], v[52:53], v[128:129]
	v_rcp_f32_e32 v128, v148
	v_rcp_f32_e32 v129, v149
	v_and_b32_e32 v151, 0xffff0000, v130
	v_lshlrev_b32_e32 v207, 16, v131
	v_and_b32_e32 v208, 0xffff0000, v131
	v_lshlrev_b32_e32 v130, 16, v137
	v_and_b32_e32 v131, 0xffff0000, v137
	v_pk_mul_f32 v[130:131], v[128:129], v[130:131]
	v_lshlrev_b32_e32 v136, 16, v138
	v_cndmask_b32_e64 v129, v131, v129, s[36:37]
	v_cndmask_b32_e64 v128, v130, v128, s[36:37]
	v_pk_mul_f32 v[54:55], v[54:55], v[128:129]
	v_rcp_f32_e32 v128, v150
	v_rcp_f32_e32 v129, v151
	v_and_b32_e32 v137, 0xffff0000, v138
	v_lshlrev_b32_e32 v138, 16, v139
	v_and_b32_e32 v139, 0xffff0000, v139
	v_pk_mul_f32 v[130:131], v[128:129], v[136:137]
	s_and_b64 vcc, exec, s[38:39]
	v_cndmask_b32_e64 v129, v131, v129, s[36:37]
	v_cndmask_b32_e64 v128, v130, v128, s[36:37]
	v_pk_mul_f32 v[48:49], v[48:49], v[128:129]
	v_rcp_f32_e32 v128, v207
	v_rcp_f32_e32 v129, v208
	s_nop 0
	v_pk_mul_f32 v[130:131], v[128:129], v[138:139]
	s_nop 0
	v_cndmask_b32_e64 v129, v131, v129, s[36:37]
	v_cndmask_b32_e64 v128, v130, v128, s[36:37]
	v_pk_mul_f32 v[50:51], v[50:51], v[128:129]
	v_lshl_add_u32 v128, s52, 8, v248
	s_cbranch_vccnz .LBB0_134
	v_ashrrev_i32_e32 v129, 31, v128
	s_nop 1
	v_lshlrev_b64 v[130:131], 11, v[128:129]
	v_readlane_b32 s6, v253, 18
	v_readlane_b32 s7, v253, 19
	v_ashrrev_i32_e32 v207, 31, v206
	v_cvt_pk_bf16_f32 v136, v52, v53
	v_cvt_pk_bf16_f32 v137, v54, v55
	v_cvt_pk_bf16_f32 v138, v48, v49
	v_cvt_pk_bf16_f32 v139, v50, v51
	s_nop 0
	v_lshl_add_u64 v[130:131], s[6:7], 0, v[130:131]
	v_lshl_add_u64 v[130:131], v[206:207], 1, v[130:131]
	s_nop 1
	global_store_dwordx4 v[130:131], v[136:139], off
.LBB0_134:
	s_waitcnt vmcnt(10)
	v_lshlrev_b32_e32 v129, 16, v112
	v_and_b32_e32 v131, 0xffff0000, v112
	v_rcp_f32_e32 v130, v129
	v_rcp_f32_e32 v131, v131
	v_lshlrev_b32_e32 v136, 16, v113
	v_and_b32_e32 v137, 0xffff0000, v113
	v_lshlrev_b32_e32 v112, 16, v124
	v_and_b32_e32 v113, 0xffff0000, v124
	v_pk_mul_f32 v[112:113], v[130:131], v[112:113]
	v_lshlrev_b32_e32 v138, 16, v114
	v_cndmask_b32_e64 v113, v113, v131, s[36:37]
	v_cndmask_b32_e64 v112, v112, v130, s[36:37]
	v_pk_mul_f32 v[44:45], v[44:45], v[112:113]
	v_rcp_f32_e32 v112, v136
	v_rcp_f32_e32 v113, v137
	v_and_b32_e32 v139, 0xffff0000, v114
	v_lshlrev_b32_e32 v145, 16, v115
	v_and_b32_e32 v146, 0xffff0000, v115
	v_lshlrev_b32_e32 v114, 16, v125
	v_and_b32_e32 v115, 0xffff0000, v125
	v_pk_mul_f32 v[114:115], v[112:113], v[114:115]
	v_lshlrev_b32_e32 v124, 16, v126
	v_cndmask_b32_e64 v113, v115, v113, s[36:37]
	v_cndmask_b32_e64 v112, v114, v112, s[36:37]
	v_pk_mul_f32 v[46:47], v[46:47], v[112:113]
	v_rcp_f32_e32 v112, v138
	v_rcp_f32_e32 v113, v139
	v_and_b32_e32 v125, 0xffff0000, v126
	v_lshlrev_b32_e32 v126, 16, v127
	v_and_b32_e32 v127, 0xffff0000, v127
	v_pk_mul_f32 v[114:115], v[112:113], v[124:125]
	s_and_b64 vcc, exec, s[38:39]
	v_cndmask_b32_e64 v113, v115, v113, s[36:37]
	v_cndmask_b32_e64 v112, v114, v112, s[36:37]
	v_pk_mul_f32 v[40:41], v[40:41], v[112:113]
	v_rcp_f32_e32 v112, v145
	v_rcp_f32_e32 v113, v146
	s_nop 0
	v_pk_mul_f32 v[114:115], v[112:113], v[126:127]
	s_nop 0
	v_cndmask_b32_e64 v113, v115, v113, s[36:37]
	v_cndmask_b32_e64 v112, v114, v112, s[36:37]
	v_pk_mul_f32 v[42:43], v[42:43], v[112:113]
	v_lshl_add_u32 v112, s52, 8, v249
	s_cbranch_vccnz .LBB0_136
	v_ashrrev_i32_e32 v113, 31, v112
	s_nop 1
	v_lshlrev_b64 v[114:115], 11, v[112:113]
	v_readlane_b32 s6, v253, 18
	v_readlane_b32 s7, v253, 19
	v_ashrrev_i32_e32 v207, 31, v206
	v_cvt_pk_bf16_f32 v124, v44, v45
	v_cvt_pk_bf16_f32 v125, v46, v47
	v_cvt_pk_bf16_f32 v126, v40, v41
	v_cvt_pk_bf16_f32 v127, v42, v43
	s_nop 0
	v_lshl_add_u64 v[114:115], s[6:7], 0, v[114:115]
	v_lshl_add_u64 v[114:115], v[206:207], 1, v[114:115]
	s_nop 1
	global_store_dwordx4 v[114:115], v[124:127], off
.LBB0_136:
	s_waitcnt vmcnt(8)
	v_lshlrev_b32_e32 v113, 16, v96
	v_and_b32_e32 v115, 0xffff0000, v96
	v_rcp_f32_e32 v114, v113
	v_rcp_f32_e32 v115, v115
	v_lshlrev_b32_e32 v124, 16, v97
	v_and_b32_e32 v125, 0xffff0000, v97
	v_lshlrev_b32_e32 v96, 16, v108
	v_and_b32_e32 v97, 0xffff0000, v108
	v_pk_mul_f32 v[96:97], v[114:115], v[96:97]
	v_lshlrev_b32_e32 v126, 16, v98
	v_cndmask_b32_e64 v97, v97, v115, s[36:37]
	v_cndmask_b32_e64 v96, v96, v114, s[36:37]
	v_pk_mul_f32 v[36:37], v[36:37], v[96:97]
	v_rcp_f32_e32 v96, v124
	v_rcp_f32_e32 v97, v125
	v_and_b32_e32 v127, 0xffff0000, v98
	v_lshlrev_b32_e32 v129, 16, v99
	v_and_b32_e32 v130, 0xffff0000, v99
	v_lshlrev_b32_e32 v98, 16, v109
	v_and_b32_e32 v99, 0xffff0000, v109
	v_pk_mul_f32 v[98:99], v[96:97], v[98:99]
	v_lshlrev_b32_e32 v108, 16, v110
	v_cndmask_b32_e64 v97, v99, v97, s[36:37]
	v_cndmask_b32_e64 v96, v98, v96, s[36:37]
	v_pk_mul_f32 v[38:39], v[38:39], v[96:97]
	v_rcp_f32_e32 v96, v126
	v_rcp_f32_e32 v97, v127
	v_and_b32_e32 v109, 0xffff0000, v110
	v_lshlrev_b32_e32 v110, 16, v111
	v_and_b32_e32 v111, 0xffff0000, v111
	v_pk_mul_f32 v[98:99], v[96:97], v[108:109]
	s_and_b64 vcc, exec, s[38:39]
	v_cndmask_b32_e64 v97, v99, v97, s[36:37]
	v_cndmask_b32_e64 v96, v98, v96, s[36:37]
	v_pk_mul_f32 v[32:33], v[32:33], v[96:97]
	v_rcp_f32_e32 v96, v129
	v_rcp_f32_e32 v97, v130
	s_nop 0
	v_pk_mul_f32 v[98:99], v[96:97], v[110:111]
	s_nop 0
	v_cndmask_b32_e64 v97, v99, v97, s[36:37]
	v_cndmask_b32_e64 v96, v98, v96, s[36:37]
	v_pk_mul_f32 v[34:35], v[34:35], v[96:97]
	v_lshl_add_u32 v96, s52, 8, v250
	s_cbranch_vccnz .LBB0_138
	v_ashrrev_i32_e32 v97, 31, v96
	s_nop 1
	v_lshlrev_b64 v[98:99], 11, v[96:97]
	v_readlane_b32 s6, v253, 18
	v_readlane_b32 s7, v253, 19
	v_ashrrev_i32_e32 v207, 31, v206
	v_cvt_pk_bf16_f32 v108, v36, v37
	v_cvt_pk_bf16_f32 v109, v38, v39
	v_cvt_pk_bf16_f32 v110, v32, v33
	v_cvt_pk_bf16_f32 v111, v34, v35
	s_nop 0
	v_lshl_add_u64 v[98:99], s[6:7], 0, v[98:99]
	v_lshl_add_u64 v[98:99], v[206:207], 1, v[98:99]
	s_nop 1
	global_store_dwordx4 v[98:99], v[108:111], off
.LBB0_138:
	s_waitcnt vmcnt(6)
	v_lshlrev_b32_e32 v97, 16, v88
	v_and_b32_e32 v99, 0xffff0000, v88
	v_rcp_f32_e32 v98, v97
	v_rcp_f32_e32 v99, v99
	v_lshlrev_b32_e32 v108, 16, v89
	v_and_b32_e32 v109, 0xffff0000, v89
	v_lshlrev_b32_e32 v88, 16, v92
	v_and_b32_e32 v89, 0xffff0000, v92
	v_pk_mul_f32 v[88:89], v[98:99], v[88:89]
	v_lshlrev_b32_e32 v110, 16, v90
	v_cndmask_b32_e64 v89, v89, v99, s[36:37]
	v_cndmask_b32_e64 v88, v88, v98, s[36:37]
	v_pk_mul_f32 v[28:29], v[28:29], v[88:89]
	v_rcp_f32_e32 v88, v108
	v_rcp_f32_e32 v89, v109
	v_and_b32_e32 v111, 0xffff0000, v90
	v_lshlrev_b32_e32 v113, 16, v91
	v_and_b32_e32 v114, 0xffff0000, v91
	v_lshlrev_b32_e32 v90, 16, v93
	v_and_b32_e32 v91, 0xffff0000, v93
	v_pk_mul_f32 v[90:91], v[88:89], v[90:91]
	v_lshlrev_b32_e32 v92, 16, v94
	v_cndmask_b32_e64 v89, v91, v89, s[36:37]
	v_cndmask_b32_e64 v88, v90, v88, s[36:37]
	v_pk_mul_f32 v[30:31], v[30:31], v[88:89]
	v_rcp_f32_e32 v88, v110
	v_rcp_f32_e32 v89, v111
	v_and_b32_e32 v93, 0xffff0000, v94
	v_lshlrev_b32_e32 v94, 16, v95
	v_and_b32_e32 v95, 0xffff0000, v95
	v_pk_mul_f32 v[90:91], v[88:89], v[92:93]
	s_and_b64 vcc, exec, s[38:39]
	v_cndmask_b32_e64 v89, v91, v89, s[36:37]
	v_cndmask_b32_e64 v88, v90, v88, s[36:37]
	v_pk_mul_f32 v[24:25], v[24:25], v[88:89]
	v_rcp_f32_e32 v88, v113
	v_rcp_f32_e32 v89, v114
	s_nop 0
	v_pk_mul_f32 v[90:91], v[88:89], v[94:95]
	s_nop 0
	v_cndmask_b32_e64 v89, v91, v89, s[36:37]
	v_cndmask_b32_e64 v88, v90, v88, s[36:37]
	v_pk_mul_f32 v[26:27], v[26:27], v[88:89]
	s_cbranch_vccnz .LBB0_140
	s_lshl_b32 s22, s55, 8
	v_ashrrev_i32_e32 v145, 31, v144
	s_nop 1
	v_lshlrev_b64 v[92:93], 11, v[144:145]
	v_readlane_b32 s6, v253, 18
	v_readlane_b32 s7, v253, 19
	s_ashr_i32 s23, s22, 31
	v_mov_b32_e32 v95, s23
	v_lshl_add_u64 v[92:93], s[6:7], 0, v[92:93]
	v_or_b32_e32 v94, s22, v192
	v_lshl_add_u64 v[92:93], v[94:95], 1, v[92:93]
	v_cvt_pk_bf16_f32 v88, v28, v29
	v_cvt_pk_bf16_f32 v89, v30, v31
	v_cvt_pk_bf16_f32 v90, v24, v25
	v_cvt_pk_bf16_f32 v91, v26, v27
	s_nop 1
	global_store_dwordx4 v[92:93], v[88:91], off offset:256
.LBB0_140:
	s_waitcnt vmcnt(4)
	s_nop 1
	v_lshlrev_b32_e32 v88, 16, v80
	v_and_b32_e32 v89, 0xffff0000, v80
	v_rcp_f32_e32 v88, v88
	v_rcp_f32_e32 v89, v89
	v_lshlrev_b32_e32 v90, 16, v81
	v_and_b32_e32 v91, 0xffff0000, v81
	v_lshlrev_b32_e32 v80, 16, v84
	v_and_b32_e32 v81, 0xffff0000, v84
	v_pk_mul_f32 v[80:81], v[88:89], v[80:81]
	v_lshlrev_b32_e32 v92, 16, v82
	v_cndmask_b32_e64 v81, v81, v89, s[36:37]
	v_cndmask_b32_e64 v80, v80, v88, s[36:37]
	v_pk_mul_f32 v[20:21], v[20:21], v[80:81]
	v_rcp_f32_e32 v80, v90
	v_rcp_f32_e32 v81, v91
	v_and_b32_e32 v93, 0xffff0000, v82
	v_lshlrev_b32_e32 v94, 16, v83
	v_and_b32_e32 v95, 0xffff0000, v83
	v_lshlrev_b32_e32 v82, 16, v85
	v_and_b32_e32 v83, 0xffff0000, v85
	v_pk_mul_f32 v[82:83], v[80:81], v[82:83]
	v_lshlrev_b32_e32 v84, 16, v86
	v_cndmask_b32_e64 v81, v83, v81, s[36:37]
	v_cndmask_b32_e64 v80, v82, v80, s[36:37]
	v_pk_mul_f32 v[22:23], v[22:23], v[80:81]
	v_rcp_f32_e32 v80, v92
	v_rcp_f32_e32 v81, v93
	v_and_b32_e32 v85, 0xffff0000, v86
	v_lshlrev_b32_e32 v86, 16, v87
	v_and_b32_e32 v87, 0xffff0000, v87
	v_pk_mul_f32 v[82:83], v[80:81], v[84:85]
	s_and_b64 vcc, exec, s[38:39]
	v_cndmask_b32_e64 v81, v83, v81, s[36:37]
	v_cndmask_b32_e64 v80, v82, v80, s[36:37]
	v_pk_mul_f32 v[16:17], v[16:17], v[80:81]
	v_rcp_f32_e32 v80, v94
	v_rcp_f32_e32 v81, v95
	s_nop 0
	v_pk_mul_f32 v[82:83], v[80:81], v[86:87]
	s_nop 0
	v_cndmask_b32_e64 v81, v83, v81, s[36:37]
	v_cndmask_b32_e64 v80, v82, v80, s[36:37]
	v_pk_mul_f32 v[18:19], v[18:19], v[80:81]
	s_cbranch_vccnz .LBB0_142
	s_lshl_b32 s22, s55, 8
	v_ashrrev_i32_e32 v129, 31, v128
	s_nop 1
	v_lshlrev_b64 v[84:85], 11, v[128:129]
	v_readlane_b32 s6, v253, 18
	v_readlane_b32 s7, v253, 19
	s_ashr_i32 s23, s22, 31
	v_mov_b32_e32 v87, s23
	v_lshl_add_u64 v[84:85], s[6:7], 0, v[84:85]
	v_or_b32_e32 v86, s22, v192
	v_lshl_add_u64 v[84:85], v[86:87], 1, v[84:85]
	v_cvt_pk_bf16_f32 v80, v20, v21
	v_cvt_pk_bf16_f32 v81, v22, v23
	v_cvt_pk_bf16_f32 v82, v16, v17
	v_cvt_pk_bf16_f32 v83, v18, v19
	s_nop 1
	global_store_dwordx4 v[84:85], v[80:83], off offset:256
.LBB0_142:
	s_waitcnt vmcnt(2)
	s_nop 1
	v_lshlrev_b32_e32 v80, 16, v72
	v_and_b32_e32 v81, 0xffff0000, v72
	v_rcp_f32_e32 v80, v80
	v_rcp_f32_e32 v81, v81
	v_lshlrev_b32_e32 v82, 16, v73
	v_and_b32_e32 v83, 0xffff0000, v73
	v_lshlrev_b32_e32 v72, 16, v76
	v_and_b32_e32 v73, 0xffff0000, v76
	v_pk_mul_f32 v[72:73], v[80:81], v[72:73]
	v_lshlrev_b32_e32 v84, 16, v74
	v_cndmask_b32_e64 v73, v73, v81, s[36:37]
	v_cndmask_b32_e64 v72, v72, v80, s[36:37]
	v_pk_mul_f32 v[12:13], v[12:13], v[72:73]
	v_rcp_f32_e32 v72, v82
	v_rcp_f32_e32 v73, v83
	v_and_b32_e32 v85, 0xffff0000, v74
	v_lshlrev_b32_e32 v86, 16, v75
	v_and_b32_e32 v87, 0xffff0000, v75
	v_lshlrev_b32_e32 v74, 16, v77
	v_and_b32_e32 v75, 0xffff0000, v77
	v_pk_mul_f32 v[74:75], v[72:73], v[74:75]
	v_lshlrev_b32_e32 v76, 16, v78
	v_cndmask_b32_e64 v73, v75, v73, s[36:37]
	v_cndmask_b32_e64 v72, v74, v72, s[36:37]
	v_pk_mul_f32 v[14:15], v[14:15], v[72:73]
	v_rcp_f32_e32 v72, v84
	v_rcp_f32_e32 v73, v85
	v_and_b32_e32 v77, 0xffff0000, v78
	v_lshlrev_b32_e32 v78, 16, v79
	v_and_b32_e32 v79, 0xffff0000, v79
	v_pk_mul_f32 v[74:75], v[72:73], v[76:77]
	s_and_b64 vcc, exec, s[38:39]
	v_cndmask_b32_e64 v73, v75, v73, s[36:37]
	v_cndmask_b32_e64 v72, v74, v72, s[36:37]
	v_pk_mul_f32 v[4:5], v[4:5], v[72:73]
	v_rcp_f32_e32 v72, v86
	v_rcp_f32_e32 v73, v87
	s_nop 0
	v_pk_mul_f32 v[74:75], v[72:73], v[78:79]
	s_nop 0
	v_cndmask_b32_e64 v73, v75, v73, s[36:37]
	v_cndmask_b32_e64 v72, v74, v72, s[36:37]
	v_pk_mul_f32 v[6:7], v[6:7], v[72:73]
	s_cbranch_vccnz .LBB0_144
	s_lshl_b32 s22, s55, 8
	v_ashrrev_i32_e32 v113, 31, v112
	s_nop 1
	v_lshlrev_b64 v[76:77], 11, v[112:113]
	v_readlane_b32 s6, v253, 18
	v_readlane_b32 s7, v253, 19
	s_ashr_i32 s23, s22, 31
	v_mov_b32_e32 v79, s23
	v_lshl_add_u64 v[76:77], s[6:7], 0, v[76:77]
	v_or_b32_e32 v78, s22, v192
	v_lshl_add_u64 v[76:77], v[78:79], 1, v[76:77]
	v_cvt_pk_bf16_f32 v72, v12, v13
	v_cvt_pk_bf16_f32 v73, v14, v15
	v_cvt_pk_bf16_f32 v74, v4, v5
	v_cvt_pk_bf16_f32 v75, v6, v7
	s_nop 1
	global_store_dwordx4 v[76:77], v[72:75], off offset:256
.LBB0_144:
	s_waitcnt vmcnt(1)
	s_nop 1
	v_lshlrev_b32_e32 v72, 16, v64
	v_and_b32_e32 v73, 0xffff0000, v64
	v_rcp_f32_e32 v72, v72
	v_rcp_f32_e32 v73, v73
	v_lshlrev_b32_e32 v74, 16, v65
	v_and_b32_e32 v75, 0xffff0000, v65
	s_waitcnt vmcnt(0)
	v_lshlrev_b32_e32 v64, 16, v68
	v_and_b32_e32 v65, 0xffff0000, v68
	v_pk_mul_f32 v[64:65], v[72:73], v[64:65]
	v_lshlrev_b32_e32 v76, 16, v66
	v_cndmask_b32_e64 v65, v65, v73, s[36:37]
	v_cndmask_b32_e64 v64, v64, v72, s[36:37]
	v_pk_mul_f32 v[8:9], v[8:9], v[64:65]
	v_rcp_f32_e32 v64, v74
	v_rcp_f32_e32 v65, v75
	v_and_b32_e32 v77, 0xffff0000, v66
	v_lshlrev_b32_e32 v78, 16, v67
	v_and_b32_e32 v79, 0xffff0000, v67
	v_lshlrev_b32_e32 v66, 16, v69
	v_and_b32_e32 v67, 0xffff0000, v69
	v_pk_mul_f32 v[66:67], v[64:65], v[66:67]
	v_lshlrev_b32_e32 v68, 16, v70
	v_cndmask_b32_e64 v65, v67, v65, s[36:37]
	v_cndmask_b32_e64 v64, v66, v64, s[36:37]
	v_pk_mul_f32 v[10:11], v[10:11], v[64:65]
	v_rcp_f32_e32 v64, v76
	v_rcp_f32_e32 v65, v77
	v_and_b32_e32 v69, 0xffff0000, v70
	v_lshlrev_b32_e32 v70, 16, v71
	v_and_b32_e32 v71, 0xffff0000, v71
	v_pk_mul_f32 v[66:67], v[64:65], v[68:69]
	s_and_b64 vcc, exec, s[38:39]
	v_cndmask_b32_e64 v65, v67, v65, s[36:37]
	v_cndmask_b32_e64 v64, v66, v64, s[36:37]
	v_pk_mul_f32 v[0:1], v[0:1], v[64:65]
	v_rcp_f32_e32 v64, v78
	v_rcp_f32_e32 v65, v79
	s_nop 0
	v_pk_mul_f32 v[66:67], v[64:65], v[70:71]
	s_nop 0
	v_cndmask_b32_e64 v65, v67, v65, s[36:37]
	v_cndmask_b32_e64 v64, v66, v64, s[36:37]
	v_pk_mul_f32 v[2:3], v[2:3], v[64:65]
	s_cbranch_vccnz .LBB0_107
	s_lshl_b32 s22, s55, 8
	v_ashrrev_i32_e32 v97, 31, v96
	s_nop 1
	v_lshlrev_b64 v[68:69], 11, v[96:97]
	v_readlane_b32 s6, v253, 18
	v_readlane_b32 s7, v253, 19
	s_ashr_i32 s23, s22, 31
	v_mov_b32_e32 v71, s23
	v_lshl_add_u64 v[68:69], s[6:7], 0, v[68:69]
	v_or_b32_e32 v70, s22, v192
	v_lshl_add_u64 v[68:69], v[70:71], 1, v[68:69]
	v_cvt_pk_bf16_f32 v64, v8, v9
	v_cvt_pk_bf16_f32 v65, v10, v11
	v_cvt_pk_bf16_f32 v66, v0, v1
	v_cvt_pk_bf16_f32 v67, v2, v3
	s_nop 1
	global_store_dwordx4 v[68:69], v[64:67], off offset:256
	s_branch .LBB0_107
.LBB0_146:
	s_waitcnt vmcnt(0)
	v_readlane_b32 s64, v255, 43
	v_readlane_b32 s65, v255, 44
	s_cmpk_gt_u32 s85, 0xff
	s_mov_b64 s[84:85], s[64:65]
	s_mov_b32 s70, 0xbfb8aa3b
	s_mov_b32 s71, 0x42ce8ed0
	v_mov_b32_e32 v234, v225
	v_mov_b32_e32 v225, v226
	s_nop 1
	s_cbranch_scc1 .LBB0_148
	s_barrier

.LBB0_232:
	v_readlane_b32 s28, v254, 26
	v_mov_b32_e32 v133, v185
	v_readlane_b32 s29, v254, 27
	v_mov_b32_e32 v129, v185
	v_readlane_b32 s22, v254, 22
	v_lshl_add_u64 v[8:9], s[28:29], 0, v[132:133]
	s_add_i32 s46, s38, 0x18000
	v_lshl_add_u64 v[10:11], s[28:29], 0, v[128:129]
	v_mov_b32_e32 v135, v185
	v_readlane_b32 s23, v254, 23
	v_lshl_add_u64 v[8:9], v[8:9], 0, s[24:25]
	s_mov_b32 m0, s46
	s_add_i32 s47, s38, 0x1a000
	v_lshl_add_u64 v[12:13], s[22:23], 0, v[134:135]
	v_mov_b32_e32 v131, v185
	s_waitcnt vmcnt(4)
	s_barrier
	global_load_lds_dwordx4 v[8:9], off
	v_lshl_add_u64 v[8:9], v[10:11], 0, s[24:25]
	s_mov_b32 m0, s47
	s_add_i32 s48, s38, 0x8000
	v_lshl_add_u64 v[14:15], s[22:23], 0, v[130:131]
	global_load_lds_dwordx4 v[8:9], off
	v_lshl_add_u64 v[8:9], v[12:13], 0, s[24:25]
	s_mov_b32 m0, s48
	s_add_i32 s49, s38, 0xa000
	v_readlane_b32 s4, v254, 28
	global_load_lds_dwordx4 v[8:9], off
	v_lshl_add_u64 v[8:9], v[14:15], 0, s[24:25]
	s_mov_b32 m0, s49
	s_add_i32 s50, s38, 0x1c000
	v_readlane_b32 s5, v254, 29
	global_load_lds_dwordx4 v[8:9], off
	s_nop 0
	v_lshl_add_u64 v[8:9], s[4:5], 0, v[132:133]
	s_mov_b32 m0, s50
	s_add_i32 s51, s38, 0x1e000
	global_load_lds_dwordx4 v[8:9], off
	v_lshl_add_u64 v[8:9], s[4:5], 0, v[128:129]
	s_mov_b32 m0, s51
	v_and_b32_e32 v10, 48, v0
	global_load_lds_dwordx4 v[8:9], off
	v_and_b32_e32 v8, 15, v0
	v_lshlrev_b32_e32 v0, 2, v0
	s_and_b32 s0, s0, 3
	v_lshl_or_b32 v7, v8, 6, v10
	s_lshl_b32 s20, s1, 13
	v_and_b32_e32 v0, 32, v0
	v_bitop3_b32 v142, v7, s20, v0 bitop3:0xde
	s_lshl_b32 s20, s0, 12
	v_bitop3_b32 v143, v7, s20, v0 bitop3:0xde
	v_lshlrev_b32_e32 v0, 16, v5
	v_and_b32_e32 v0, 0xfffe0000, v0
	v_lshl_add_u32 v0, v4, 13, v0
	v_and_b32_e32 v4, 1, v5
	v_lshl_or_b32 v0, v4, 6, v0
	v_lshl_add_u32 v136, v6, 1, v0
	v_lshlrev_b32_e32 v0, 16, v1
	s_lshl_b32 s0, s0, 6
	v_and_b32_e32 v0, 0xfffe0000, v0
	s_waitcnt vmcnt(6)
	s_lshl_b32 s52, s1, 2
	s_or_b32 s1, s0, 0x100
	v_lshl_add_u32 v0, v2, 13, v0
	v_and_b32_e32 v1, 1, v1
	v_lshl_or_b32 v0, v1, 6, v0
	s_lshl_b32 s63, s0, 4
	s_lshl_b32 s64, s1, 4
	v_readlane_b32 s0, v254, 18
	s_nop 1
	s_add_i32 s53, s52, 8
	s_or_b32 s54, s52, 1
	s_or_b32 s55, s52, 2
	s_or_b32 s58, s52, 3
	s_add_i32 s59, s52, 9
	s_add_i32 s60, s52, 10
	s_add_i32 s61, s52, 11
	v_mov_b32_e32 v137, v185
	v_lshl_add_u32 v138, v3, 1, v0
	v_mov_b32_e32 v139, v185
	s_mov_b32 s62, 0
	v_lshlrev_b32_e32 v184, 4, v10
	v_lshlrev_b32_e32 v140, 4, v8
	s_mov_b32 s71, s0
	v_readlane_b32 s70, v254, 16
	v_readlane_b32 s56, v254, 17
	v_readlane_b32 s78, v253, 22
	v_readlane_b32 s79, v253, 23
	s_barrier
	s_nop 1
.LBB0_233:
	s_add_i32 s62, s62, 1
	s_waitcnt lgkmcnt(0)
	s_mul_i32 s0, s62, s90
	s_mov_b64 s[26:27], s[22:23]
	s_add_i32 s22, s0, s96
	s_cmpk_lt_i32 s22, 0x100
	s_cselect_b64 s[30:31], -1, 0
	s_cmpk_gt_i32 s22, 0xff
	s_mov_b64 s[34:35], s[28:29]
	s_mov_b32 s20, s69
	s_mov_b32 s29, s68
	s_mov_b32 s28, s65
	s_cselect_b64 s[0:1], -1, 0
	s_and_b32 s68, s22, 3
	s_bfe_u32 s69, s22, 0x30002
	s_ashr_i32 s65, s22, 5
	s_and_b64 s[22:23], s[30:31], exec
	s_cselect_b32 s29, s68, s29
	s_cselect_b32 s28, s65, s28
	s_cselect_b32 s22, s69, s20
	s_lshl_b32 s36, s29, 10
	s_ashr_i32 s23, s22, 31
	s_ashr_i32 s37, s36, 31
	s_nop 1
	s_lshl_b64 s[22:23], s[22:23], 21
	s_lshl_b64 s[36:37], s[36:37], 1
	v_readlane_b32 s16, v253, 12
	v_readlane_b32 s17, v253, 13
	s_add_u32 s20, s16, s22
	s_addc_u32 s23, s17, s23
	s_add_u32 s22, s20, s36
	s_addc_u32 s23, s23, s37
	s_and_b64 vcc, s[30:31], exec
	s_cselect_b32 vcc_lo, s23, s27
	s_cselect_b32 vcc_hi, s22, s26
	s_ashr_i32 s29, s28, 31
	s_lshl_b64 s[28:29], s[28:29], 13
	s_add_u32 s20, s78, s28
	s_addc_u32 s29, s79, s29
	s_add_u32 s28, s20, s36
	s_addc_u32 s29, s29, s37
	s_and_b64 s[30:31], s[30:31], exec
	s_cselect_b32 s33, s29, s35
	s_cselect_b32 s20, s28, s34
	s_add_u32 s30, s26, 0x100080
	s_addc_u32 s31, s27, 0
	s_add_u32 s26, s34, 0x100
	v_mov_b32_e32 v0, 0
	s_addc_u32 s27, s35, 0
	s_mov_b32 s96, -2
	v_mov_b32_e32 v1, v0
	v_mov_b32_e32 v2, v0
	v_mov_b32_e32 v3, v0
	v_mov_b32_e32 v4, v0
	v_mov_b32_e32 v5, v0
	v_mov_b32_e32 v6, v0
	v_mov_b32_e32 v7, v0
	v_mov_b32_e32 v8, v0
	v_mov_b32_e32 v9, v0
	v_mov_b32_e32 v10, v0
	v_mov_b32_e32 v11, v0
	v_mov_b32_e32 v12, v0
	v_mov_b32_e32 v13, v0
	v_mov_b32_e32 v14, v0
	v_mov_b32_e32 v15, v0
	v_mov_b32_e32 v16, v0
	v_mov_b32_e32 v17, v0
	v_mov_b32_e32 v18, v0
	v_mov_b32_e32 v19, v0
	v_mov_b32_e32 v20, v0
	v_mov_b32_e32 v21, v0
	v_mov_b32_e32 v22, v0
	v_mov_b32_e32 v23, v0
	v_mov_b32_e32 v24, v0
	v_mov_b32_e32 v25, v0
	v_mov_b32_e32 v26, v0
	v_mov_b32_e32 v27, v0
	v_mov_b32_e32 v28, v0
	v_mov_b32_e32 v29, v0
	v_mov_b32_e32 v30, v0
	v_mov_b32_e32 v31, v0
	v_mov_b32_e32 v32, v0
	v_mov_b32_e32 v33, v0
	v_mov_b32_e32 v34, v0
	v_mov_b32_e32 v35, v0
	v_mov_b32_e32 v36, v0
	v_mov_b32_e32 v37, v0
	v_mov_b32_e32 v38, v0
	v_mov_b32_e32 v39, v0
	v_mov_b32_e32 v40, v0
	v_mov_b32_e32 v41, v0
	v_mov_b32_e32 v42, v0
	v_mov_b32_e32 v43, v0
	v_mov_b32_e32 v44, v0
	v_mov_b32_e32 v45, v0
	v_mov_b32_e32 v46, v0
	v_mov_b32_e32 v47, v0
	v_mov_b32_e32 v48, v0
	v_mov_b32_e32 v49, v0
	v_mov_b32_e32 v50, v0
	v_mov_b32_e32 v51, v0
	v_mov_b32_e32 v52, v0
	v_mov_b32_e32 v53, v0
	v_mov_b32_e32 v54, v0
	v_mov_b32_e32 v55, v0
	v_mov_b32_e32 v56, v0
	v_mov_b32_e32 v57, v0
	v_mov_b32_e32 v58, v0
	v_mov_b32_e32 v59, v0
	v_mov_b32_e32 v60, v0
	v_mov_b32_e32 v61, v0
	v_mov_b32_e32 v62, v0
	v_mov_b32_e32 v63, v0
	v_mov_b32_e32 v64, v0
	v_mov_b32_e32 v65, v0
	v_mov_b32_e32 v66, v0
	v_mov_b32_e32 v67, v0
	v_mov_b32_e32 v68, v0
	v_mov_b32_e32 v69, v0
	v_mov_b32_e32 v70, v0
	v_mov_b32_e32 v71, v0
	v_mov_b32_e32 v72, v0
	v_mov_b32_e32 v73, v0
	v_mov_b32_e32 v74, v0
	v_mov_b32_e32 v75, v0
	v_mov_b32_e32 v76, v0
	v_mov_b32_e32 v77, v0
	v_mov_b32_e32 v78, v0
	v_mov_b32_e32 v79, v0
	v_mov_b32_e32 v80, v0
	v_mov_b32_e32 v81, v0
	v_mov_b32_e32 v82, v0
	v_mov_b32_e32 v83, v0
	v_mov_b32_e32 v84, v0
	v_mov_b32_e32 v85, v0
	v_mov_b32_e32 v86, v0
	v_mov_b32_e32 v87, v0
	v_mov_b32_e32 v88, v0
	v_mov_b32_e32 v89, v0
	v_mov_b32_e32 v90, v0
	v_mov_b32_e32 v91, v0
	v_mov_b32_e32 v92, v0
	v_mov_b32_e32 v93, v0
	v_mov_b32_e32 v94, v0
	v_mov_b32_e32 v95, v0
	v_mov_b32_e32 v96, v0
	v_mov_b32_e32 v97, v0
	v_mov_b32_e32 v98, v0
	v_mov_b32_e32 v99, v0
	v_mov_b32_e32 v100, v0
	v_mov_b32_e32 v101, v0
	v_mov_b32_e32 v102, v0
	v_mov_b32_e32 v103, v0
	v_mov_b32_e32 v104, v0
	v_mov_b32_e32 v105, v0
	v_mov_b32_e32 v106, v0
	v_mov_b32_e32 v107, v0
	v_mov_b32_e32 v108, v0
	v_mov_b32_e32 v109, v0
	v_mov_b32_e32 v110, v0
	v_mov_b32_e32 v111, v0
	v_mov_b32_e32 v112, v0
	v_mov_b32_e32 v113, v0
	v_mov_b32_e32 v114, v0
	v_mov_b32_e32 v115, v0
	v_mov_b32_e32 v116, v0
	v_mov_b32_e32 v117, v0
	v_mov_b32_e32 v118, v0
	v_mov_b32_e32 v119, v0
	v_mov_b32_e32 v120, v0
	v_mov_b32_e32 v121, v0
	v_mov_b32_e32 v122, v0
	v_mov_b32_e32 v123, v0
	v_mov_b32_e32 v124, v0
	v_mov_b32_e32 v125, v0
	v_mov_b32_e32 v126, v0
	v_mov_b32_e32 v127, v0
	s_nop 1
.LBB0_234:
	v_or_b32_e32 v141, 0x10000, v143
	v_add_u32_e32 v148, 0x10400, v143
	ds_read_b128 v[144:147], v141
	ds_read_b128 v[148:151], v148
	v_add_u32_e32 v141, 0x10800, v143
	v_add_u32_e32 v156, 0x10c00, v143
	ds_read_b128 v[152:155], v141
	ds_read_b128 v[156:159], v156
	s_add_u32 s34, s30, 0xfff00080
	s_addc_u32 s35, s31, -1
	s_cmp_eq_u32 s96, 12
	s_cselect_b32 s37, vcc_lo, s35
	s_cselect_b32 s36, vcc_hi, s34
	s_cselect_b32 s35, s33, s27
	s_cselect_b32 s34, s20, s26
	v_lshl_add_u64 v[190:191], s[30:31], 0, v[136:137]
	s_add_i32 m0, s38, 0xc000
	ds_read_b128 v[160:163], v142
	ds_read_b128 v[164:167], v142 offset:1024
	ds_read_b128 v[168:171], v142 offset:2048
	ds_read_b128 v[172:175], v142 offset:3072
	ds_read_b128 v[176:179], v142 offset:4096
	ds_read_b128 v[180:183], v142 offset:5120
	ds_read_b128 v[186:189], v142 offset:6144
	ds_read_b128 v[194:197], v142 offset:7168
	global_load_lds_dwordx4 v[190:191], off
	v_lshl_add_u64 v[190:191], s[30:31], 0, v[138:139]
	s_add_i32 m0, s38, 0xe000
	s_nop 0
	global_load_lds_dwordx4 v[190:191], off
	s_waitcnt lgkmcnt(8)
	s_barrier
	s_waitcnt lgkmcnt(0)
	s_setprio 1
	s_waitcnt lgkmcnt(0)
	v_mfma_f32_16x16x32_bf16 v[124:127], v[144:147], v[160:163], v[124:127]
	v_mfma_f32_16x16x32_bf16 v[120:123], v[152:155], v[160:163], v[120:123]
	v_mfma_f32_16x16x32_bf16 v[116:119], v[144:147], v[168:171], v[116:119]
	v_mfma_f32_16x16x32_bf16 v[112:115], v[152:155], v[168:171], v[112:115]
	v_mfma_f32_16x16x32_bf16 v[108:111], v[144:147], v[176:179], v[108:111]
	v_mfma_f32_16x16x32_bf16 v[104:107], v[152:155], v[176:179], v[104:107]
	v_mfma_f32_16x16x32_bf16 v[100:103], v[144:147], v[186:189], v[100:103]
	v_mfma_f32_16x16x32_bf16 v[96:99], v[152:155], v[186:189], v[96:99]
	v_mfma_f32_16x16x32_bf16 v[124:127], v[148:151], v[164:167], v[124:127]
	v_mfma_f32_16x16x32_bf16 v[120:123], v[156:159], v[164:167], v[120:123]
	v_mfma_f32_16x16x32_bf16 v[116:119], v[148:151], v[172:175], v[116:119]
	v_mfma_f32_16x16x32_bf16 v[112:115], v[156:159], v[172:175], v[112:115]
	v_mfma_f32_16x16x32_bf16 v[108:111], v[148:151], v[180:183], v[108:111]
	v_mfma_f32_16x16x32_bf16 v[104:107], v[156:159], v[180:183], v[104:107]
	v_mfma_f32_16x16x32_bf16 v[100:103], v[148:151], v[194:197], v[100:103]
	v_mfma_f32_16x16x32_bf16 v[96:99], v[156:159], v[194:197], v[96:99]
	s_setprio 0
	s_barrier
	v_or_b32_e32 v141, 0x14000, v143
	v_add_u32_e32 v190, 0x14400, v143
	ds_read_b128 v[198:201], v141
	ds_read_b128 v[202:205], v190
	v_add_u32_e32 v141, 0x14800, v143
	v_add_u32_e32 v190, 0x14c00, v143
	s_mov_b32 m0, s39
	ds_read_b128 v[206:209], v141
	ds_read_b128 v[210:213], v190
	v_lshl_add_u64 v[190:191], s[34:35], 0, v[132:133]
	global_load_lds_dwordx4 v[190:191], off
	v_lshl_add_u64 v[214:215], s[34:35], 0, v[128:129]
	s_mov_b32 m0, s40
	s_nop 0
	global_load_lds_dwordx4 v[214:215], off
	s_barrier
	s_waitcnt lgkmcnt(0)
	s_setprio 1
	s_waitcnt lgkmcnt(0)
	v_mfma_f32_16x16x32_bf16 v[92:95], v[198:201], v[160:163], v[92:95]
	v_mfma_f32_16x16x32_bf16 v[88:91], v[206:209], v[160:163], v[88:91]
	v_mfma_f32_16x16x32_bf16 v[84:87], v[198:201], v[168:171], v[84:87]
	v_mfma_f32_16x16x32_bf16 v[80:83], v[206:209], v[168:171], v[80:83]
	v_mfma_f32_16x16x32_bf16 v[76:79], v[198:201], v[176:179], v[76:79]
	v_mfma_f32_16x16x32_bf16 v[72:75], v[206:209], v[176:179], v[72:75]
	v_mfma_f32_16x16x32_bf16 v[68:71], v[198:201], v[186:189], v[68:71]
	v_mfma_f32_16x16x32_bf16 v[64:67], v[206:209], v[186:189], v[64:67]
	v_mfma_f32_16x16x32_bf16 v[92:95], v[202:205], v[164:167], v[92:95]
	v_mfma_f32_16x16x32_bf16 v[88:91], v[210:213], v[164:167], v[88:91]
	v_mfma_f32_16x16x32_bf16 v[84:87], v[202:205], v[172:175], v[84:87]
	v_mfma_f32_16x16x32_bf16 v[80:83], v[210:213], v[172:175], v[80:83]
	v_mfma_f32_16x16x32_bf16 v[76:79], v[202:205], v[180:183], v[76:79]
	v_mfma_f32_16x16x32_bf16 v[72:75], v[210:213], v[180:183], v[72:75]
	v_mfma_f32_16x16x32_bf16 v[68:71], v[202:205], v[194:197], v[68:71]
	v_mfma_f32_16x16x32_bf16 v[64:67], v[210:213], v[194:197], v[64:67]
	s_setprio 0
	s_mov_b32 m0, s38
	v_lshl_add_u64 v[216:217], s[36:37], 0, v[134:135]
	s_barrier
	ds_read_b128 v[160:163], v142 offset:16384
	ds_read_b128 v[164:167], v142 offset:17408
	ds_read_b128 v[168:171], v142 offset:18432
	ds_read_b128 v[172:175], v142 offset:19456
	ds_read_b128 v[176:179], v142 offset:20480
	ds_read_b128 v[180:183], v142 offset:21504
	ds_read_b128 v[186:189], v142 offset:22528
	ds_read_b128 v[194:197], v142 offset:23552
	global_load_lds_dwordx4 v[216:217], off
	v_lshl_add_u64 v[242:243], s[36:37], 0, v[130:131]
	s_mov_b32 m0, s41
	s_nop 0
	global_load_lds_dwordx4 v[242:243], off
	s_barrier
	s_waitcnt lgkmcnt(0)
	s_setprio 1
	s_waitcnt lgkmcnt(0)
	v_mfma_f32_16x16x32_bf16 v[60:63], v[144:147], v[160:163], v[60:63]
	v_mfma_f32_16x16x32_bf16 v[56:59], v[152:155], v[160:163], v[56:59]
	v_mfma_f32_16x16x32_bf16 v[52:55], v[144:147], v[168:171], v[52:55]
	v_mfma_f32_16x16x32_bf16 v[48:51], v[152:155], v[168:171], v[48:51]
	v_mfma_f32_16x16x32_bf16 v[44:47], v[144:147], v[176:179], v[44:47]
	v_mfma_f32_16x16x32_bf16 v[40:43], v[152:155], v[176:179], v[40:43]
	v_mfma_f32_16x16x32_bf16 v[36:39], v[144:147], v[186:189], v[36:39]
	v_mfma_f32_16x16x32_bf16 v[32:35], v[152:155], v[186:189], v[32:35]
	v_mfma_f32_16x16x32_bf16 v[60:63], v[148:151], v[164:167], v[60:63]
	v_mfma_f32_16x16x32_bf16 v[56:59], v[156:159], v[164:167], v[56:59]
	v_mfma_f32_16x16x32_bf16 v[52:55], v[148:151], v[172:175], v[52:55]
	v_mfma_f32_16x16x32_bf16 v[48:51], v[156:159], v[172:175], v[48:51]
	v_mfma_f32_16x16x32_bf16 v[44:47], v[148:151], v[180:183], v[44:47]
	v_mfma_f32_16x16x32_bf16 v[40:43], v[156:159], v[180:183], v[40:43]
	v_mfma_f32_16x16x32_bf16 v[36:39], v[148:151], v[194:197], v[36:39]
	v_mfma_f32_16x16x32_bf16 v[32:35], v[156:159], v[194:197], v[32:35]
	s_setprio 0
	s_barrier
	s_add_u32 s66, s34, 0x800000
	s_addc_u32 s67, s35, 0
	s_mov_b32 m0, s42
	v_lshl_add_u64 v[144:145], s[66:67], 0, v[132:133]
	global_load_lds_dwordx4 v[144:145], off
	v_lshl_add_u64 v[144:145], s[66:67], 0, v[128:129]
	s_mov_b32 m0, s43
	s_nop 0
	global_load_lds_dwordx4 v[144:145], off
	s_waitcnt vmcnt(6)
	s_barrier
	s_setprio 1
	v_mfma_f32_16x16x32_bf16 v[28:31], v[198:201], v[160:163], v[28:31]
	v_mfma_f32_16x16x32_bf16 v[24:27], v[206:209], v[160:163], v[24:27]
	v_mfma_f32_16x16x32_bf16 v[20:23], v[198:201], v[168:171], v[20:23]
	v_mfma_f32_16x16x32_bf16 v[16:19], v[206:209], v[168:171], v[16:19]
	v_mfma_f32_16x16x32_bf16 v[12:15], v[198:201], v[176:179], v[12:15]
	v_mfma_f32_16x16x32_bf16 v[8:11], v[206:209], v[176:179], v[8:11]
	v_mfma_f32_16x16x32_bf16 v[4:7], v[198:201], v[186:189], v[4:7]
	v_mfma_f32_16x16x32_bf16 v[0:3], v[206:209], v[186:189], v[0:3]
	v_mfma_f32_16x16x32_bf16 v[28:31], v[202:205], v[164:167], v[28:31]
	v_mfma_f32_16x16x32_bf16 v[24:27], v[210:213], v[164:167], v[24:27]
	v_mfma_f32_16x16x32_bf16 v[20:23], v[202:205], v[172:175], v[20:23]
	v_mfma_f32_16x16x32_bf16 v[16:19], v[210:213], v[172:175], v[16:19]
	v_mfma_f32_16x16x32_bf16 v[12:15], v[202:205], v[180:183], v[12:15]
	v_mfma_f32_16x16x32_bf16 v[8:11], v[210:213], v[180:183], v[8:11]
	v_mfma_f32_16x16x32_bf16 v[4:7], v[202:205], v[194:197], v[4:7]
	v_mfma_f32_16x16x32_bf16 v[0:3], v[210:213], v[194:197], v[0:3]
	s_setprio 0
	v_or_b32_e32 v141, 0x18000, v143
	v_add_u32_e32 v148, 0x18400, v143
	s_barrier
	ds_read_b128 v[144:147], v141
	ds_read_b128 v[148:151], v148
	v_add_u32_e32 v141, 0x18800, v143
	v_add_u32_e32 v156, 0x18c00, v143
	ds_read_b128 v[152:155], v141
	ds_read_b128 v[156:159], v156
	s_add_u32 s36, s36, 0x100000
	s_addc_u32 s37, s37, 0
	s_mov_b32 m0, s44
	v_lshl_add_u64 v[198:199], s[36:37], 0, v[134:135]
	ds_read_b128 v[160:163], v142 offset:32768
	ds_read_b128 v[164:167], v142 offset:33792
	ds_read_b128 v[168:171], v142 offset:34816
	ds_read_b128 v[172:175], v142 offset:35840
	ds_read_b128 v[176:179], v142 offset:36864
	ds_read_b128 v[180:183], v142 offset:37888
	ds_read_b128 v[186:189], v142 offset:38912
	ds_read_b128 v[194:197], v142 offset:39936
	global_load_lds_dwordx4 v[198:199], off
	v_lshl_add_u64 v[198:199], s[36:37], 0, v[130:131]
	s_mov_b32 m0, s45
	s_nop 0
	global_load_lds_dwordx4 v[198:199], off
	s_waitcnt lgkmcnt(8)
	s_barrier
	s_waitcnt lgkmcnt(0)
	s_setprio 1
	s_waitcnt lgkmcnt(0)
	v_mfma_f32_16x16x32_bf16 v[124:127], v[144:147], v[160:163], v[124:127]
	v_mfma_f32_16x16x32_bf16 v[120:123], v[152:155], v[160:163], v[120:123]
	v_mfma_f32_16x16x32_bf16 v[116:119], v[144:147], v[168:171], v[116:119]
	v_mfma_f32_16x16x32_bf16 v[112:115], v[152:155], v[168:171], v[112:115]
	v_mfma_f32_16x16x32_bf16 v[108:111], v[144:147], v[176:179], v[108:111]
	v_mfma_f32_16x16x32_bf16 v[104:107], v[152:155], v[176:179], v[104:107]
	v_mfma_f32_16x16x32_bf16 v[100:103], v[144:147], v[186:189], v[100:103]
	v_mfma_f32_16x16x32_bf16 v[96:99], v[152:155], v[186:189], v[96:99]
	v_mfma_f32_16x16x32_bf16 v[124:127], v[148:151], v[164:167], v[124:127]
	v_mfma_f32_16x16x32_bf16 v[120:123], v[156:159], v[164:167], v[120:123]
	v_mfma_f32_16x16x32_bf16 v[116:119], v[148:151], v[172:175], v[116:119]
	v_mfma_f32_16x16x32_bf16 v[112:115], v[156:159], v[172:175], v[112:115]
	v_mfma_f32_16x16x32_bf16 v[108:111], v[148:151], v[180:183], v[108:111]
	v_mfma_f32_16x16x32_bf16 v[104:107], v[156:159], v[180:183], v[104:107]
	v_mfma_f32_16x16x32_bf16 v[100:103], v[148:151], v[194:197], v[100:103]
	v_mfma_f32_16x16x32_bf16 v[96:99], v[156:159], v[194:197], v[96:99]
	s_setprio 0
	s_barrier
	v_or_b32_e32 v141, 0x1c000, v143
	s_mov_b32 m0, s46
	v_add_u32_e32 v192, 0x1c400, v143
	ds_read_b128 v[198:201], v141
	ds_read_b128 v[202:205], v192
	v_add_u32_e32 v141, 0x1c800, v143
	v_lshl_add_u64 v[190:191], v[190:191], 0, s[24:25]
	v_add_u32_e32 v192, 0x1cc00, v143
	ds_read_b128 v[206:209], v141
	ds_read_b128 v[210:213], v192
	global_load_lds_dwordx4 v[190:191], off
	v_lshl_add_u64 v[190:191], v[214:215], 0, s[24:25]
	s_mov_b32 m0, s47
	s_nop 0
	global_load_lds_dwordx4 v[190:191], off
	s_barrier
	s_waitcnt lgkmcnt(0)
	s_setprio 1
	s_waitcnt lgkmcnt(0)
	v_mfma_f32_16x16x32_bf16 v[92:95], v[198:201], v[160:163], v[92:95]
	v_mfma_f32_16x16x32_bf16 v[88:91], v[206:209], v[160:163], v[88:91]
	v_mfma_f32_16x16x32_bf16 v[84:87], v[198:201], v[168:171], v[84:87]
	v_mfma_f32_16x16x32_bf16 v[80:83], v[206:209], v[168:171], v[80:83]
	v_mfma_f32_16x16x32_bf16 v[76:79], v[198:201], v[176:179], v[76:79]
	v_mfma_f32_16x16x32_bf16 v[72:75], v[206:209], v[176:179], v[72:75]
	v_mfma_f32_16x16x32_bf16 v[68:71], v[198:201], v[186:189], v[68:71]
	v_mfma_f32_16x16x32_bf16 v[64:67], v[206:209], v[186:189], v[64:67]
	v_mfma_f32_16x16x32_bf16 v[92:95], v[202:205], v[164:167], v[92:95]
	v_mfma_f32_16x16x32_bf16 v[88:91], v[210:213], v[164:167], v[88:91]
	v_mfma_f32_16x16x32_bf16 v[84:87], v[202:205], v[172:175], v[84:87]
	v_mfma_f32_16x16x32_bf16 v[80:83], v[210:213], v[172:175], v[80:83]
	v_mfma_f32_16x16x32_bf16 v[76:79], v[202:205], v[180:183], v[76:79]
	v_mfma_f32_16x16x32_bf16 v[72:75], v[210:213], v[180:183], v[72:75]
	v_mfma_f32_16x16x32_bf16 v[68:71], v[202:205], v[194:197], v[68:71]
	v_mfma_f32_16x16x32_bf16 v[64:67], v[210:213], v[194:197], v[64:67]
	s_setprio 0
	s_mov_b32 m0, s48
	v_lshl_add_u64 v[190:191], v[216:217], 0, s[24:25]
	s_barrier
	ds_read_b128 v[160:163], v142 offset:49152
	ds_read_b128 v[164:167], v142 offset:50176
	ds_read_b128 v[168:171], v142 offset:51200
	ds_read_b128 v[172:175], v142 offset:52224
	ds_read_b128 v[176:179], v142 offset:53248
	ds_read_b128 v[180:183], v142 offset:54272
	ds_read_b128 v[186:189], v142 offset:55296
	ds_read_b128 v[194:197], v142 offset:56320
	global_load_lds_dwordx4 v[190:191], off
	v_lshl_add_u64 v[190:191], v[242:243], 0, s[24:25]
	s_mov_b32 m0, s49
	s_nop 0
	global_load_lds_dwordx4 v[190:191], off
	s_barrier
	s_waitcnt lgkmcnt(0)
	s_setprio 1
	s_waitcnt lgkmcnt(0)
	v_mfma_f32_16x16x32_bf16 v[60:63], v[144:147], v[160:163], v[60:63]
	v_mfma_f32_16x16x32_bf16 v[56:59], v[152:155], v[160:163], v[56:59]
	v_mfma_f32_16x16x32_bf16 v[52:55], v[144:147], v[168:171], v[52:55]
	v_mfma_f32_16x16x32_bf16 v[48:51], v[152:155], v[168:171], v[48:51]
	v_mfma_f32_16x16x32_bf16 v[44:47], v[144:147], v[176:179], v[44:47]
	v_mfma_f32_16x16x32_bf16 v[40:43], v[152:155], v[176:179], v[40:43]
	v_mfma_f32_16x16x32_bf16 v[36:39], v[144:147], v[186:189], v[36:39]
	v_mfma_f32_16x16x32_bf16 v[32:35], v[152:155], v[186:189], v[32:35]
	v_mfma_f32_16x16x32_bf16 v[60:63], v[148:151], v[164:167], v[60:63]
	v_mfma_f32_16x16x32_bf16 v[56:59], v[156:159], v[164:167], v[56:59]
	v_mfma_f32_16x16x32_bf16 v[52:55], v[148:151], v[172:175], v[52:55]
	v_mfma_f32_16x16x32_bf16 v[48:51], v[156:159], v[172:175], v[48:51]
	v_mfma_f32_16x16x32_bf16 v[44:47], v[148:151], v[180:183], v[44:47]
	v_mfma_f32_16x16x32_bf16 v[40:43], v[156:159], v[180:183], v[40:43]
	v_mfma_f32_16x16x32_bf16 v[36:39], v[148:151], v[194:197], v[36:39]
	v_mfma_f32_16x16x32_bf16 v[32:35], v[156:159], v[194:197], v[32:35]
	s_setprio 0
	s_barrier
	s_add_u32 s34, s34, 0x800080
	s_addc_u32 s35, s35, 0
	s_mov_b32 m0, s50
	v_lshl_add_u64 v[144:145], s[34:35], 0, v[132:133]
	global_load_lds_dwordx4 v[144:145], off
	v_lshl_add_u64 v[144:145], s[34:35], 0, v[128:129]
	s_mov_b32 m0, s51
	s_nop 0
	global_load_lds_dwordx4 v[144:145], off
	s_waitcnt vmcnt(6)
	s_barrier
	s_setprio 1
	v_mfma_f32_16x16x32_bf16 v[28:31], v[198:201], v[160:163], v[28:31]
	v_mfma_f32_16x16x32_bf16 v[24:27], v[206:209], v[160:163], v[24:27]
	v_mfma_f32_16x16x32_bf16 v[20:23], v[198:201], v[168:171], v[20:23]
	v_mfma_f32_16x16x32_bf16 v[16:19], v[206:209], v[168:171], v[16:19]
	v_mfma_f32_16x16x32_bf16 v[12:15], v[198:201], v[176:179], v[12:15]
	v_mfma_f32_16x16x32_bf16 v[8:11], v[206:209], v[176:179], v[8:11]
	v_mfma_f32_16x16x32_bf16 v[4:7], v[198:201], v[186:189], v[4:7]
	v_mfma_f32_16x16x32_bf16 v[0:3], v[206:209], v[186:189], v[0:3]
	v_mfma_f32_16x16x32_bf16 v[28:31], v[202:205], v[164:167], v[28:31]
	v_mfma_f32_16x16x32_bf16 v[24:27], v[210:213], v[164:167], v[24:27]
	v_mfma_f32_16x16x32_bf16 v[20:23], v[202:205], v[172:175], v[20:23]
	v_mfma_f32_16x16x32_bf16 v[16:19], v[210:213], v[172:175], v[16:19]
	v_mfma_f32_16x16x32_bf16 v[12:15], v[202:205], v[180:183], v[12:15]
	v_mfma_f32_16x16x32_bf16 v[8:11], v[210:213], v[180:183], v[8:11]
	v_mfma_f32_16x16x32_bf16 v[4:7], v[202:205], v[194:197], v[4:7]
	v_mfma_f32_16x16x32_bf16 v[0:3], v[210:213], v[194:197], v[0:3]
	s_setprio 0
	s_add_i32 s96, s96, 2
	s_add_u32 s30, s30, 0x100
	s_addc_u32 s31, s31, 0
	s_add_u32 s26, s26, 0x100
	s_addc_u32 s27, s27, 0
	s_cmp_gt_u32 s96, 13
	s_barrier
	s_cbranch_scc0 .LBB0_234
	s_lshl_b32 s20, s71, 7
	s_lshl_b32 s26, s56, 4
	s_or_b32 s27, s26, s20
	s_add_i32 s34, s27, s52
	s_lshl_b32 s88, s70, 19
	s_nop 1
	s_ashr_i32 s35, s34, 31
	s_lshl_b64 s[30:31], s[88:89], 4
	v_readlane_b32 s74, v253, 18
	v_readlane_b32 s75, v253, 19
	s_add_u32 s27, s74, s30
	s_addc_u32 s30, s75, s31
	s_lshl_b64 s[34:35], s[34:35], 13
	s_add_u32 s31, s27, s34
	s_addc_u32 s33, s30, s35
	s_add_u32 s34, s31, s63
	s_addc_u32 s35, s33, 0
	v_cvt_pk_bf16_f32 v124, v124, v125
	v_cvt_pk_bf16_f32 v125, v126, v127
	v_cvt_pk_bf16_f32 v126, v120, v121
	v_lshl_add_u64 v[120:121], s[34:35], 0, v[184:185]
	s_add_i32 s34, s54, s20
	s_add_i32 s34, s34, s26
	s_ashr_i32 s35, s34, 31
	s_lshl_b64 s[34:35], s[34:35], 13
	s_add_u32 s36, s27, s34
	s_addc_u32 s37, s30, s35
	s_add_u32 s34, s36, s63
	s_addc_u32 s35, s37, 0
	v_cvt_pk_bf16_f32 v116, v116, v117
	v_cvt_pk_bf16_f32 v117, v118, v119
	v_cvt_pk_bf16_f32 v118, v112, v113
	v_lshl_add_u64 v[112:113], s[34:35], 0, v[184:185]
	s_add_i32 s34, s55, s20
	s_add_i32 s34, s34, s26
	s_ashr_i32 s35, s34, 31
	s_lshl_b64 s[34:35], s[34:35], 13
	s_add_u32 s66, s27, s34
	s_addc_u32 s67, s30, s35
	s_add_u32 s34, s66, s63
	s_addc_u32 s35, s67, 0
	v_cvt_pk_bf16_f32 v108, v108, v109
	v_cvt_pk_bf16_f32 v109, v110, v111
	v_cvt_pk_bf16_f32 v110, v104, v105
	v_lshl_add_u64 v[104:105], s[34:35], 0, v[184:185]
	s_add_i32 s34, s58, s20
	s_add_i32 s34, s34, s26
	s_ashr_i32 s35, s34, 31
	s_lshl_b64 s[34:35], s[34:35], 13
	s_add_u32 s70, s27, s34
	s_addc_u32 s71, s30, s35
	s_add_u32 s34, s70, s63
	s_addc_u32 s35, s71, 0
	v_cvt_pk_bf16_f32 v100, v100, v101
	v_cvt_pk_bf16_f32 v101, v102, v103
	v_cvt_pk_bf16_f32 v102, v96, v97
	v_lshl_add_u64 v[96:97], s[34:35], 0, v[184:185]
	s_add_u32 s34, s31, s64
	s_addc_u32 s35, s33, 0
	v_cvt_pk_bf16_f32 v92, v92, v93
	v_cvt_pk_bf16_f32 v93, v94, v95
	v_cvt_pk_bf16_f32 v94, v88, v89
	v_lshl_add_u64 v[88:89], s[34:35], 0, v[184:185]
	s_add_u32 s34, s36, s64
	s_addc_u32 s35, s37, 0
	v_cvt_pk_bf16_f32 v84, v84, v85
	v_cvt_pk_bf16_f32 v85, v86, v87
	v_cvt_pk_bf16_f32 v86, v80, v81
	v_lshl_add_u64 v[80:81], s[34:35], 0, v[184:185]
	s_add_u32 s34, s66, s64
	s_addc_u32 s35, s67, 0
	v_cvt_pk_bf16_f32 v76, v76, v77
	v_cvt_pk_bf16_f32 v77, v78, v79
	v_cvt_pk_bf16_f32 v78, v72, v73
	v_lshl_add_u64 v[72:73], s[34:35], 0, v[184:185]
	s_add_u32 s34, s70, s64
	s_addc_u32 s35, s71, 0
	s_add_i32 s31, s53, s20
	v_cvt_pk_bf16_f32 v68, v68, v69
	v_cvt_pk_bf16_f32 v69, v70, v71
	v_cvt_pk_bf16_f32 v70, v64, v65
	v_lshl_add_u64 v[64:65], s[34:35], 0, v[184:185]
	s_add_i32 s34, s31, s26
	s_ashr_i32 s35, s34, 31
	s_lshl_b64 s[34:35], s[34:35], 13
	s_add_u32 s31, s27, s34
	s_addc_u32 s33, s30, s35
	s_add_u32 s34, s31, s63
	s_addc_u32 s35, s33, 0
	v_cvt_pk_bf16_f32 v60, v60, v61
	v_cvt_pk_bf16_f32 v61, v62, v63
	v_cvt_pk_bf16_f32 v62, v56, v57
	v_lshl_add_u64 v[56:57], s[34:35], 0, v[184:185]
	s_add_i32 s34, s59, s20
	s_add_i32 s34, s34, s26
	s_ashr_i32 s35, s34, 31
	s_lshl_b64 s[34:35], s[34:35], 13
	s_add_u32 s36, s27, s34
	s_addc_u32 s37, s30, s35
	s_add_u32 s34, s36, s63
	s_addc_u32 s35, s37, 0
	v_cvt_pk_bf16_f32 v52, v52, v53
	v_cvt_pk_bf16_f32 v53, v54, v55
	v_cvt_pk_bf16_f32 v54, v48, v49
	v_lshl_add_u64 v[48:49], s[34:35], 0, v[184:185]
	s_add_i32 s34, s60, s20
	s_add_i32 s34, s34, s26
	s_ashr_i32 s35, s34, 31
	s_lshl_b64 s[34:35], s[34:35], 13
	s_add_u32 s66, s27, s34
	s_addc_u32 s67, s30, s35
	s_add_u32 s34, s66, s63
	s_addc_u32 s35, s67, 0
	s_add_i32 s20, s61, s20
	v_cvt_pk_bf16_f32 v44, v44, v45
	v_cvt_pk_bf16_f32 v45, v46, v47
	v_cvt_pk_bf16_f32 v46, v40, v41
	v_lshl_add_u64 v[40:41], s[34:35], 0, v[184:185]
	s_add_i32 s34, s20, s26
	s_ashr_i32 s35, s34, 31
	s_lshl_b64 s[34:35], s[34:35], 13
	s_add_u32 s20, s27, s34
	s_addc_u32 s30, s30, s35
	s_add_u32 s26, s20, s63
	s_addc_u32 s27, s30, 0
	v_cvt_pk_bf16_f32 v36, v36, v37
	v_cvt_pk_bf16_f32 v37, v38, v39
	v_cvt_pk_bf16_f32 v38, v32, v33
	v_lshl_add_u64 v[32:33], s[26:27], 0, v[184:185]
	s_add_u32 s26, s31, s64
	s_addc_u32 s27, s33, 0
	v_cvt_pk_bf16_f32 v28, v28, v29
	v_cvt_pk_bf16_f32 v29, v30, v31
	v_cvt_pk_bf16_f32 v30, v24, v25
	v_lshl_add_u64 v[24:25], s[26:27], 0, v[184:185]
	s_add_u32 s26, s36, s64
	s_addc_u32 s27, s37, 0
	v_cvt_pk_bf16_f32 v20, v20, v21
	v_cvt_pk_bf16_f32 v21, v22, v23
	v_cvt_pk_bf16_f32 v22, v16, v17
	v_lshl_add_u64 v[16:17], s[26:27], 0, v[184:185]
	s_add_u32 s26, s66, s64
	s_addc_u32 s27, s67, 0
	v_cvt_pk_bf16_f32 v12, v12, v13
	v_cvt_pk_bf16_f32 v13, v14, v15
	v_cvt_pk_bf16_f32 v14, v8, v9
	v_lshl_add_u64 v[8:9], s[26:27], 0, v[184:185]
	s_add_u32 s26, s20, s64
	s_addc_u32 s27, s30, 0
	v_mov_b32_e32 v141, v185
	v_cvt_pk_bf16_f32 v4, v4, v5
	v_cvt_pk_bf16_f32 v5, v6, v7
	v_cvt_pk_bf16_f32 v6, v0, v1
	v_lshl_add_u64 v[0:1], s[26:27], 0, v[184:185]
	v_readlane_b32 s78, v253, 22
	v_readlane_b32 s79, v253, 23
	v_lshl_add_u64 v[120:121], v[120:121], 0, v[140:141]
	v_lshl_add_u64 v[112:113], v[112:113], 0, v[140:141]
	v_lshl_add_u64 v[104:105], v[104:105], 0, v[140:141]
	v_lshl_add_u64 v[96:97], v[96:97], 0, v[140:141]
	v_lshl_add_u64 v[88:89], v[88:89], 0, v[140:141]
	v_lshl_add_u64 v[80:81], v[80:81], 0, v[140:141]
	v_lshl_add_u64 v[72:73], v[72:73], 0, v[140:141]
	v_lshl_add_u64 v[64:65], v[64:65], 0, v[140:141]
	v_lshl_add_u64 v[56:57], v[56:57], 0, v[140:141]
	v_lshl_add_u64 v[48:49], v[48:49], 0, v[140:141]
	v_lshl_add_u64 v[40:41], v[40:41], 0, v[140:141]
	v_lshl_add_u64 v[32:33], v[32:33], 0, v[140:141]
	v_lshl_add_u64 v[24:25], v[24:25], 0, v[140:141]
	v_lshl_add_u64 v[16:17], v[16:17], 0, v[140:141]
	v_lshl_add_u64 v[8:9], v[8:9], 0, v[140:141]
	v_lshl_add_u64 v[0:1], v[0:1], 0, v[140:141]
	s_and_b64 vcc, exec, s[0:1]
	s_mov_b32 s71, s65
	s_mov_b32 s70, s68
	s_mov_b32 s56, s69
	v_readlane_b32 s96, v255, 22
	v_cvt_pk_bf16_f32 v127, v122, v123
	s_nop 1
	global_store_dwordx4 v[120:121], v[124:127], off
	v_cvt_pk_bf16_f32 v119, v114, v115
	global_store_dwordx4 v[112:113], v[116:119], off
	v_cvt_pk_bf16_f32 v111, v106, v107
	global_store_dwordx4 v[104:105], v[108:111], off
	v_cvt_pk_bf16_f32 v103, v98, v99
	global_store_dwordx4 v[96:97], v[100:103], off
	v_cvt_pk_bf16_f32 v95, v90, v91
	global_store_dwordx4 v[88:89], v[92:95], off
	v_cvt_pk_bf16_f32 v87, v82, v83
	global_store_dwordx4 v[80:81], v[84:87], off
	v_cvt_pk_bf16_f32 v79, v74, v75
	global_store_dwordx4 v[72:73], v[76:79], off
	v_cvt_pk_bf16_f32 v71, v66, v67
	global_store_dwordx4 v[64:65], v[68:71], off
	v_cvt_pk_bf16_f32 v63, v58, v59
	global_store_dwordx4 v[56:57], v[60:63], off
	v_cvt_pk_bf16_f32 v55, v50, v51
	global_store_dwordx4 v[48:49], v[52:55], off
	v_cvt_pk_bf16_f32 v47, v42, v43
	global_store_dwordx4 v[40:41], v[44:47], off
	v_cvt_pk_bf16_f32 v39, v34, v35
	global_store_dwordx4 v[32:33], v[36:39], off
	v_cvt_pk_bf16_f32 v31, v26, v27
	global_store_dwordx4 v[24:25], v[28:31], off
	v_cvt_pk_bf16_f32 v23, v18, v19
	global_store_dwordx4 v[16:17], v[20:23], off
	v_cvt_pk_bf16_f32 v15, v10, v11
	global_store_dwordx4 v[8:9], v[12:15], off
	v_cvt_pk_bf16_f32 v7, v2, v3
	global_store_dwordx4 v[0:1], v[4:7], off
	s_cbranch_vccz .LBB0_233
	v_readlane_b32 s84, v255, 43
	s_waitcnt vmcnt(0)
	s_nop 1
	v_readlane_b32 s72, v255, 23
	v_readlane_b32 s86, v255, 31
	s_cmpk_gt_u32 s93, 0xff
	v_readlane_b32 s85, v255, 44
	v_readlane_b32 s73, v255, 24
	v_readlane_b32 s74, v255, 25
	v_readlane_b32 s75, v255, 26
	v_readlane_b32 s76, v255, 27
	v_readlane_b32 s77, v255, 28
	v_readlane_b32 s78, v255, 29
	v_readlane_b32 s79, v255, 30
	s_mov_b32 s80, s57
	v_readlane_b32 s93, v255, 34
	v_readlane_b32 s81, v255, 33
	v_readlane_b32 s87, v255, 32
	s_mov_b32 s70, 0xbfb8aa3b
	s_mov_b32 s71, 0x42ce8ed0
	s_cbranch_scc1 .LBB0_238
	s_barrier
.LBB0_238:
	v_readlane_b32 s48, v253, 16
	v_readlane_b32 s56, v253, 24
	v_readlane_b32 s57, v253, 25
	s_mov_b32 s36, 0x800000
	s_barrier
	v_readlane_b32 s49, v253, 17
	s_nop 1
	v_readlane_b32 s53, v253, 21
	v_readlane_b32 s54, v253, 22
	v_readlane_b32 s55, v253, 23
	s_nop 1
.LBB0_239:
	s_sub_i32 s0, s84, 32
	s_cmp_lt_u32 s0, 10
	s_cbranch_scc1 .LBB0_252
	v_readlane_b32 s0, v254, 30
	v_mov_b32_e32 v6, v193
	s_waitcnt lgkmcnt(0)
	s_add_i32 s0, s90, s0
	s_cmp_gt_i32 s0, 7
	v_readfirstlane_b32 s33, v6
	s_cbranch_scc1 .LBB0_250
	v_lshlrev_b32_e32 v3, 4, v6
	v_add_u32_e32 v1, 0x2000, v3
	v_ashrrev_i32_e32 v0, 31, v1
	v_lshrrev_b32_e32 v0, 22, v0
	v_add_u32_e32 v0, v1, v0
	v_ashrrev_i32_e32 v0, 10, v0
	v_mul_i32_i24_e32 v2, 0x400, v0
	v_sub_u32_e32 v1, v1, v2
	v_lshrrev_b32_e32 v2, 4, v1
	v_bitop3_b32 v2, v2, v1, 32 bitop3:0x6c
	v_ashrrev_i32_e32 v1, 31, v2
	v_lshrrev_b32_e32 v1, 26, v1
	v_add_u32_e32 v4, v2, v1
	v_lshlrev_b32_e32 v5, 3, v0
	v_ashrrev_i32_e32 v1, 6, v4
	v_and_b32_e32 v5, -16, v5
	v_add_u32_e32 v5, v1, v5
	v_and_b32_e32 v7, 3, v1
	s_mov_b32 s1, 0x7ffe0
	v_lshrrev_b32_e32 v8, 2, v5
	v_lshlrev_b32_e32 v9, 1, v5
	v_and_b32_e32 v4, 0xc0, v4
	v_and_or_b32 v7, v5, s1, v7
	v_and_b32_e32 v8, 4, v8
	v_and_b32_e32 v9, 24, v9
	v_sub_u32_e32 v2, v2, v4
	v_or3_b32 v7, v7, v8, v9
	v_lshlrev_b32_e32 v8, 5, v0
	v_ashrrev_i16_sdwa v2, v250, sext(v2) dst_sel:DWORD dst_unused:UNUSED_PAD src0_sel:DWORD src1_sel:BYTE_0
	v_and_b32_e32 v8, 32, v8
	v_bfe_i32 v2, v2, 0, 16
	v_add_lshl_u32 v4, v8, v2, 1
	v_lshl_add_u32 v128, v7, 13, v4
	v_lshl_add_u32 v130, v5, 10, v4
	v_bfe_i32 v4, v6, 27, 1
	v_lshrrev_b32_e32 v4, 22, v4
	v_add_u32_e32 v4, v3, v4
	v_and_b32_e32 v4, 0xfffffc00, v4
	v_sub_u32_e32 v3, v3, v4
	v_lshrrev_b32_e32 v4, 4, v3
	v_bitop3_b32 v5, v4, v3, 32 bitop3:0x6c
	v_ashrrev_i32_e32 v4, 31, v6
	v_lshrrev_b32_e32 v4, 26, v4
	v_ashrrev_i32_e32 v3, 31, v3
	v_add_u32_e32 v4, v6, v4
	v_lshrrev_b32_e32 v3, 26, v3
	v_ashrrev_i32_e32 v4, 6, v4
	v_add_u32_e32 v3, v5, v3
	v_lshlrev_b32_e32 v7, 3, v4
	v_ashrrev_i32_e32 v3, 6, v3
	v_and_b32_e32 v7, -16, v7
	v_add_u32_e32 v7, v3, v7
	v_and_b32_e32 v8, 3, v3
	v_lshrrev_b32_e32 v9, 2, v7
	v_lshlrev_b32_e32 v10, 1, v7
	v_and_or_b32 v8, v7, s1, v8
	v_and_b32_e32 v9, 4, v9
	v_and_b32_e32 v10, 24, v10
	v_or3_b32 v8, v8, v9, v10
	v_mul_i32_i24_e32 v10, 64, v3
	s_ashr_i32 s26, s33, 6
	v_sub_u32_e32 v5, v5, v10
	s_ashr_i32 s1, s0, 31
	s_ashr_i32 s20, s33, 8
	s_lshl_b32 s38, s26, 10
	v_lshlrev_b32_e32 v9, 5, v4
	v_ashrrev_i16_sdwa v5, v250, sext(v5) dst_sel:DWORD dst_unused:UNUSED_PAD src0_sel:DWORD src1_sel:BYTE_0
	s_lshl_b64 s[22:23], s[0:1], 10
	v_and_b32_e32 v9, 32, v9
	v_bfe_i32 v5, v5, 0, 16
	s_add_u32 s22, s56, s22
	v_add_lshl_u32 v9, v9, v5, 1
	s_addc_u32 s23, s57, s23
	s_add_i32 s1, s38, 0x10000
	v_lshl_add_u32 v184, v8, 13, v9
	s_waitcnt vmcnt(0)
	s_mov_b32 m0, s1
	s_add_i32 s39, s38, 0x12000
	s_nop 1
	global_load_lds_dwordx4 v184, s[22:23]
	s_mov_b32 m0, s39
	s_add_i32 s40, s38, 0x2000
	v_lshl_add_u32 v132, v7, 10, v9
	global_load_lds_dwordx4 v128, s[22:23]
	s_mov_b32 m0, s38
	s_nop 1
	v_readlane_b32 s54, v253, 14
	v_readlane_b32 s55, v253, 15
	s_add_u32 s28, s22, 0x100000
	s_nop 1
	s_addc_u32 s29, s23, 0
	s_add_i32 s41, s38, 0x14000
	s_nop 1
	global_load_lds_dwordx4 v132, s[54:55]
	s_mov_b32 m0, s40
	s_add_i32 s42, s38, 0x16000
	global_load_lds_dwordx4 v130, s[54:55]
	s_mov_b32 m0, s41
	s_nop 1
	global_load_lds_dwordx4 v184, s[28:29]
	s_mov_b32 m0, s42
	s_add_i32 s43, s38, 0x4000
	v_readlane_b32 s4, v254, 31
	global_load_lds_dwordx4 v128, s[28:29]
	s_mov_b32 m0, s43
	v_readlane_b32 s5, v254, 32
	s_add_i32 s44, s38, 0x6000
	s_mov_b32 s88, s80
	s_cmp_lg_u32 s20, 1
	s_nop 1
	global_load_lds_dwordx4 v132, s[4:5]
	s_mov_b32 m0, s44
	s_nop 1
	global_load_lds_dwordx4 v130, s[4:5]
	s_nop 1
	s_cbranch_scc1 .LBB0_243
	s_barrier
.LBB0_243:
	v_and_b32_e32 v16, 15, v6
	v_and_b32_e32 v17, 48, v6
	v_lshlrev_b32_e32 v6, 2, v6
	s_and_b32 s28, s26, 3
	v_lshl_or_b32 v7, v16, 6, v17
	s_lshl_b32 s26, s20, 13
	v_and_b32_e32 v6, 32, v6
	v_lshl_add_u64 v[8:9], s[22:23], 0, v[184:185]
	v_mov_b32_e32 v129, v185
	s_nop 1
	v_bitop3_b32 v142, v7, s26, v6 bitop3:0xde
	s_lshl_b32 s26, s28, 12
	s_add_i32 s45, s38, 0x18000
	v_lshl_add_u64 v[10:11], s[22:23], 0, v[128:129]
	v_mov_b32_e32 v133, v185
	v_readlane_b32 s62, v253, 14
	v_readlane_b32 s63, v253, 15
	v_bitop3_b32 v143, v7, s26, v6 bitop3:0xde
	v_lshl_add_u64 v[6:7], v[8:9], 0, s[24:25]
	s_mov_b32 m0, s45
	s_add_i32 s46, s38, 0x1a000
	v_lshl_add_u64 v[12:13], s[62:63], 0, v[132:133]
	v_mov_b32_e32 v131, v185
	s_waitcnt vmcnt(4)
	s_barrier
	global_load_lds_dwordx4 v[6:7], off
	v_lshl_add_u64 v[6:7], v[10:11], 0, s[24:25]
	s_mov_b32 m0, s46
	s_add_i32 s47, s38, 0x8000
	s_add_i32 s48, s38, 0xa000
	s_nop 1
	v_lshl_add_u64 v[14:15], s[62:63], 0, v[130:131]
	global_load_lds_dwordx4 v[6:7], off
	v_lshl_add_u64 v[6:7], v[12:13], 0, s[24:25]
	s_mov_b32 m0, s47
	s_add_u32 s26, s22, 0x100080
	s_nop 1
	global_load_lds_dwordx4 v[6:7], off
	v_lshl_add_u64 v[6:7], v[14:15], 0, s[24:25]
	s_mov_b32 m0, s48
	s_addc_u32 s27, s23, 0
	s_add_i32 s49, s38, 0x1c000
	global_load_lds_dwordx4 v[6:7], off
	v_lshl_add_u64 v[6:7], s[26:27], 0, v[184:185]
	s_mov_b32 m0, s49
	s_add_i32 s50, s38, 0x1e000
	global_load_lds_dwordx4 v[6:7], off
	v_lshl_add_u64 v[6:7], s[26:27], 0, v[128:129]
	s_mov_b32 m0, s50
	s_nop 1
	global_load_lds_dwordx4 v[6:7], off
	s_lshl_b32 s51, s20, 2
	s_lshl_b32 s20, s28, 10
	v_readlane_b32 s4, v254, 33
	s_add_u32 s26, s4, s20
	v_readlane_b32 s4, v254, 34
	s_addc_u32 s27, s4, 0
	v_lshlrev_b32_e32 v6, 4, v17
	v_mov_b32_e32 v7, v185
	v_lshl_add_u64 v[6:7], s[26:27], 0, v[6:7]
	v_lshlrev_b32_e32 v8, 4, v16
	v_mov_b32_e32 v9, v185
	v_lshl_add_u64 v[134:135], v[6:7], 0, v[8:9]
	v_lshlrev_b32_e32 v6, 13, v4
	v_and_b32_e32 v6, 0xffffc000, v6
	v_lshl_add_u32 v3, v3, 10, v6
	v_and_b32_e32 v4, 1, v4
	v_lshl_or_b32 v3, v4, 6, v3
	v_lshl_add_u32 v138, v5, 1, v3
	v_lshlrev_b32_e32 v3, 13, v0
	v_and_b32_e32 v3, 0xffffc000, v3
	s_waitcnt vmcnt(6)
	v_lshl_add_u32 v1, v1, 10, v3
	v_and_b32_e32 v0, 1, v0
	s_nop 1
	v_lshl_or_b32 v0, v0, 6, v1
	v_readlane_b32 s58, v253, 10
	s_or_b32 s52, s51, 1
	s_or_b32 s53, s51, 2
	s_or_b32 s54, s51, 3
	v_lshl_add_u64 v[136:137], v[134:135], 0, s[94:95]
	v_mov_b32_e32 v139, v185
	v_lshl_add_u32 v140, v2, 1, v0
	v_mov_b32_e32 v141, v185
	s_mov_b32 s55, 0
	s_mov_b32 s59, s0
	s_nop 1
	s_barrier
.LBB0_244:
	s_add_i32 s55, s55, 1
	s_mov_b64 s[26:27], s[22:23]
	s_mul_i32 s22, s55, s90
	s_mov_b32 s20, s58
	s_add_i32 s58, s22, s0
	s_cmp_lt_i32 s58, 8
	s_cselect_b32 s22, s58, s20
	s_ashr_i32 s23, s22, 31
	s_nop 1
	s_lshl_b64 s[22:23], s[22:23], 10
	v_readlane_b32 s12, v253, 24
	v_readlane_b32 s13, v253, 25
	s_add_u32 s22, s12, s22
	s_addc_u32 s23, s13, s23
	s_cmp_lt_i32 s58, 8
	s_cselect_b32 s20, s23, s27
	s_cselect_b32 s60, s22, s26
	s_cmp_gt_i32 s58, 7
	s_cselect_b64 s[28:29], -1, 0
	s_add_u32 s26, s26, 0x100
	v_mov_b32_e32 v0, 0
	v_readlane_b32 s30, v255, 17
	s_nop 1
	s_addc_u32 s27, s27, 0
	s_mov_b32 s61, -2
	v_readlane_b32 s31, v255, 18
	v_mov_b32_e32 v1, v0
	v_mov_b32_e32 v2, v0
	v_mov_b32_e32 v3, v0
	v_mov_b32_e32 v4, v0
	v_mov_b32_e32 v5, v0
	v_mov_b32_e32 v6, v0
	v_mov_b32_e32 v7, v0
	v_mov_b32_e32 v8, v0
	v_mov_b32_e32 v9, v0
	v_mov_b32_e32 v10, v0
	v_mov_b32_e32 v11, v0
	v_mov_b32_e32 v12, v0
	v_mov_b32_e32 v13, v0
	v_mov_b32_e32 v14, v0
	v_mov_b32_e32 v15, v0
	v_mov_b32_e32 v16, v0
	v_mov_b32_e32 v17, v0
	v_mov_b32_e32 v18, v0
	v_mov_b32_e32 v19, v0
	v_mov_b32_e32 v20, v0
	v_mov_b32_e32 v21, v0
	v_mov_b32_e32 v22, v0
	v_mov_b32_e32 v23, v0
	v_mov_b32_e32 v24, v0
	v_mov_b32_e32 v25, v0
	v_mov_b32_e32 v26, v0
	v_mov_b32_e32 v27, v0
	v_mov_b32_e32 v28, v0
	v_mov_b32_e32 v29, v0
	v_mov_b32_e32 v30, v0
	v_mov_b32_e32 v31, v0
	v_mov_b32_e32 v32, v0
	v_mov_b32_e32 v33, v0
	v_mov_b32_e32 v34, v0
	v_mov_b32_e32 v35, v0
	v_mov_b32_e32 v36, v0
	v_mov_b32_e32 v37, v0
	v_mov_b32_e32 v38, v0
	v_mov_b32_e32 v39, v0
	v_mov_b32_e32 v40, v0
	v_mov_b32_e32 v41, v0
	v_mov_b32_e32 v42, v0
	v_mov_b32_e32 v43, v0
	v_mov_b32_e32 v44, v0
	v_mov_b32_e32 v45, v0
	v_mov_b32_e32 v46, v0
	v_mov_b32_e32 v47, v0
	v_mov_b32_e32 v48, v0
	v_mov_b32_e32 v49, v0
	v_mov_b32_e32 v50, v0
	v_mov_b32_e32 v51, v0
	v_mov_b32_e32 v52, v0
	v_mov_b32_e32 v53, v0
	v_mov_b32_e32 v54, v0
	v_mov_b32_e32 v55, v0
	v_mov_b32_e32 v56, v0
	v_mov_b32_e32 v57, v0
	v_mov_b32_e32 v58, v0
	v_mov_b32_e32 v59, v0
	v_mov_b32_e32 v60, v0
	v_mov_b32_e32 v61, v0
	v_mov_b32_e32 v62, v0
	v_mov_b32_e32 v63, v0
	v_mov_b32_e32 v64, v0
	v_mov_b32_e32 v65, v0
	v_mov_b32_e32 v66, v0
	v_mov_b32_e32 v67, v0
	v_mov_b32_e32 v68, v0
	v_mov_b32_e32 v69, v0
	v_mov_b32_e32 v70, v0
	v_mov_b32_e32 v71, v0
	v_mov_b32_e32 v72, v0
	v_mov_b32_e32 v73, v0
	v_mov_b32_e32 v74, v0
	v_mov_b32_e32 v75, v0
	v_mov_b32_e32 v76, v0
	v_mov_b32_e32 v77, v0
	v_mov_b32_e32 v78, v0
	v_mov_b32_e32 v79, v0
	v_mov_b32_e32 v80, v0
	v_mov_b32_e32 v81, v0
	v_mov_b32_e32 v82, v0
	v_mov_b32_e32 v83, v0
	v_mov_b32_e32 v84, v0
	v_mov_b32_e32 v85, v0
	v_mov_b32_e32 v86, v0
	v_mov_b32_e32 v87, v0
	v_mov_b32_e32 v88, v0
	v_mov_b32_e32 v89, v0
	v_mov_b32_e32 v90, v0
	v_mov_b32_e32 v91, v0
	v_mov_b32_e32 v92, v0
	v_mov_b32_e32 v93, v0
	v_mov_b32_e32 v94, v0
	v_mov_b32_e32 v95, v0
	v_mov_b32_e32 v96, v0
	v_mov_b32_e32 v97, v0
	v_mov_b32_e32 v98, v0
	v_mov_b32_e32 v99, v0
	v_mov_b32_e32 v100, v0
	v_mov_b32_e32 v101, v0
	v_mov_b32_e32 v102, v0
	v_mov_b32_e32 v103, v0
	v_mov_b32_e32 v104, v0
	v_mov_b32_e32 v105, v0
	v_mov_b32_e32 v106, v0
	v_mov_b32_e32 v107, v0
	v_mov_b32_e32 v108, v0
	v_mov_b32_e32 v109, v0
	v_mov_b32_e32 v110, v0
	v_mov_b32_e32 v111, v0
	v_mov_b32_e32 v112, v0
	v_mov_b32_e32 v113, v0
	v_mov_b32_e32 v114, v0
	v_mov_b32_e32 v115, v0
	v_mov_b32_e32 v116, v0
	v_mov_b32_e32 v117, v0
	v_mov_b32_e32 v118, v0
	v_mov_b32_e32 v119, v0
	v_mov_b32_e32 v120, v0
	v_mov_b32_e32 v121, v0
	v_mov_b32_e32 v122, v0
	v_mov_b32_e32 v123, v0
	v_mov_b32_e32 v124, v0
	v_mov_b32_e32 v125, v0
	v_mov_b32_e32 v126, v0
	v_mov_b32_e32 v127, v0
	v_readlane_b32 s78, v253, 14
	v_readlane_b32 s79, v253, 15
	s_nop 1
	v_readlane_b32 s65, v253, 1
	s_nop 1
	v_readlane_b32 s68, v253, 4
	v_readlane_b32 s69, v253, 5
	s_nop 1

.LBB0_284:
	s_andn2_b64 vcc, exec, s[22:23]
	s_cbranch_vccnz .LBB0_479
	v_bfe_i32 v2, v0, 27, 1
	v_lshlrev_b32_e32 v4, 4, v0
	v_lshrrev_b32_e32 v2, 22, v2
	v_add_u32_e32 v2, v4, v2
	v_and_b32_e32 v2, 0xfffffc00, v2
	v_sub_u32_e32 v2, v4, v2
	v_lshrrev_b32_e32 v3, 4, v2
	v_bitop3_b32 v3, v3, v2, 32 bitop3:0x6c
	v_ashrrev_i32_e32 v2, 31, v2
	v_lshrrev_b32_e32 v2, 26, v2
	v_ashrrev_i32_e32 v1, 31, v0
	v_add_u32_e32 v2, v3, v2
	v_lshrrev_b32_e32 v1, 26, v1
	v_ashrrev_i32_e32 v2, 6, v2
	v_add_u32_e32 v1, v0, v1
	v_mul_i32_i24_e32 v7, 64, v2
	v_ashrrev_i32_e32 v1, 6, v1
	v_sub_u32_e32 v3, v3, v7
	v_lshlrev_b32_e32 v5, 3, v1
	v_lshlrev_b32_e32 v6, 5, v1
	v_ashrrev_i16_sdwa v3, v250, sext(v3) dst_sel:DWORD dst_unused:UNUSED_PAD src0_sel:DWORD src1_sel:BYTE_0
	v_and_b32_e32 v5, -16, v5
	v_and_b32_e32 v6, 32, v6
	v_bfe_i32 v3, v3, 0, 16
	v_add_u32_e32 v5, v2, v5
	v_and_b32_e32 v9, 3, v2
	s_mov_b32 s4, 0x1fffe0
	v_add_lshl_u32 v6, v6, v3, 1
	v_lshlrev_b32_e32 v7, 1, v5
	v_lshrrev_b32_e32 v8, 2, v5
	v_and_or_b32 v9, v5, s4, v9
	v_lshl_add_u32 v132, v5, 11, v6
	v_add_u32_e32 v5, 0x2000, v4
	v_ashrrev_i32_e32 v4, 31, v5
	v_lshrrev_b32_e32 v4, 22, v4
	v_and_b32_e32 v7, 24, v7
	v_and_b32_e32 v8, 4, v8
	v_add_u32_e32 v4, v5, v4
	s_bitcmp1_b32 s92, 0
	s_nop 1
	v_or3_b32 v7, v9, v8, v7
	v_ashrrev_i32_e32 v4, 10, v4
	s_cselect_b32 s20, 0x2180000, 0
	v_readlane_b32 s58, v253, 2
	v_lshl_add_u32 v134, v7, 11, v6
	v_mul_i32_i24_e32 v6, 0x400, v4
	s_nop 1
	v_readlane_b32 s59, v253, 3
	s_add_u32 s56, s58, s20
	v_sub_u32_e32 v5, v5, v6
	s_addc_u32 s57, s59, 0
	s_ashr_i32 s20, s91, 6
	v_lshrrev_b32_e32 v6, 4, v5
	s_lshl_b32 s23, s53, 8
	v_bitop3_b32 v6, v6, v5, 32 bitop3:0x6c
	v_lshlrev_b32_e32 v5, 3, v4
	s_ashr_i32 s22, s91, 8
	s_lshl_b32 s58, s20, 10
	s_addk_i32 s23, 0x1800
	v_and_b32_e32 v7, -16, v5
	v_ashrrev_i32_e32 v5, 31, v6
	s_and_b64 s[26:27], s[0:1], exec
	v_lshrrev_b32_e32 v5, 26, v5
	s_cselect_b32 s26, s53, s23
	v_add_u32_e32 v8, v6, v5
	s_ashr_i32 s27, s26, 31
	v_ashrrev_i32_e32 v5, 6, v8
	s_and_b64 s[28:29], s[0:1], exec
	v_add_u32_e32 v7, v5, v7
	v_and_b32_e32 v11, 3, v5
	s_cselect_b32 s23, 19, 11
	s_ashr_i32 s39, s38, 31
	v_and_or_b32 v11, v7, s4, v11
	s_lshl_b64 s[26:27], s[26:27], s23
	s_lshl_b64 s[28:29], s[38:39], 19
	s_nop 1
	s_and_b64 s[30:31], s[0:1], exec
	v_readlane_b32 s6, v253, 18
	v_readlane_b32 s7, v253, 19
	s_cselect_b32 s30, s56, s6
	v_and_b32_e32 v8, 0xc0, v8
	s_cselect_b32 s23, s57, s7
	s_add_u32 s28, s30, s28
	v_sub_u32_e32 v6, v6, v8
	s_addc_u32 s29, s23, s29
	s_add_i32 s39, s58, 0x10000
	s_add_i32 s59, s58, 0x12000
	v_lshlrev_b32_e32 v9, 5, v4
	v_ashrrev_i16_sdwa v6, v250, sext(v6) dst_sel:DWORD dst_unused:UNUSED_PAD src0_sel:DWORD src1_sel:BYTE_0
	v_lshlrev_b32_e32 v8, 1, v7
	v_lshrrev_b32_e32 v10, 2, v7
	s_and_b64 s[0:1], s[0:1], exec
	v_and_b32_e32 v9, 32, v9
	v_bfe_i32 v6, v6, 0, 16
	v_and_b32_e32 v8, 24, v8
	v_and_b32_e32 v10, 4, v10
	s_cselect_b32 s0, s6, s56
	s_nop 1
	v_or3_b32 v8, v11, v10, v8
	v_add_lshl_u32 v9, v9, v6, 1
	s_waitcnt vmcnt(0)
	s_mov_b32 m0, s39
	s_cselect_b32 s1, s7, s57
	s_add_u32 s0, s0, s26
	v_lshl_add_u32 v138, v8, 11, v9
	global_load_lds_dwordx4 v134, s[28:29]
	s_mov_b32 m0, s59
	s_addc_u32 s1, s1, s27
	s_add_i32 s60, s58, 0x2000
	s_nop 1
	global_load_lds_dwordx4 v138, s[28:29]
	s_mov_b32 m0, s58
	s_add_u32 s26, s28, 0x40000
	s_nop 1
	v_lshl_add_u32 v136, v7, 11, v9
	global_load_lds_dwordx4 v132, s[0:1]
	s_mov_b32 m0, s60
	s_addc_u32 s27, s29, 0
	s_add_i32 s61, s58, 0x14000
	global_load_lds_dwordx4 v136, s[0:1]
	s_mov_b32 m0, s61
	s_add_i32 s62, s58, 0x16000
	global_load_lds_dwordx4 v134, s[26:27]
	s_mov_b32 m0, s62
	s_nop 1
	global_load_lds_dwordx4 v138, s[26:27]
	s_add_u32 s26, s0, 0x40000
	s_nop 1
	s_addc_u32 s27, s1, 0
	s_add_i32 s63, s58, 0x4000
	s_mov_b32 m0, s63
	s_add_i32 s64, s58, 0x6000
	global_load_lds_dwordx4 v132, s[26:27]
	s_mov_b32 m0, s64
	v_writelane_b32 v255, s84, 43
	global_load_lds_dwordx4 v136, s[26:27]
	s_nop 0
	v_writelane_b32 v255, s85, 44
	v_writelane_b32 v255, s86, 45
	v_writelane_b32 v255, s87, 46
	s_cmp_lg_u32 s22, 1
	s_nop 1
	s_cbranch_scc1 .LBB0_287
	s_barrier
.LBB0_287:
	v_mov_b32_e32 v135, v185
	v_lshl_add_u64 v[8:9], s[28:29], 0, v[134:135]
	v_mov_b32_e32 v139, v185
	s_add_i32 s68, s58, 0x18000
	v_lshl_add_u64 v[10:11], s[28:29], 0, v[138:139]
	v_mov_b32_e32 v133, v185
	s_and_b32 s49, s20, 3
	v_lshl_add_u64 v[8:9], v[8:9], 0, s[24:25]
	s_mov_b32 m0, s68
	s_add_i32 s69, s58, 0x1a000
	v_lshl_add_u64 v[12:13], s[0:1], 0, v[132:133]
	v_mov_b32_e32 v137, v185
	s_lshl_b32 s66, s22, 6
	s_lshl_b32 s20, s22, 13
	s_lshl_b32 s23, s49, 12
	s_waitcnt vmcnt(4)
	s_barrier
	global_load_lds_dwordx4 v[8:9], off
	v_lshl_add_u64 v[8:9], v[10:11], 0, s[24:25]
	s_mov_b32 m0, s69
	s_add_i32 s70, s58, 0x8000
	s_add_i32 s71, s58, 0xa000
	v_lshl_add_u64 v[14:15], s[0:1], 0, v[136:137]
	global_load_lds_dwordx4 v[8:9], off
	v_lshl_add_u64 v[8:9], v[12:13], 0, s[24:25]
	s_mov_b32 m0, s70
	s_add_u32 s26, s28, 0x40080
	global_load_lds_dwordx4 v[8:9], off
	v_lshl_add_u64 v[8:9], v[14:15], 0, s[24:25]
	s_mov_b32 m0, s71
	s_addc_u32 s27, s29, 0
	s_add_i32 s52, s58, 0x1c000
	global_load_lds_dwordx4 v[8:9], off
	v_lshl_add_u64 v[8:9], s[26:27], 0, v[134:135]
	s_mov_b32 m0, s52
	s_add_i32 s50, s58, 0x1e000
	global_load_lds_dwordx4 v[8:9], off
	v_lshl_add_u64 v[8:9], s[26:27], 0, v[138:139]
	s_mov_b32 m0, s50
	v_bfe_u32 v7, v0, 4, 2
	global_load_lds_dwordx4 v[8:9], off
	v_and_b32_e32 v140, 15, v0
	v_lshlrev_b32_e32 v142, 4, v7
	v_lshlrev_b32_e32 v0, 2, v0
	v_lshlrev_b32_e32 v8, 3, v7
	v_lshl_or_b32 v7, v140, 6, v142
	v_and_b32_e32 v0, 32, v0
	v_bitop3_b32 v141, v7, s20, v0 bitop3:0xde
	v_bitop3_b32 v143, v7, s23, v0 bitop3:0xde
	v_lshlrev_b32_e32 v0, 14, v1
	s_lshl_b32 s67, s22, 2
	v_and_b32_e32 v0, 0xffff8000, v0
	s_add_i32 s4, s67, 8
	v_lshl_add_u32 v0, v2, 11, v0
	v_and_b32_e32 v1, 1, v1
	v_writelane_b32 v255, s4, 47
	s_add_i32 s4, s67, 9
	v_lshl_or_b32 v0, v1, 6, v0
	v_writelane_b32 v255, s4, 49
	s_add_i32 s4, s67, 10
	v_lshl_add_u32 v148, v3, 1, v0
	v_lshlrev_b32_e32 v0, 14, v4
	v_writelane_b32 v255, s4, 50
	s_add_i32 s4, s67, 11
	v_and_b32_e32 v0, 0xffff8000, v0
	s_waitcnt vmcnt(6)
	v_lshl_or_b32 v144, s49, 5, v8
	v_writelane_b32 v255, s4, 51
	s_nop 1
	v_lshl_add_u32 v0, v5, 11, v0
	v_and_b32_e32 v1, 1, v4
	v_lshlrev_b32_e32 v184, 1, v144
	v_readlane_b32 s12, v253, 24
	v_readlane_b32 s13, v253, 25
	v_lshl_or_b32 v0, v1, 6, v0
	s_or_b32 s48, s49, 0xffffffc0
	v_mov_b32_e32 v145, v185
	s_or_b32 s84, s67, 1
	s_or_b32 s85, s67, 2
	s_or_b32 s92, s67, 3
	v_or_b32_e32 v156, 0x80, v144
	s_orn2_b32 s49, s49, 59
	v_lshl_add_u64 v[146:147], s[12:13], 0, v[184:185]
	v_mov_b32_e32 v149, v185
	v_lshl_add_u32 v150, v6, 1, v0
	v_mov_b32_e32 v151, v185
	s_mov_b32 s65, 0
	s_barrier
	s_nop 1
	s_branch .LBB0_289

.LBB0_298:
	s_lshl_b32 s20, s55, 8
	s_addk_i32 s20, 0x1800
	s_cmp_eq_u32 s54, 0
	s_nop 1
	s_cselect_b32 s26, s55, s20
	v_readlane_b32 s6, v253, 18
	v_readlane_b32 s7, v253, 19
	s_cselect_b32 s20, 19, 11
	s_cselect_b32 s34, s7, s57
	s_cselect_b32 s35, s6, s56
	s_cselect_b32 s36, s56, s6
	s_cselect_b32 s37, s57, s7
	s_ashr_i32 s27, s26, 31
	s_lshl_b64 s[26:27], s[26:27], s20
	s_add_u32 s42, s35, s26
	s_addc_u32 s43, s34, s27
	s_and_b64 s[26:27], s[30:31], exec
	s_cselect_b32 s20, s43, s1
	s_cselect_b32 s34, s42, s0
	s_ashr_i32 s41, s40, 31
	s_lshl_b64 s[26:27], s[40:41], 19
	s_add_u32 s44, s36, s26
	s_addc_u32 s45, s37, s27
	s_and_b64 s[26:27], s[30:31], exec
	s_cselect_b32 s35, s45, s29
	s_cselect_b32 s36, s44, s28
	s_add_u32 s0, s0, 0x40080
	s_addc_u32 s1, s1, 0
	s_add_u32 s37, s28, 0x100
	v_mov_b32_e32 v0, 0
	s_addc_u32 s26, s29, 0
	s_mov_b32 s27, -2
	v_mov_b32_e32 v1, v0
	v_mov_b32_e32 v2, v0
	v_mov_b32_e32 v3, v0
	v_mov_b32_e32 v4, v0
	v_mov_b32_e32 v5, v0
	v_mov_b32_e32 v6, v0
	v_mov_b32_e32 v7, v0
	v_mov_b32_e32 v8, v0
	v_mov_b32_e32 v9, v0
	v_mov_b32_e32 v10, v0
	v_mov_b32_e32 v11, v0
	v_mov_b32_e32 v12, v0
	v_mov_b32_e32 v13, v0
	v_mov_b32_e32 v14, v0
	v_mov_b32_e32 v15, v0
	v_mov_b32_e32 v16, v0
	v_mov_b32_e32 v17, v0
	v_mov_b32_e32 v18, v0
	v_mov_b32_e32 v19, v0
	v_mov_b32_e32 v20, v0
	v_mov_b32_e32 v21, v0
	v_mov_b32_e32 v22, v0
	v_mov_b32_e32 v23, v0
	v_mov_b32_e32 v24, v0
	v_mov_b32_e32 v25, v0
	v_mov_b32_e32 v26, v0
	v_mov_b32_e32 v27, v0
	v_mov_b32_e32 v28, v0
	v_mov_b32_e32 v29, v0
	v_mov_b32_e32 v30, v0
	v_mov_b32_e32 v31, v0
	v_mov_b32_e32 v32, v0
	v_mov_b32_e32 v33, v0
	v_mov_b32_e32 v34, v0
	v_mov_b32_e32 v35, v0
	v_mov_b32_e32 v36, v0
	v_mov_b32_e32 v37, v0
	v_mov_b32_e32 v38, v0
	v_mov_b32_e32 v39, v0
	v_mov_b32_e32 v40, v0
	v_mov_b32_e32 v41, v0
	v_mov_b32_e32 v42, v0
	v_mov_b32_e32 v43, v0
	v_mov_b32_e32 v44, v0
	v_mov_b32_e32 v45, v0
	v_mov_b32_e32 v46, v0
	v_mov_b32_e32 v47, v0
	v_mov_b32_e32 v48, v0
	v_mov_b32_e32 v49, v0
	v_mov_b32_e32 v50, v0
	v_mov_b32_e32 v51, v0
	v_mov_b32_e32 v52, v0
	v_mov_b32_e32 v53, v0
	v_mov_b32_e32 v54, v0
	v_mov_b32_e32 v55, v0
	v_mov_b32_e32 v56, v0
	v_mov_b32_e32 v57, v0
	v_mov_b32_e32 v58, v0
	v_mov_b32_e32 v59, v0
	v_mov_b32_e32 v60, v0
	v_mov_b32_e32 v61, v0
	v_mov_b32_e32 v62, v0
	v_mov_b32_e32 v63, v0
	v_mov_b32_e32 v64, v0
	v_mov_b32_e32 v65, v0
	v_mov_b32_e32 v66, v0
	v_mov_b32_e32 v67, v0
	v_mov_b32_e32 v68, v0
	v_mov_b32_e32 v69, v0
	v_mov_b32_e32 v70, v0
	v_mov_b32_e32 v71, v0
	v_mov_b32_e32 v72, v0
	v_mov_b32_e32 v73, v0
	v_mov_b32_e32 v74, v0
	v_mov_b32_e32 v75, v0
	v_mov_b32_e32 v76, v0
	v_mov_b32_e32 v77, v0
	v_mov_b32_e32 v78, v0
	v_mov_b32_e32 v79, v0
	v_mov_b32_e32 v80, v0
	v_mov_b32_e32 v81, v0
	v_mov_b32_e32 v82, v0
	v_mov_b32_e32 v83, v0
	v_mov_b32_e32 v84, v0
	v_mov_b32_e32 v85, v0
	v_mov_b32_e32 v86, v0
	v_mov_b32_e32 v87, v0
	v_mov_b32_e32 v88, v0
	v_mov_b32_e32 v89, v0
	v_mov_b32_e32 v90, v0
	v_mov_b32_e32 v91, v0
	v_mov_b32_e32 v92, v0
	v_mov_b32_e32 v93, v0
	v_mov_b32_e32 v94, v0
	v_mov_b32_e32 v95, v0
	v_mov_b32_e32 v96, v0
	v_mov_b32_e32 v97, v0
	v_mov_b32_e32 v98, v0
	v_mov_b32_e32 v99, v0
	v_mov_b32_e32 v100, v0
	v_mov_b32_e32 v101, v0
	v_mov_b32_e32 v102, v0
	v_mov_b32_e32 v103, v0
	v_mov_b32_e32 v104, v0
	v_mov_b32_e32 v105, v0
	v_mov_b32_e32 v106, v0
	v_mov_b32_e32 v107, v0
	v_mov_b32_e32 v108, v0
	v_mov_b32_e32 v109, v0
	v_mov_b32_e32 v110, v0
	v_mov_b32_e32 v111, v0
	v_mov_b32_e32 v112, v0
	v_mov_b32_e32 v113, v0
	v_mov_b32_e32 v114, v0
	v_mov_b32_e32 v115, v0
	v_mov_b32_e32 v116, v0
	v_mov_b32_e32 v117, v0
	v_mov_b32_e32 v118, v0
	v_mov_b32_e32 v119, v0
	v_mov_b32_e32 v120, v0
	v_mov_b32_e32 v121, v0
	v_mov_b32_e32 v122, v0
	v_mov_b32_e32 v123, v0
	v_mov_b32_e32 v124, v0
	v_mov_b32_e32 v125, v0
	v_mov_b32_e32 v126, v0
	v_mov_b32_e32 v127, v0
	s_nop 1

.LBB0_303:
	s_andn2_saveexec_b64 s[0:1], s[0:1]
	s_cbranch_execz .LBB0_305
	s_ashr_i32 s26, s38, 3
	v_lshlrev_b32_e32 v184, 3, v157
	s_ashr_i32 s27, s26, 31
	v_lshl_add_u64 v[158:159], v[184:185], 0, s[26:27]
	s_nop 1
	s_ashr_i32 s31, s30, 31
	v_lshlrev_b64 v[158:159], 13, v[158:159]
	v_readlane_b32 s10, v253, 22
	v_readlane_b32 s11, v253, 23
	v_and_b32_e32 v153, 0x778, v152
	s_lshl_b64 s[26:27], s[30:31], 12
	v_lshl_add_u64 v[158:159], s[10:11], 0, v[158:159]
	v_lshl_add_u64 v[158:159], v[158:159], 0, s[26:27]
	v_lshlrev_b32_e32 v184, 1, v153
	v_lshl_add_u64 v[158:159], v[158:159], 0, v[184:185]
	s_nop 1
	global_store_dwordx4 v[158:159], v[128:131], off

.LBB0_306:
.LBB0_307:
	s_cmp_lt_i32 s38, 8
	s_mov_b64 s[0:1], -1
	s_cbranch_scc0 .LBB0_309
	v_ashrrev_i32_e32 v155, 31, v154
	v_readlane_b32 s4, v253, 16
	v_lshlrev_b64 v[158:159], 12, v[154:155]
	v_readlane_b32 s5, v253, 17
	v_ashrrev_i32_e32 v153, 31, v152
	v_cvt_pk_bf16_f32 v128, v124, v125
	v_cvt_pk_bf16_f32 v129, v126, v127
	v_cvt_pk_bf16_f32 v130, v120, v121
	v_cvt_pk_bf16_f32 v131, v122, v123
	s_nop 0
	v_lshl_add_u64 v[158:159], s[4:5], 0, v[158:159]
	v_lshl_add_u64 v[158:159], v[152:153], 1, v[158:159]
	s_nop 1
	global_store_dwordx4 v[158:159], v[128:131], off
	s_mov_b64 s[0:1], 0

.LBB0_314:
	s_andn2_saveexec_b64 s[28:29], s[28:29]
	s_cbranch_execz .LBB0_316
	s_ashr_i32 s26, s38, 3
	v_lshlrev_b32_e32 v184, 3, v126
	s_ashr_i32 s27, s26, 31
	v_lshl_add_u64 v[128:129], v[184:185], 0, s[26:27]
	s_nop 1
	s_ashr_i32 s1, s0, 31
	v_lshlrev_b64 v[128:129], 13, v[128:129]
	v_readlane_b32 s10, v253, 22
	v_readlane_b32 s11, v253, 23
	v_and_b32_e32 v125, 0x778, v152
	s_lshl_b64 s[0:1], s[0:1], 12
	v_lshl_add_u64 v[128:129], s[10:11], 0, v[128:129]
	v_lshl_add_u64 v[128:129], v[128:129], 0, s[0:1]
	v_lshlrev_b32_e32 v184, 1, v125
	v_lshl_add_u64 v[128:129], v[128:129], 0, v[184:185]
	s_nop 1
	global_store_dwordx4 v[128:129], v[120:123], off

.LBB0_317:
.LBB0_318:
	s_cmp_gt_i32 s38, 7
	s_mov_b64 s[0:1], -1
	s_cbranch_scc1 .LBB0_320
	v_ashrrev_i32_e32 v125, 31, v124
	v_readlane_b32 s4, v253, 16
	v_lshlrev_b64 v[128:129], 12, v[124:125]
	v_readlane_b32 s5, v253, 17
	v_ashrrev_i32_e32 v153, 31, v152
	s_mov_b64 s[0:1], 0
	v_lshl_add_u64 v[128:129], s[4:5], 0, v[128:129]
	v_lshl_add_u64 v[128:129], v[152:153], 1, v[128:129]
	v_cvt_pk_bf16_f32 v120, v116, v117
	v_cvt_pk_bf16_f32 v121, v118, v119
	v_cvt_pk_bf16_f32 v122, v112, v113
	v_cvt_pk_bf16_f32 v123, v114, v115
	s_nop 1
	global_store_dwordx4 v[128:129], v[120:123], off

.LBB0_325:
	s_andn2_saveexec_b64 s[28:29], s[28:29]
	s_cbranch_execz .LBB0_327
	s_ashr_i32 s26, s38, 3
	v_lshlrev_b32_e32 v184, 3, v118
	s_ashr_i32 s27, s26, 31
	v_lshl_add_u64 v[120:121], v[184:185], 0, s[26:27]
	s_nop 1
	s_ashr_i32 s1, s0, 31
	v_lshlrev_b64 v[120:121], 13, v[120:121]
	v_readlane_b32 s10, v253, 22
	v_readlane_b32 s11, v253, 23
	v_and_b32_e32 v117, 0x778, v152
	s_lshl_b64 s[0:1], s[0:1], 12
	v_lshl_add_u64 v[120:121], s[10:11], 0, v[120:121]
	v_lshl_add_u64 v[120:121], v[120:121], 0, s[0:1]
	v_lshlrev_b32_e32 v184, 1, v117
	v_lshl_add_u64 v[120:121], v[120:121], 0, v[184:185]
	s_nop 1
	global_store_dwordx4 v[120:121], v[112:115], off

.LBB0_328:
.LBB0_329:
	s_cmp_gt_i32 s38, 7
	s_mov_b64 s[0:1], -1
	s_cbranch_scc1 .LBB0_331
	v_ashrrev_i32_e32 v117, 31, v116
	v_readlane_b32 s4, v253, 16
	v_lshlrev_b64 v[120:121], 12, v[116:117]
	v_readlane_b32 s5, v253, 17
	v_ashrrev_i32_e32 v153, 31, v152
	s_mov_b64 s[0:1], 0
	v_lshl_add_u64 v[120:121], s[4:5], 0, v[120:121]
	v_lshl_add_u64 v[120:121], v[152:153], 1, v[120:121]
	v_cvt_pk_bf16_f32 v112, v108, v109
	v_cvt_pk_bf16_f32 v113, v110, v111
	v_cvt_pk_bf16_f32 v114, v104, v105
	v_cvt_pk_bf16_f32 v115, v106, v107
	s_nop 1
	global_store_dwordx4 v[120:121], v[112:115], off

.LBB0_336:
	s_andn2_saveexec_b64 s[28:29], s[28:29]
	s_cbranch_execz .LBB0_338
	s_ashr_i32 s26, s38, 3
	v_lshlrev_b32_e32 v184, 3, v110
	s_ashr_i32 s27, s26, 31
	v_lshl_add_u64 v[112:113], v[184:185], 0, s[26:27]
	s_nop 1
	s_ashr_i32 s1, s0, 31
	v_lshlrev_b64 v[112:113], 13, v[112:113]
	v_readlane_b32 s10, v253, 22
	v_readlane_b32 s11, v253, 23
	v_and_b32_e32 v109, 0x778, v152
	s_lshl_b64 s[0:1], s[0:1], 12
	v_lshl_add_u64 v[112:113], s[10:11], 0, v[112:113]
	v_lshl_add_u64 v[112:113], v[112:113], 0, s[0:1]
	v_lshlrev_b32_e32 v184, 1, v109
	v_lshl_add_u64 v[112:113], v[112:113], 0, v[184:185]
	s_nop 1
	global_store_dwordx4 v[112:113], v[104:107], off

.LBB0_339:
.LBB0_340:
	s_cmp_gt_i32 s38, 7
	s_mov_b64 s[0:1], -1
	s_cbranch_scc1 .LBB0_342
	v_ashrrev_i32_e32 v109, 31, v108
	v_readlane_b32 s4, v253, 16
	v_lshlrev_b64 v[112:113], 12, v[108:109]
	v_readlane_b32 s5, v253, 17
	v_ashrrev_i32_e32 v153, 31, v152
	s_mov_b64 s[0:1], 0
	v_lshl_add_u64 v[112:113], s[4:5], 0, v[112:113]
	v_lshl_add_u64 v[112:113], v[152:153], 1, v[112:113]
	v_cvt_pk_bf16_f32 v104, v100, v101
	v_cvt_pk_bf16_f32 v105, v102, v103
	v_cvt_pk_bf16_f32 v106, v96, v97
	v_cvt_pk_bf16_f32 v107, v98, v99
	s_nop 1
	global_store_dwordx4 v[112:113], v[104:107], off

.LBB0_347:
	s_andn2_saveexec_b64 s[0:1], s[0:1]
	s_cbranch_execz .LBB0_349
	s_ashr_i32 s26, s38, 3
	v_lshlrev_b32_e32 v184, 3, v157
	s_ashr_i32 s27, s26, 31
	v_lshl_add_u64 v[102:103], v[184:185], 0, s[26:27]
	s_nop 1
	s_ashr_i32 s29, s28, 31
	v_lshlrev_b64 v[102:103], 13, v[102:103]
	v_readlane_b32 s10, v253, 22
	v_readlane_b32 s11, v253, 23
	v_and_b32_e32 v101, 0x7f8, v100
	s_lshl_b64 s[26:27], s[28:29], 12
	v_lshl_add_u64 v[102:103], s[10:11], 0, v[102:103]
	v_lshl_add_u64 v[102:103], v[102:103], 0, s[26:27]
	v_lshlrev_b32_e32 v184, 1, v101
	v_lshl_add_u64 v[102:103], v[102:103], 0, v[184:185]
	s_nop 1
	global_store_dwordx4 v[102:103], v[96:99], off

.LBB0_350:
.LBB0_351:
	s_cmp_gt_i32 s38, 7
	s_mov_b64 s[0:1], -1
	s_cbranch_scc1 .LBB0_353
	v_ashrrev_i32_e32 v155, 31, v154
	v_readlane_b32 s4, v253, 16
	v_lshlrev_b64 v[102:103], 12, v[154:155]
	v_readlane_b32 s5, v253, 17
	s_ashr_i32 s47, s46, 31
	v_lshl_add_u64 v[104:105], s[46:47], 0, v[144:145]
	v_lshl_add_u64 v[102:103], s[4:5], 0, v[102:103]
	v_lshl_add_u64 v[102:103], v[104:105], 1, v[102:103]
	s_mov_b64 s[0:1], 0
	v_cvt_pk_bf16_f32 v96, v92, v93
	v_cvt_pk_bf16_f32 v97, v94, v95
	v_cvt_pk_bf16_f32 v98, v88, v89
	v_cvt_pk_bf16_f32 v99, v90, v91
	s_nop 1
	global_store_dwordx4 v[102:103], v[96:99], off offset:256

.LBB0_358:
	s_andn2_saveexec_b64 s[28:29], s[28:29]
	s_cbranch_execz .LBB0_360
	s_ashr_i32 s26, s38, 3
	v_lshlrev_b32_e32 v184, 3, v126
	s_ashr_i32 s27, s26, 31
	v_lshl_add_u64 v[92:93], v[184:185], 0, s[26:27]
	s_nop 1
	s_ashr_i32 s1, s0, 31
	v_lshlrev_b64 v[92:93], 13, v[92:93]
	v_readlane_b32 s10, v253, 22
	v_readlane_b32 s11, v253, 23
	v_and_b32_e32 v94, 0x7f8, v100
	s_lshl_b64 s[0:1], s[0:1], 12
	v_lshl_add_u64 v[92:93], s[10:11], 0, v[92:93]
	v_lshl_add_u64 v[92:93], v[92:93], 0, s[0:1]
	v_lshlrev_b32_e32 v184, 1, v94
	v_lshl_add_u64 v[92:93], v[92:93], 0, v[184:185]
	s_nop 1
	global_store_dwordx4 v[92:93], v[88:91], off

.LBB0_361:
.LBB0_362:
	s_cmp_gt_i32 s38, 7
	s_mov_b64 s[0:1], -1
	s_cbranch_scc1 .LBB0_364
	v_ashrrev_i32_e32 v125, 31, v124
	v_readlane_b32 s4, v253, 16
	v_lshlrev_b64 v[92:93], 12, v[124:125]
	v_readlane_b32 s5, v253, 17
	s_ashr_i32 s47, s46, 31
	v_lshl_add_u64 v[94:95], s[46:47], 0, v[144:145]
	v_lshl_add_u64 v[92:93], s[4:5], 0, v[92:93]
	v_lshl_add_u64 v[92:93], v[94:95], 1, v[92:93]
	s_mov_b64 s[0:1], 0
	v_cvt_pk_bf16_f32 v88, v84, v85
	v_cvt_pk_bf16_f32 v89, v86, v87
	v_cvt_pk_bf16_f32 v90, v80, v81
	v_cvt_pk_bf16_f32 v91, v82, v83
	s_nop 1
	global_store_dwordx4 v[92:93], v[88:91], off offset:256

.LBB0_369:
	s_andn2_saveexec_b64 s[28:29], s[28:29]
	s_cbranch_execz .LBB0_371
	s_ashr_i32 s26, s38, 3
	v_lshlrev_b32_e32 v184, 3, v118
	s_ashr_i32 s27, s26, 31
	v_lshl_add_u64 v[84:85], v[184:185], 0, s[26:27]
	s_nop 1
	s_ashr_i32 s1, s0, 31
	v_lshlrev_b64 v[84:85], 13, v[84:85]
	v_readlane_b32 s10, v253, 22
	v_readlane_b32 s11, v253, 23
	v_and_b32_e32 v86, 0x7f8, v100
	s_lshl_b64 s[0:1], s[0:1], 12
	v_lshl_add_u64 v[84:85], s[10:11], 0, v[84:85]
	v_lshl_add_u64 v[84:85], v[84:85], 0, s[0:1]
	v_lshlrev_b32_e32 v184, 1, v86
	v_lshl_add_u64 v[84:85], v[84:85], 0, v[184:185]
	s_nop 1
	global_store_dwordx4 v[84:85], v[80:83], off

.LBB0_372:
.LBB0_373:
	s_cmp_gt_i32 s38, 7
	s_mov_b64 s[0:1], -1
	s_cbranch_scc1 .LBB0_375
	v_ashrrev_i32_e32 v117, 31, v116
	v_readlane_b32 s4, v253, 16
	v_lshlrev_b64 v[84:85], 12, v[116:117]
	v_readlane_b32 s5, v253, 17
	s_ashr_i32 s47, s46, 31
	v_lshl_add_u64 v[86:87], s[46:47], 0, v[144:145]
	v_lshl_add_u64 v[84:85], s[4:5], 0, v[84:85]
	v_lshl_add_u64 v[84:85], v[86:87], 1, v[84:85]
	s_mov_b64 s[0:1], 0
	v_cvt_pk_bf16_f32 v80, v76, v77
	v_cvt_pk_bf16_f32 v81, v78, v79
	v_cvt_pk_bf16_f32 v82, v72, v73
	v_cvt_pk_bf16_f32 v83, v74, v75
	s_nop 1
	global_store_dwordx4 v[84:85], v[80:83], off offset:256

.LBB0_380:
	s_andn2_saveexec_b64 s[28:29], s[28:29]
	s_cbranch_execz .LBB0_382
	s_ashr_i32 s26, s38, 3
	v_lshlrev_b32_e32 v184, 3, v110
	s_ashr_i32 s27, s26, 31
	v_lshl_add_u64 v[76:77], v[184:185], 0, s[26:27]
	s_nop 1
	s_ashr_i32 s1, s0, 31
	v_lshlrev_b64 v[76:77], 13, v[76:77]
	v_readlane_b32 s10, v253, 22
	v_readlane_b32 s11, v253, 23
	v_and_b32_e32 v78, 0x7f8, v100
	s_lshl_b64 s[0:1], s[0:1], 12
	v_lshl_add_u64 v[76:77], s[10:11], 0, v[76:77]
	v_lshl_add_u64 v[76:77], v[76:77], 0, s[0:1]
	v_lshlrev_b32_e32 v184, 1, v78
	v_lshl_add_u64 v[76:77], v[76:77], 0, v[184:185]
	s_nop 1
	global_store_dwordx4 v[76:77], v[72:75], off

.LBB0_383:
.LBB0_384:
	s_cmp_gt_i32 s38, 7
	s_mov_b64 s[0:1], -1
	s_cbranch_scc1 .LBB0_386
	v_ashrrev_i32_e32 v109, 31, v108
	v_readlane_b32 s4, v253, 16
	v_lshlrev_b64 v[76:77], 12, v[108:109]
	v_readlane_b32 s5, v253, 17
	s_ashr_i32 s47, s46, 31
	v_lshl_add_u64 v[78:79], s[46:47], 0, v[144:145]
	v_lshl_add_u64 v[76:77], s[4:5], 0, v[76:77]
	v_lshl_add_u64 v[76:77], v[78:79], 1, v[76:77]
	s_mov_b64 s[0:1], 0
	v_cvt_pk_bf16_f32 v72, v68, v69
	v_cvt_pk_bf16_f32 v73, v70, v71
	v_cvt_pk_bf16_f32 v74, v64, v65
	v_cvt_pk_bf16_f32 v75, v66, v67
	s_nop 1
	global_store_dwordx4 v[76:77], v[72:75], off offset:256

.LBB0_391:
	s_andn2_saveexec_b64 s[28:29], s[28:29]
	s_cbranch_execz .LBB0_393
	s_ashr_i32 s26, s38, 3
	v_lshlrev_b32_e32 v184, 3, v70
	s_ashr_i32 s27, s26, 31
	v_lshl_add_u64 v[72:73], v[184:185], 0, s[26:27]
	s_nop 1
	s_ashr_i32 s1, s0, 31
	v_lshlrev_b64 v[72:73], 13, v[72:73]
	v_readlane_b32 s10, v253, 22
	v_readlane_b32 s11, v253, 23
	v_and_b32_e32 v69, 0x778, v152
	s_lshl_b64 s[0:1], s[0:1], 12
	v_lshl_add_u64 v[72:73], s[10:11], 0, v[72:73]
	v_lshl_add_u64 v[72:73], v[72:73], 0, s[0:1]
	v_lshlrev_b32_e32 v184, 1, v69
	v_lshl_add_u64 v[72:73], v[72:73], 0, v[184:185]
	s_nop 1
	global_store_dwordx4 v[72:73], v[64:67], off

.LBB0_394:
.LBB0_395:
	s_cmp_gt_i32 s38, 7
	s_mov_b64 s[0:1], -1
	s_cbranch_scc1 .LBB0_397
	v_ashrrev_i32_e32 v69, 31, v68
	v_readlane_b32 s4, v253, 16
	v_lshlrev_b64 v[72:73], 12, v[68:69]
	v_readlane_b32 s5, v253, 17
	v_ashrrev_i32_e32 v153, 31, v152
	s_mov_b64 s[0:1], 0
	v_lshl_add_u64 v[72:73], s[4:5], 0, v[72:73]
	v_lshl_add_u64 v[72:73], v[152:153], 1, v[72:73]
	v_cvt_pk_bf16_f32 v64, v60, v61
	v_cvt_pk_bf16_f32 v65, v62, v63
	v_cvt_pk_bf16_f32 v66, v56, v57
	v_cvt_pk_bf16_f32 v67, v58, v59
	s_nop 1
	global_store_dwordx4 v[72:73], v[64:67], off

.LBB0_402:
	s_andn2_saveexec_b64 s[28:29], s[28:29]
	s_cbranch_execz .LBB0_404
	s_ashr_i32 s26, s38, 3
	v_lshlrev_b32_e32 v184, 3, v62
	s_ashr_i32 s27, s26, 31
	v_lshl_add_u64 v[64:65], v[184:185], 0, s[26:27]
	s_nop 1
	s_ashr_i32 s1, s0, 31
	v_lshlrev_b64 v[64:65], 13, v[64:65]
	v_readlane_b32 s10, v253, 22
	v_readlane_b32 s11, v253, 23
	v_and_b32_e32 v61, 0x778, v152
	s_lshl_b64 s[0:1], s[0:1], 12
	v_lshl_add_u64 v[64:65], s[10:11], 0, v[64:65]
	v_lshl_add_u64 v[64:65], v[64:65], 0, s[0:1]
	v_lshlrev_b32_e32 v184, 1, v61
	v_lshl_add_u64 v[64:65], v[64:65], 0, v[184:185]
	s_nop 1
	global_store_dwordx4 v[64:65], v[56:59], off

.LBB0_405:
.LBB0_406:
	s_cmp_gt_i32 s38, 7
	s_mov_b64 s[0:1], -1
	s_cbranch_scc1 .LBB0_408
	v_ashrrev_i32_e32 v61, 31, v60
	v_readlane_b32 s4, v253, 16
	v_lshlrev_b64 v[64:65], 12, v[60:61]
	v_readlane_b32 s5, v253, 17
	v_ashrrev_i32_e32 v153, 31, v152
	s_mov_b64 s[0:1], 0
	v_lshl_add_u64 v[64:65], s[4:5], 0, v[64:65]
	v_lshl_add_u64 v[64:65], v[152:153], 1, v[64:65]
	v_cvt_pk_bf16_f32 v56, v52, v53
	v_cvt_pk_bf16_f32 v57, v54, v55
	v_cvt_pk_bf16_f32 v58, v48, v49
	v_cvt_pk_bf16_f32 v59, v50, v51
	s_nop 1
	global_store_dwordx4 v[64:65], v[56:59], off

.LBB0_413:
	s_andn2_saveexec_b64 s[28:29], s[28:29]
	s_cbranch_execz .LBB0_415
	s_ashr_i32 s26, s38, 3
	v_lshlrev_b32_e32 v184, 3, v54
	s_ashr_i32 s27, s26, 31
	v_lshl_add_u64 v[56:57], v[184:185], 0, s[26:27]
	s_nop 1
	s_ashr_i32 s1, s0, 31
	v_lshlrev_b64 v[56:57], 13, v[56:57]
	v_readlane_b32 s10, v253, 22
	v_readlane_b32 s11, v253, 23
	v_and_b32_e32 v53, 0x778, v152
	s_lshl_b64 s[0:1], s[0:1], 12
	v_lshl_add_u64 v[56:57], s[10:11], 0, v[56:57]
	v_lshl_add_u64 v[56:57], v[56:57], 0, s[0:1]
	v_lshlrev_b32_e32 v184, 1, v53
	v_lshl_add_u64 v[56:57], v[56:57], 0, v[184:185]
	s_nop 1
	global_store_dwordx4 v[56:57], v[48:51], off

.LBB0_416:
.LBB0_417:
	s_cmp_gt_i32 s38, 7
	s_mov_b64 s[0:1], -1
	s_cbranch_scc1 .LBB0_419
	v_ashrrev_i32_e32 v53, 31, v52
	v_readlane_b32 s4, v253, 16
	v_lshlrev_b64 v[56:57], 12, v[52:53]
	v_readlane_b32 s5, v253, 17
	v_ashrrev_i32_e32 v153, 31, v152
	s_mov_b64 s[0:1], 0
	v_lshl_add_u64 v[56:57], s[4:5], 0, v[56:57]
	v_lshl_add_u64 v[56:57], v[152:153], 1, v[56:57]
	v_cvt_pk_bf16_f32 v48, v44, v45
	v_cvt_pk_bf16_f32 v49, v46, v47
	v_cvt_pk_bf16_f32 v50, v40, v41
	v_cvt_pk_bf16_f32 v51, v42, v43
	s_nop 1
	global_store_dwordx4 v[56:57], v[48:51], off

.LBB0_424:
	s_andn2_saveexec_b64 s[28:29], s[28:29]
	s_cbranch_execz .LBB0_426
	s_ashr_i32 s26, s38, 3
	v_lshlrev_b32_e32 v184, 3, v46
	s_ashr_i32 s27, s26, 31
	v_lshl_add_u64 v[48:49], v[184:185], 0, s[26:27]
	s_nop 1
	s_ashr_i32 s1, s0, 31
	v_lshlrev_b64 v[48:49], 13, v[48:49]
	v_readlane_b32 s10, v253, 22
	v_readlane_b32 s11, v253, 23
	v_and_b32_e32 v45, 0x778, v152
	s_lshl_b64 s[0:1], s[0:1], 12
	v_lshl_add_u64 v[48:49], s[10:11], 0, v[48:49]
	v_lshl_add_u64 v[48:49], v[48:49], 0, s[0:1]
	v_lshlrev_b32_e32 v184, 1, v45
	v_lshl_add_u64 v[48:49], v[48:49], 0, v[184:185]
	s_nop 1
	global_store_dwordx4 v[48:49], v[40:43], off

.LBB0_427:
.LBB0_428:
	s_cmp_gt_i32 s38, 7
	s_mov_b64 s[0:1], -1
	s_cbranch_scc1 .LBB0_430
	v_ashrrev_i32_e32 v45, 31, v44
	v_readlane_b32 s4, v253, 16
	v_lshlrev_b64 v[48:49], 12, v[44:45]
	v_readlane_b32 s5, v253, 17
	v_ashrrev_i32_e32 v153, 31, v152
	s_mov_b64 s[0:1], 0
	v_lshl_add_u64 v[48:49], s[4:5], 0, v[48:49]
	v_lshl_add_u64 v[48:49], v[152:153], 1, v[48:49]
	v_cvt_pk_bf16_f32 v40, v36, v37
	v_cvt_pk_bf16_f32 v41, v38, v39
	v_cvt_pk_bf16_f32 v42, v32, v33
	v_cvt_pk_bf16_f32 v43, v34, v35
	s_nop 1
	global_store_dwordx4 v[48:49], v[40:43], off

.LBB0_435:
	s_andn2_saveexec_b64 s[28:29], s[28:29]
	s_cbranch_execz .LBB0_437
	s_ashr_i32 s26, s38, 3
	v_lshlrev_b32_e32 v184, 3, v70
	s_ashr_i32 s27, s26, 31
	v_lshl_add_u64 v[36:37], v[184:185], 0, s[26:27]
	s_nop 1
	s_ashr_i32 s1, s0, 31
	v_lshlrev_b64 v[36:37], 13, v[36:37]
	v_readlane_b32 s10, v253, 22
	v_readlane_b32 s11, v253, 23
	v_and_b32_e32 v38, 0x7f8, v100
	s_lshl_b64 s[0:1], s[0:1], 12
	v_lshl_add_u64 v[36:37], s[10:11], 0, v[36:37]
	v_lshl_add_u64 v[36:37], v[36:37], 0, s[0:1]
	v_lshlrev_b32_e32 v184, 1, v38
	v_lshl_add_u64 v[36:37], v[36:37], 0, v[184:185]
	s_nop 1
	global_store_dwordx4 v[36:37], v[32:35], off

.LBB0_438:
.LBB0_439:
	s_cmp_gt_i32 s38, 7
	s_mov_b64 s[0:1], -1
	s_cbranch_scc1 .LBB0_441
	v_ashrrev_i32_e32 v69, 31, v68
	v_readlane_b32 s4, v253, 16
	v_lshlrev_b64 v[36:37], 12, v[68:69]
	v_readlane_b32 s5, v253, 17
	s_ashr_i32 s47, s46, 31
	v_lshl_add_u64 v[38:39], s[46:47], 0, v[144:145]
	v_lshl_add_u64 v[36:37], s[4:5], 0, v[36:37]
	v_lshl_add_u64 v[36:37], v[38:39], 1, v[36:37]
	s_mov_b64 s[0:1], 0
	v_cvt_pk_bf16_f32 v32, v28, v29
	v_cvt_pk_bf16_f32 v33, v30, v31
	v_cvt_pk_bf16_f32 v34, v24, v25
	v_cvt_pk_bf16_f32 v35, v26, v27
	s_nop 1
	global_store_dwordx4 v[36:37], v[32:35], off offset:256

.LBB0_446:
	s_andn2_saveexec_b64 s[28:29], s[28:29]
	s_cbranch_execz .LBB0_448
	s_ashr_i32 s26, s38, 3
	v_lshlrev_b32_e32 v184, 3, v62
	s_ashr_i32 s27, s26, 31
	v_lshl_add_u64 v[28:29], v[184:185], 0, s[26:27]
	s_nop 1
	s_ashr_i32 s1, s0, 31
	v_lshlrev_b64 v[28:29], 13, v[28:29]
	v_readlane_b32 s10, v253, 22
	v_readlane_b32 s11, v253, 23
	v_and_b32_e32 v30, 0x7f8, v100
	s_lshl_b64 s[0:1], s[0:1], 12
	v_lshl_add_u64 v[28:29], s[10:11], 0, v[28:29]
	v_lshl_add_u64 v[28:29], v[28:29], 0, s[0:1]
	v_lshlrev_b32_e32 v184, 1, v30
	v_lshl_add_u64 v[28:29], v[28:29], 0, v[184:185]
	s_nop 1
	global_store_dwordx4 v[28:29], v[24:27], off

.LBB0_449:
.LBB0_450:
	s_cmp_gt_i32 s38, 7
	s_mov_b64 s[0:1], -1
	s_cbranch_scc1 .LBB0_452
	v_ashrrev_i32_e32 v61, 31, v60
	v_readlane_b32 s4, v253, 16
	v_lshlrev_b64 v[28:29], 12, v[60:61]
	v_readlane_b32 s5, v253, 17
	s_ashr_i32 s47, s46, 31
	v_lshl_add_u64 v[30:31], s[46:47], 0, v[144:145]
	v_lshl_add_u64 v[28:29], s[4:5], 0, v[28:29]
	v_lshl_add_u64 v[28:29], v[30:31], 1, v[28:29]
	s_mov_b64 s[0:1], 0
	v_cvt_pk_bf16_f32 v24, v20, v21
	v_cvt_pk_bf16_f32 v25, v22, v23
	v_cvt_pk_bf16_f32 v26, v16, v17
	v_cvt_pk_bf16_f32 v27, v18, v19
	s_nop 1
	global_store_dwordx4 v[28:29], v[24:27], off offset:256

.LBB0_457:
	s_andn2_saveexec_b64 s[28:29], s[28:29]
	s_cbranch_execz .LBB0_459
	s_ashr_i32 s26, s38, 3
	v_lshlrev_b32_e32 v184, 3, v54
	s_ashr_i32 s27, s26, 31
	v_lshl_add_u64 v[20:21], v[184:185], 0, s[26:27]
	s_nop 1
	s_ashr_i32 s1, s0, 31
	v_lshlrev_b64 v[20:21], 13, v[20:21]
	v_readlane_b32 s10, v253, 22
	v_readlane_b32 s11, v253, 23
	v_and_b32_e32 v22, 0x7f8, v100
	s_lshl_b64 s[0:1], s[0:1], 12
	v_lshl_add_u64 v[20:21], s[10:11], 0, v[20:21]
	v_lshl_add_u64 v[20:21], v[20:21], 0, s[0:1]
	v_lshlrev_b32_e32 v184, 1, v22
	v_lshl_add_u64 v[20:21], v[20:21], 0, v[184:185]
	s_nop 1
	global_store_dwordx4 v[20:21], v[16:19], off

.LBB0_460:
.LBB0_461:
	s_cmp_gt_i32 s38, 7
	s_mov_b64 s[0:1], -1
	s_cbranch_scc1 .LBB0_463
	v_ashrrev_i32_e32 v53, 31, v52
	v_readlane_b32 s4, v253, 16
	v_lshlrev_b64 v[20:21], 12, v[52:53]
	v_readlane_b32 s5, v253, 17
	s_ashr_i32 s47, s46, 31
	v_lshl_add_u64 v[22:23], s[46:47], 0, v[144:145]
	v_lshl_add_u64 v[20:21], s[4:5], 0, v[20:21]
	v_lshl_add_u64 v[20:21], v[22:23], 1, v[20:21]
	s_mov_b64 s[0:1], 0
	v_cvt_pk_bf16_f32 v16, v12, v13
	v_cvt_pk_bf16_f32 v17, v14, v15
	v_cvt_pk_bf16_f32 v18, v8, v9
	v_cvt_pk_bf16_f32 v19, v10, v11
	s_nop 1
	global_store_dwordx4 v[20:21], v[16:19], off offset:256

.LBB0_468:
	s_or_saveexec_b64 s[28:29], s[28:29]
	s_mov_b32 s36, 0x800000
	s_xor_b64 exec, exec, s[28:29]
	s_cbranch_execz .LBB0_470
	s_ashr_i32 s26, s38, 3
	v_lshlrev_b32_e32 v184, 3, v46
	s_ashr_i32 s27, s26, 31
	v_lshl_add_u64 v[12:13], v[184:185], 0, s[26:27]
	s_nop 1
	s_ashr_i32 s1, s0, 31
	v_lshlrev_b64 v[12:13], 13, v[12:13]
	v_readlane_b32 s10, v253, 22
	v_readlane_b32 s11, v253, 23
	v_and_b32_e32 v14, 0x7f8, v100
	s_lshl_b64 s[0:1], s[0:1], 12
	v_lshl_add_u64 v[12:13], s[10:11], 0, v[12:13]
	v_lshl_add_u64 v[12:13], v[12:13], 0, s[0:1]
	v_lshlrev_b32_e32 v184, 1, v14
	v_lshl_add_u64 v[12:13], v[12:13], 0, v[184:185]
	s_nop 1
	global_store_dwordx4 v[12:13], v[8:11], off

.LBB0_472:
	s_cmp_gt_i32 s38, 7
	s_mov_b64 s[0:1], -1
	s_cbranch_scc1 .LBB0_474
	v_ashrrev_i32_e32 v45, 31, v44
	v_readlane_b32 s4, v253, 16
	v_lshlrev_b64 v[12:13], 12, v[44:45]
	v_readlane_b32 s5, v253, 17
	s_ashr_i32 s47, s46, 31
	v_lshl_add_u64 v[14:15], s[46:47], 0, v[144:145]
	v_lshl_add_u64 v[12:13], s[4:5], 0, v[12:13]
	v_lshl_add_u64 v[12:13], v[14:15], 1, v[12:13]
	s_mov_b64 s[0:1], 0
	v_cvt_pk_bf16_f32 v8, v4, v5
	v_cvt_pk_bf16_f32 v9, v6, v7
	v_cvt_pk_bf16_f32 v10, v0, v1
	v_cvt_pk_bf16_f32 v11, v2, v3
	s_nop 1
	global_store_dwordx4 v[12:13], v[8:11], off offset:256

.LBB0_476:
	s_waitcnt vmcnt(0)
	v_readlane_b32 s64, v255, 43
	v_readlane_b32 s65, v255, 44
	s_cmpk_gt_u32 s91, 0xff
	s_mov_b64 s[84:85], s[64:65]
	s_nop 1
	s_cbranch_scc1 .LBB0_478
	s_barrier
